# DSA job: the first 8 V-row gathers of the PV phase are requested before the softmax (cross-segment overlap; destinations are registers dead during the softmax)
# speedup vs baseline: 1.0012x; 1.0012x over previous
; DI void dsa_job(const Params& p, int b, int tq0, char* lds) {
;     ...
;   int bk[4];
; #pragma unroll
;   for (int j = 0; j < 4; ++j) { int dist = tq - ku[j]; bk[j] = (dist < 128) ? btab[dist & 127] : 31; }
; #pragma unroll
;   for (int hd = 0; hd < 8; ++hd) {
;     float mx = NEGL;
; #pragma unroll
;     for (int j = 0; j < 4; ++j) {
;       float v = lg[j][hd] * 0.125f + biasC[bk[j] * 8 + hd];
;       v = (kk[j] == 0xFFFF) ? NEGL : v;
;       lg[j][hd] = v;
;       mx = fmaxf(mx, v);
;     }
;     mx = wmax(mx);
;     float sm = 0.f;
; #pragma unroll
;     for (int j = 0; j < 4; ++j) { float e = __expf(lg[j][hd] - mx); lg[j][hd] = e; sm += e; }
;     sm = wsum(sm);
;     const float inv = 1.f / sm;
; #pragma unroll
;     for (int j = 0; j < 4; ++j) lg[j][hd] *= inv;
;   }
;     ...
;   auto pv_load = [&](int grp, u32x4* dst) {
; #pragma unroll
;     for (int s = 0; s < 16; ++s) dst[s] = *(const u32x4*)(vb + (size_t)kid[4 * (grp * 16 + s) + ksub] * LDH);
.LBB0_2356:
	s_or_b64 exec, exec, s[8:9]
	v_readlane_b32 s8, v239, 40
	s_mov_b32 s12, 0xf149f2ca
	v_bfe_u32 v208, v163, 3, 1
	v_add_u32_e32 v52, s8, v76
	ds_read_b128 v[52:55], v52
	s_waitcnt vmcnt(0)
	v_lshlrev_b32_e32 v220, 7, v208
	v_mov_b32_e32 v221, v3
	v_lshl_add_u64 v[220:221], s[10:11], 0, v[220:221]
	v_lshl_add_u64 v[220:221], v[220:221], 0, v[2:3]
	v_add_co_u32_e32 v220, vcc, 0x1800, v220
	s_nop 1
	v_addc_co_u32_e32 v221, vcc, 0, v221, vcc
	ds_read2_b32 v[222:223], v210 offset1:4
	ds_read2_b32 v[224:225], v210 offset0:8 offset1:12
	ds_read2_b32 v[226:227], v210 offset0:16 offset1:20
	ds_read2_b32 v[228:229], v210 offset0:24 offset1:28
	s_waitcnt lgkmcnt(0)
	v_mad_i64_i32 v[230:231], s[14:15], v222, s53, v[220:221]
	global_load_dwordx4 v[144:147], v[230:231], off
	v_mad_i64_i32 v[230:231], s[14:15], v223, s53, v[220:221]
	global_load_dwordx4 v[136:139], v[230:231], off
	v_mad_i64_i32 v[230:231], s[14:15], v224, s53, v[220:221]
	global_load_dwordx4 v[128:131], v[230:231], off
	v_mad_i64_i32 v[230:231], s[14:15], v225, s53, v[220:221]
	global_load_dwordx4 v[120:123], v[230:231], off
	v_mad_i64_i32 v[230:231], s[14:15], v226, s53, v[220:221]
	global_load_dwordx4 v[112:115], v[230:231], off
	v_mad_i64_i32 v[230:231], s[14:15], v227, s53, v[220:221]
	global_load_dwordx4 v[104:107], v[230:231], off
	v_mad_i64_i32 v[230:231], s[14:15], v228, s53, v[220:221]
	global_load_dwordx4 v[96:99], v[230:231], off
	v_mad_i64_i32 v[230:231], s[14:15], v229, s53, v[220:221]
	global_load_dwordx4 v[88:91], v[230:231], off
	v_lshlrev_b32_e32 v150, 5, v162
	v_lshlrev_b32_e32 v151, 4, v208
	v_add3_u32 v209, v159, v150, v151
	s_waitcnt lgkmcnt(0)
	v_fmamk_f32 v32, v32, 0x3e000000, v52
	v_add_u32_e32 v52, s8, v74
	ds_read_b128 v[56:59], v52
	v_cndmask_b32_e64 v32, v32, v203, s[4:5]
	v_fmac_f32_e32 v55, 0x3e000000, v35
	s_waitcnt lgkmcnt(0)
	v_fmamk_f32 v28, v28, 0x3e000000, v56
	v_add_u32_e32 v56, s8, v75
	ds_read_b128 v[60:63], v56
	v_add_u32_e32 v56, s8, v73
	ds_read_b128 v[64:67], v56
	v_cndmask_b32_e64 v28, v28, v203, s[6:7]
	v_max3_f32 v52, v32, s12, v28
	s_waitcnt lgkmcnt(1)
	v_fmamk_f32 v24, v24, 0x3e000000, v60
	v_cndmask_b32_e64 v24, v24, v203, s[0:1]
	s_waitcnt lgkmcnt(0)
	v_fmamk_f32 v20, v20, 0x3e000000, v64
	v_cndmask_b32_e64 v20, v20, v203, s[2:3]
	v_max3_f32 v52, v52, v24, v20
	v_fmamk_f32 v29, v29, 0x3e000000, v57
	v_cndmask_b32_e64 v29, v29, v203, s[6:7]
	v_mov_b32_dpp v56, v52 quad_perm:[1,0,3,2] row_mask:0xf bank_mask:0xf bound_ctrl:1
	v_max_f32_e32 v56, v56, v56
	v_max_f32_e32 v52, v52, v56
	v_fmamk_f32 v25, v25, 0x3e000000, v61
	v_fmamk_f32 v21, v21, 0x3e000000, v65
	v_mov_b32_dpp v56, v52 quad_perm:[2,3,0,1] row_mask:0xf bank_mask:0xf bound_ctrl:1
	v_max_f32_e32 v56, v56, v56
	v_max_f32_e32 v52, v52, v56
	v_cndmask_b32_e64 v25, v25, v203, s[0:1]
	v_cndmask_b32_e64 v21, v21, v203, s[2:3]
	v_mov_b32_dpp v56, v52 row_half_mirror row_mask:0xf bank_mask:0xf bound_ctrl:1
	v_max_f32_e32 v56, v56, v56
	v_max_f32_e32 v52, v52, v56
	v_fmamk_f32 v22, v22, 0x3e000000, v66
	v_cndmask_b32_e64 v22, v22, v203, s[2:3]
	v_mov_b32_dpp v56, v52 row_mirror row_mask:0xf bank_mask:0xf bound_ctrl:1
	v_max_f32_e32 v56, v56, v56
	v_max_f32_e32 v52, v52, v56
	v_mov_b32_e32 v56, v52
	s_nop 1
	v_permlane16_swap_b32_e32 v52, v56
	v_max_f32_e32 v56, v56, v56
	v_max_f32_e32 v52, v52, v52
	v_max_f32_e32 v52, v52, v56
	v_mov_b32_e32 v56, v52
	s_nop 1
	v_permlane32_swap_b32_e32 v52, v56
	v_max_f32_e32 v56, v56, v56
	v_max_f32_e32 v52, v52, v52
	v_max_f32_e32 v52, v52, v56
	v_sub_f32_e32 v32, v32, v52
	v_mul_f32_e32 v32, 0x3fb8aa3b, v32
	v_sub_f32_e32 v28, v28, v52
	v_exp_f32_e32 v64, v32
	v_mul_f32_e32 v28, 0x3fb8aa3b, v28
	v_sub_f32_e32 v24, v24, v52
	v_exp_f32_e32 v60, v28
	v_mul_f32_e32 v24, 0x3fb8aa3b, v24
	v_exp_f32_e32 v56, v24
	v_add_f32_e32 v32, 0, v64
	v_add_f32_e32 v28, v60, v32
	v_sub_f32_e32 v20, v20, v52
	v_add_f32_e32 v24, v56, v28
	v_fmamk_f32 v28, v33, 0x3e000000, v53
	v_cndmask_b32_e64 v28, v28, v203, s[4:5]
	v_max3_f32 v32, v28, s12, v29
	v_max3_f32 v32, v32, v25, v21
	v_mul_f32_e32 v20, 0x3fb8aa3b, v20
	v_exp_f32_e32 v52, v20
	v_mov_b32_dpp v33, v32 quad_perm:[1,0,3,2] row_mask:0xf bank_mask:0xf bound_ctrl:1
	v_max_f32_e32 v33, v33, v33
	v_max_f32_e32 v32, v32, v33
	v_add_f32_e32 v20, v52, v24
	v_fmac_f32_e32 v59, 0x3e000000, v31
	v_mov_b32_dpp v33, v32 quad_perm:[2,3,0,1] row_mask:0xf bank_mask:0xf bound_ctrl:1
	v_max_f32_e32 v33, v33, v33
	v_max_f32_e32 v32, v32, v33
	v_add_f32_dpp v20, v20, v20 quad_perm:[1,0,3,2] row_mask:0xf bank_mask:0xf bound_ctrl:1
	v_fmac_f32_e32 v63, 0x3e000000, v27
	v_mov_b32_dpp v33, v32 row_half_mirror row_mask:0xf bank_mask:0xf bound_ctrl:1
	v_max_f32_e32 v33, v33, v33
	v_max_f32_e32 v32, v32, v33
	v_add_f32_dpp v20, v20, v20 quad_perm:[2,3,0,1] row_mask:0xf bank_mask:0xf bound_ctrl:1
	v_fmac_f32_e32 v67, 0x3e000000, v23
	v_mov_b32_dpp v33, v32 row_mirror row_mask:0xf bank_mask:0xf bound_ctrl:1
	v_max_f32_e32 v33, v33, v33
	v_max_f32_e32 v32, v32, v33
	v_mov_b32_e32 v33, v32
	s_nop 1
	v_permlane16_swap_b32_e32 v32, v33
	v_max_f32_e32 v33, v33, v33
	v_max_f32_e32 v32, v32, v32
	v_max_f32_e32 v32, v32, v33
	v_mov_b32_e32 v33, v32
	s_nop 1
	v_permlane32_swap_b32_e32 v32, v33
	v_max_f32_e32 v33, v33, v33
	v_max_f32_e32 v32, v32, v32
	v_max_f32_e32 v32, v32, v33
	v_sub_f32_e32 v28, v28, v32
	v_mul_f32_e32 v28, 0x3fb8aa3b, v28
	v_sub_f32_e32 v29, v29, v32
	v_exp_f32_e32 v65, v28
	v_mul_f32_e32 v29, 0x3fb8aa3b, v29
	v_sub_f32_e32 v25, v25, v32
	v_exp_f32_e32 v61, v29
	v_mul_f32_e32 v25, 0x3fb8aa3b, v25
	v_sub_f32_e32 v21, v21, v32
	v_exp_f32_e32 v57, v25
	v_mul_f32_e32 v21, 0x3fb8aa3b, v21
	v_exp_f32_e32 v53, v21
; DI void dsa_job(const Params& p, int b, int tq0, char* lds) {
;     ...
; #pragma unroll
;   for (int hd = 0; hd < 8; ++hd) {
;     float mx = NEGL;
; #pragma unroll
;     for (int j = 0; j < 4; ++j) {
;       float v = lg[j][hd] * 0.125f + biasC[bk[j] * 8 + hd];
;       v = (kk[j] == 0xFFFF) ? NEGL : v;
;       lg[j][hd] = v;
;       mx = fmaxf(mx, v);
;     }
;     mx = wmax(mx);
;     float sm = 0.f;
; #pragma unroll
;     for (int j = 0; j < 4; ++j) { float e = __expf(lg[j][hd] - mx); lg[j][hd] = e; sm += e; }
;     sm = wsum(sm);
;     const float inv = 1.f / sm;
; #pragma unroll
;     for (int j = 0; j < 4; ++j) lg[j][hd] *= inv;
;   }
	v_add_f32_e32 v28, 0, v65
	v_add_f32_e32 v28, v61, v28
	v_add_f32_e32 v25, v57, v28
	v_add_f32_e32 v21, v53, v25
	v_add_f32_dpp v20, v20, v20 row_half_mirror row_mask:0xf bank_mask:0xf bound_ctrl:1
	v_cndmask_b32_e64 v23, v67, v203, s[2:3]
	v_add_f32_dpp v21, v21, v21 quad_perm:[1,0,3,2] row_mask:0xf bank_mask:0xf bound_ctrl:1
	v_add_f32_dpp v20, v20, v20 row_mirror row_mask:0xf bank_mask:0xf bound_ctrl:1
	v_mov_b32_e32 v24, v20
	v_add_f32_dpp v21, v21, v21 quad_perm:[2,3,0,1] row_mask:0xf bank_mask:0xf bound_ctrl:1
	s_nop 0
	v_permlane16_swap_b32_e32 v20, v24
	v_add_f32_dpp v21, v21, v21 row_half_mirror row_mask:0xf bank_mask:0xf bound_ctrl:1
	v_add_f32_e32 v20, v20, v24
	v_mov_b32_e32 v24, v20
	v_add_f32_dpp v21, v21, v21 row_mirror row_mask:0xf bank_mask:0xf bound_ctrl:1
	v_mov_b32_e32 v25, v21
	s_nop 1
	v_permlane16_swap_b32_e32 v21, v25
	v_add_f32_e32 v21, v21, v25
	v_mov_b32_e32 v25, v21
	v_permlane32_swap_b32_e32 v20, v24
	s_nop 0
	v_permlane32_swap_b32_e32 v21, v25
	v_pk_add_f32 v[20:21], v[20:21], v[24:25]
	s_nop 0
	v_div_scale_f32 v24, s[8:9], v21, v21, 1.0
	v_rcp_f32_e32 v25, v24
	s_nop 0
	v_fma_f32 v28, -v24, v25, 1.0
	v_fmac_f32_e32 v25, v28, v25
	v_div_scale_f32 v28, vcc, 1.0, v21, 1.0
	v_mul_f32_e32 v29, v28, v25
	v_fma_f32 v32, -v24, v29, v28
	v_fmac_f32_e32 v29, v32, v25
	v_fma_f32 v24, -v24, v29, v28
	v_div_fmas_f32 v24, v24, v25, v29
	v_div_fixup_f32 v69, v24, v21, 1.0
	v_div_scale_f32 v21, s[8:9], v20, v20, 1.0
	v_rcp_f32_e32 v24, v21
	s_nop 0
	v_fma_f32 v25, -v21, v24, 1.0
	v_fmac_f32_e32 v24, v25, v24
	v_div_scale_f32 v25, vcc, 1.0, v20, 1.0
	v_mul_f32_e32 v28, v25, v24
	v_fma_f32 v29, -v21, v28, v25
	v_fmac_f32_e32 v28, v29, v24
	v_fma_f32 v21, -v21, v28, v25
	v_div_fmas_f32 v21, v21, v24, v28
	v_div_fixup_f32 v68, v21, v20, 1.0
	v_fmamk_f32 v20, v34, 0x3e000000, v54
	v_fmamk_f32 v21, v30, 0x3e000000, v58
	v_cndmask_b32_e64 v20, v20, v203, s[4:5]
	v_cndmask_b32_e64 v21, v21, v203, s[6:7]
	v_fmamk_f32 v25, v26, 0x3e000000, v62
	v_max3_f32 v24, v20, s12, v21
	v_cndmask_b32_e64 v25, v25, v203, s[0:1]
	v_max3_f32 v24, v24, v25, v22
	s_nop 1
	v_mov_b32_dpp v26, v24 quad_perm:[1,0,3,2] row_mask:0xf bank_mask:0xf bound_ctrl:1
	v_max_f32_e32 v26, v26, v26
	v_max_f32_e32 v24, v24, v26
	s_nop 1
	v_mov_b32_dpp v26, v24 quad_perm:[2,3,0,1] row_mask:0xf bank_mask:0xf bound_ctrl:1
	v_max_f32_e32 v26, v26, v26
	v_max_f32_e32 v24, v24, v26
	s_nop 1
	v_mov_b32_dpp v26, v24 row_half_mirror row_mask:0xf bank_mask:0xf bound_ctrl:1
	v_max_f32_e32 v26, v26, v26
	v_max_f32_e32 v24, v24, v26
	s_nop 1
	v_mov_b32_dpp v26, v24 row_mirror row_mask:0xf bank_mask:0xf bound_ctrl:1
	v_max_f32_e32 v26, v26, v26
	v_max_f32_e32 v24, v24, v26
	v_mov_b32_e32 v26, v24
	s_nop 1
	v_permlane16_swap_b32_e32 v24, v26
	v_max_f32_e32 v26, v26, v26
	v_max_f32_e32 v24, v24, v24
	v_max_f32_e32 v24, v24, v26
	v_mov_b32_e32 v26, v24
	s_nop 1
	v_permlane32_swap_b32_e32 v24, v26
	v_max_f32_e32 v26, v26, v26
	v_max_f32_e32 v24, v24, v24
	v_max_f32_e32 v24, v24, v26
	v_sub_f32_e32 v21, v21, v24
	v_sub_f32_e32 v20, v20, v24
	v_mul_f32_e32 v21, 0x3fb8aa3b, v21
	v_mul_f32_e32 v20, 0x3fb8aa3b, v20
	v_exp_f32_e32 v62, v21
	v_sub_f32_e32 v21, v25, v24
	v_exp_f32_e32 v66, v20
	v_mul_f32_e32 v21, 0x3fb8aa3b, v21
	v_exp_f32_e32 v58, v21
	v_sub_f32_e32 v21, v22, v24
	v_mul_f32_e32 v21, 0x3fb8aa3b, v21
	v_exp_f32_e32 v54, v21
	v_add_f32_e32 v20, 0, v66
	v_add_f32_e32 v20, v62, v20
	v_add_f32_e32 v20, v58, v20
	v_add_f32_e32 v20, v54, v20
	v_cndmask_b32_e64 v24, v59, v203, s[6:7]
	v_cndmask_b32_e64 v26, v63, v203, s[0:1]
	v_add_f32_dpp v20, v20, v20 quad_perm:[1,0,3,2] row_mask:0xf bank_mask:0xf bound_ctrl:1
	s_nop 1
	v_add_f32_dpp v20, v20, v20 quad_perm:[2,3,0,1] row_mask:0xf bank_mask:0xf bound_ctrl:1
	s_nop 1
	v_add_f32_dpp v20, v20, v20 row_half_mirror row_mask:0xf bank_mask:0xf bound_ctrl:1
	s_nop 1
	v_add_f32_dpp v20, v20, v20 row_mirror row_mask:0xf bank_mask:0xf bound_ctrl:1
	v_mov_b32_e32 v21, v20
	s_nop 1
	v_permlane16_swap_b32_e32 v20, v21
	v_add_f32_e32 v20, v20, v21
	v_cndmask_b32_e64 v21, v55, v203, s[4:5]
	v_max3_f32 v25, v21, s12, v24
	v_max3_f32 v25, v25, v26, v23
	v_mov_b32_e32 v22, v20
	s_nop 1
	v_permlane32_swap_b32_e32 v20, v22
	v_mov_b32_dpp v27, v25 quad_perm:[1,0,3,2] row_mask:0xf bank_mask:0xf bound_ctrl:1
	v_max_f32_e32 v27, v27, v27
	v_max_f32_e32 v25, v25, v27
	s_nop 1
	v_mov_b32_dpp v27, v25 quad_perm:[2,3,0,1] row_mask:0xf bank_mask:0xf bound_ctrl:1
	v_max_f32_e32 v27, v27, v27
	v_max_f32_e32 v25, v25, v27
	s_nop 1
	v_mov_b32_dpp v27, v25 row_half_mirror row_mask:0xf bank_mask:0xf bound_ctrl:1
	v_max_f32_e32 v27, v27, v27
	v_max_f32_e32 v25, v25, v27
	s_nop 1
	v_mov_b32_dpp v27, v25 row_mirror row_mask:0xf bank_mask:0xf bound_ctrl:1
	v_max_f32_e32 v27, v27, v27
	v_max_f32_e32 v25, v25, v27
	v_mov_b32_e32 v27, v25
	s_nop 1
	v_permlane16_swap_b32_e32 v25, v27
	v_max_f32_e32 v27, v27, v27
	v_max_f32_e32 v25, v25, v25
	v_max_f32_e32 v25, v25, v27
	v_mov_b32_e32 v27, v25
	s_nop 1
	v_permlane32_swap_b32_e32 v25, v27
	v_max_f32_e32 v27, v27, v27
	v_max_f32_e32 v25, v25, v25
	v_max_f32_e32 v25, v25, v27
	v_sub_f32_e32 v21, v21, v25
	v_sub_f32_e32 v24, v24, v25
	v_mul_f32_e32 v21, 0x3fb8aa3b, v21
	v_mul_f32_e32 v24, 0x3fb8aa3b, v24
	v_exp_f32_e32 v67, v21
	v_exp_f32_e32 v63, v24
	v_sub_f32_e32 v24, v26, v25
	v_mul_f32_e32 v24, 0x3fb8aa3b, v24
	v_sub_f32_e32 v23, v23, v25
	v_exp_f32_e32 v59, v24
	v_mul_f32_e32 v23, 0x3fb8aa3b, v23
	v_exp_f32_e32 v55, v23
	v_add_f32_e32 v21, 0, v67
	v_add_f32_e32 v21, v63, v21
	v_add_f32_e32 v21, v59, v21
	v_add_f32_e32 v21, v55, v21
	s_nop 1
	v_add_f32_dpp v21, v21, v21 quad_perm:[1,0,3,2] row_mask:0xf bank_mask:0xf bound_ctrl:1
	s_nop 1
	v_add_f32_dpp v21, v21, v21 quad_perm:[2,3,0,1] row_mask:0xf bank_mask:0xf bound_ctrl:1
	s_nop 1
	v_add_f32_dpp v21, v21, v21 row_half_mirror row_mask:0xf bank_mask:0xf bound_ctrl:1
	s_nop 1
	v_add_f32_dpp v21, v21, v21 row_mirror row_mask:0xf bank_mask:0xf bound_ctrl:1
	v_mov_b32_e32 v23, v21
	s_nop 1
	v_permlane16_swap_b32_e32 v21, v23
	v_add_f32_e32 v21, v21, v23
	v_mov_b32_e32 v23, v21
	s_nop 1
	v_permlane32_swap_b32_e32 v21, v23
	v_pk_add_f32 v[20:21], v[20:21], v[22:23]
	s_nop 0
	v_div_scale_f32 v22, s[8:9], v21, v21, 1.0
	v_rcp_f32_e32 v23, v22
	s_nop 0
	v_fma_f32 v24, -v22, v23, 1.0
	v_fmac_f32_e32 v23, v24, v23
	v_div_scale_f32 v24, vcc, 1.0, v21, 1.0
	v_mul_f32_e32 v25, v24, v23
	v_fma_f32 v26, -v22, v25, v24
	v_fmac_f32_e32 v25, v26, v23
	v_fma_f32 v22, -v22, v25, v24
	v_div_fmas_f32 v22, v22, v23, v25
	v_div_fixup_f32 v71, v22, v21, 1.0
	v_div_scale_f32 v21, s[8:9], v20, v20, 1.0
	v_rcp_f32_e32 v22, v21
	v_readlane_b32 s8, v238, 28
	v_fma_f32 v23, -v21, v22, 1.0
	v_fmac_f32_e32 v22, v23, v22
	v_div_scale_f32 v23, vcc, 1.0, v20, 1.0
	v_mul_f32_e32 v24, v23, v22
	v_fma_f32 v25, -v21, v24, v23
	v_fmac_f32_e32 v24, v25, v22
	v_fma_f32 v21, -v21, v24, v23
	v_div_fmas_f32 v21, v21, v22, v24
	v_div_fixup_f32 v70, v21, v20, 1.0
	v_add_u32_e32 v20, s8, v76
	ds_read_b128 v[20:23], v20
	s_waitcnt lgkmcnt(0)
; DI void dsa_job(const Params& p, int b, int tq0, char* lds) {
;     ...
; #pragma unroll
;   for (int hd = 0; hd < 8; ++hd) {
;     float mx = NEGL;
; #pragma unroll
;     for (int j = 0; j < 4; ++j) {
;       float v = lg[j][hd] * 0.125f + biasC[bk[j] * 8 + hd];
;       v = (kk[j] == 0xFFFF) ? NEGL : v;
;       lg[j][hd] = v;
;       mx = fmaxf(mx, v);
;     }
;     mx = wmax(mx);
;     float sm = 0.f;
; #pragma unroll
;     for (int j = 0; j < 4; ++j) { float e = __expf(lg[j][hd] - mx); lg[j][hd] = e; sm += e; }
;     sm = wsum(sm);
;     const float inv = 1.f / sm;
; #pragma unroll
;     for (int j = 0; j < 4; ++j) lg[j][hd] *= inv;
;   }
	v_fmamk_f32 v16, v16, 0x3e000000, v20
	v_add_u32_e32 v20, s8, v74
	ds_read_b128 v[24:27], v20
	v_fmamk_f32 v17, v17, 0x3e000000, v21
	v_cndmask_b32_e64 v16, v16, v203, s[4:5]
	v_cndmask_b32_e64 v17, v17, v203, s[4:5]
	v_fmamk_f32 v18, v18, 0x3e000000, v22
	s_waitcnt lgkmcnt(0)
	v_fmamk_f32 v12, v12, 0x3e000000, v24
	v_add_u32_e32 v24, s8, v75
	ds_read_b128 v[28:31], v24
	v_add_u32_e32 v24, s8, v73
	ds_read_b128 v[32:35], v24
	v_fmamk_f32 v13, v13, 0x3e000000, v25
	v_cndmask_b32_e64 v12, v12, v203, s[6:7]
	s_waitcnt lgkmcnt(1)
	v_fmamk_f32 v8, v8, 0x3e000000, v28
	v_cndmask_b32_e64 v13, v13, v203, s[6:7]
	s_waitcnt lgkmcnt(0)
	v_fmamk_f32 v4, v4, 0x3e000000, v32
	v_fmamk_f32 v9, v9, 0x3e000000, v29
	v_fmamk_f32 v5, v5, 0x3e000000, v33
	v_max3_f32 v20, v16, s12, v12
	v_cndmask_b32_e64 v8, v8, v203, s[0:1]
	v_cndmask_b32_e64 v4, v4, v203, s[2:3]
	v_max3_f32 v21, v17, s12, v13
	v_cndmask_b32_e64 v9, v9, v203, s[0:1]
	v_cndmask_b32_e64 v5, v5, v203, s[2:3]
	v_max3_f32 v20, v20, v8, v4
	v_max3_f32 v21, v21, v9, v5
	v_fmamk_f32 v14, v14, 0x3e000000, v26
	v_mov_b32_dpp v24, v20 quad_perm:[1,0,3,2] row_mask:0xf bank_mask:0xf bound_ctrl:1
	v_mov_b32_dpp v25, v21 quad_perm:[1,0,3,2] row_mask:0xf bank_mask:0xf bound_ctrl:1
	v_max_f32_e32 v24, v24, v24
	v_max_f32_e32 v25, v25, v25
	v_max_f32_e32 v20, v20, v24
	v_max_f32_e32 v21, v21, v25
	v_cndmask_b32_e64 v18, v18, v203, s[4:5]
	v_mov_b32_dpp v24, v20 quad_perm:[2,3,0,1] row_mask:0xf bank_mask:0xf bound_ctrl:1
	v_mov_b32_dpp v25, v21 quad_perm:[2,3,0,1] row_mask:0xf bank_mask:0xf bound_ctrl:1
	v_max_f32_e32 v24, v24, v24
	v_max_f32_e32 v25, v25, v25
	v_max_f32_e32 v20, v20, v24
	v_max_f32_e32 v21, v21, v25
	v_cndmask_b32_e64 v14, v14, v203, s[6:7]
	v_mov_b32_dpp v24, v20 row_half_mirror row_mask:0xf bank_mask:0xf bound_ctrl:1
	v_mov_b32_dpp v25, v21 row_half_mirror row_mask:0xf bank_mask:0xf bound_ctrl:1
	v_max_f32_e32 v24, v24, v24
	v_max_f32_e32 v25, v25, v25
	v_max_f32_e32 v20, v20, v24
	v_max_f32_e32 v21, v21, v25
	v_fmamk_f32 v10, v10, 0x3e000000, v30
	v_mov_b32_dpp v24, v20 row_mirror row_mask:0xf bank_mask:0xf bound_ctrl:1
	v_mov_b32_dpp v25, v21 row_mirror row_mask:0xf bank_mask:0xf bound_ctrl:1
	v_max_f32_e32 v24, v24, v24
	v_max_f32_e32 v25, v25, v25
	v_max_f32_e32 v20, v20, v24
	v_max_f32_e32 v21, v21, v25
	v_mov_b32_e32 v24, v20
	v_mov_b32_e32 v25, v21
	s_nop 0
	v_permlane16_swap_b32_e32 v20, v24
	v_permlane16_swap_b32_e32 v21, v25
	v_max_f32_e32 v24, v24, v24
	v_max_f32_e32 v20, v20, v20
	v_max_f32_e32 v25, v25, v25
	v_max_f32_e32 v21, v21, v21
	v_max_f32_e32 v20, v20, v24
	v_max_f32_e32 v21, v21, v25
	v_mov_b32_e32 v24, v20
	v_mov_b32_e32 v25, v21
	s_nop 0
	v_permlane32_swap_b32_e32 v20, v24
	v_permlane32_swap_b32_e32 v21, v25
	v_max_f32_e32 v24, v24, v24
	v_max_f32_e32 v20, v20, v20
	v_max_f32_e32 v25, v25, v25
	v_max_f32_e32 v21, v21, v21
	v_max_f32_e32 v20, v20, v24
	v_max_f32_e32 v21, v21, v25
	v_sub_f32_e32 v16, v16, v20
	v_sub_f32_e32 v17, v17, v21
	v_mul_f32_e32 v16, 0x3fb8aa3b, v16
	v_sub_f32_e32 v12, v12, v20
	v_mul_f32_e32 v17, 0x3fb8aa3b, v17
	v_sub_f32_e32 v13, v13, v21
	v_exp_f32_e32 v16, v16
	v_mul_f32_e32 v12, 0x3fb8aa3b, v12
	v_sub_f32_e32 v8, v8, v20
	v_exp_f32_e32 v17, v17
	v_mul_f32_e32 v13, 0x3fb8aa3b, v13
	v_sub_f32_e32 v9, v9, v21
	v_exp_f32_e32 v12, v12
	v_mul_f32_e32 v8, 0x3fb8aa3b, v8
	v_sub_f32_e32 v4, v4, v20
	v_exp_f32_e32 v13, v13
	v_mul_f32_e32 v9, 0x3fb8aa3b, v9
	v_sub_f32_e32 v5, v5, v21
	v_exp_f32_e32 v8, v8
	v_mul_f32_e32 v4, 0x3fb8aa3b, v4
	v_exp_f32_e32 v9, v9
	v_mul_f32_e32 v5, 0x3fb8aa3b, v5
	v_exp_f32_e32 v4, v4
	v_exp_f32_e32 v5, v5
	v_add_f32_e32 v24, 0, v16
	v_add_f32_e32 v25, 0, v17
	v_add_f32_e32 v24, v12, v24
	v_add_f32_e32 v25, v13, v25
	v_add_f32_e32 v24, v8, v24
	v_add_f32_e32 v25, v9, v25
	v_add_f32_e32 v20, v4, v24
	v_add_f32_e32 v21, v5, v25
	v_fmamk_f32 v6, v6, 0x3e000000, v34
	v_add_f32_dpp v20, v20, v20 quad_perm:[1,0,3,2] row_mask:0xf bank_mask:0xf bound_ctrl:1
	v_add_f32_dpp v21, v21, v21 quad_perm:[1,0,3,2] row_mask:0xf bank_mask:0xf bound_ctrl:1
	v_max3_f32 v22, v18, s12, v14
	v_add_f32_dpp v20, v20, v20 quad_perm:[2,3,0,1] row_mask:0xf bank_mask:0xf bound_ctrl:1
	v_add_f32_dpp v21, v21, v21 quad_perm:[2,3,0,1] row_mask:0xf bank_mask:0xf bound_ctrl:1
	v_cndmask_b32_e64 v10, v10, v203, s[0:1]
	v_add_f32_dpp v20, v20, v20 row_half_mirror row_mask:0xf bank_mask:0xf bound_ctrl:1
	v_add_f32_dpp v21, v21, v21 row_half_mirror row_mask:0xf bank_mask:0xf bound_ctrl:1
	v_fmac_f32_e32 v23, 0x3e000000, v19
	v_add_f32_dpp v20, v20, v20 row_mirror row_mask:0xf bank_mask:0xf bound_ctrl:1
	v_add_f32_dpp v21, v21, v21 row_mirror row_mask:0xf bank_mask:0xf bound_ctrl:1
	v_mov_b32_e32 v24, v20
	v_mov_b32_e32 v25, v21
	s_nop 0
	v_permlane16_swap_b32_e32 v20, v24
	v_permlane16_swap_b32_e32 v21, v25
	v_add_f32_e32 v20, v20, v24
	v_add_f32_e32 v21, v21, v25
	v_mov_b32_e32 v24, v20
	v_mov_b32_e32 v25, v21
	s_nop 0
	v_permlane32_swap_b32_e32 v20, v24
	v_permlane32_swap_b32_e32 v21, v25
	v_pk_add_f32 v[20:21], v[20:21], v[24:25]
	v_fmac_f32_e32 v27, 0x3e000000, v15
	v_div_scale_f32 v24, s[8:9], v21, v21, 1.0
	v_rcp_f32_e32 v25, v24
	v_cndmask_b32_e64 v19, v23, v203, s[4:5]
	v_cndmask_b32_e64 v15, v27, v203, s[6:7]
	v_fmac_f32_e32 v31, 0x3e000000, v11
	v_fma_f32 v28, -v24, v25, 1.0
	v_fmac_f32_e32 v25, v28, v25
	v_div_scale_f32 v28, vcc, 1.0, v21, 1.0
	v_mul_f32_e32 v29, v28, v25
	v_fma_f32 v32, -v24, v29, v28
	v_fmac_f32_e32 v29, v32, v25
	v_fma_f32 v24, -v24, v29, v28
	v_div_fmas_f32 v24, v24, v25, v29
	v_div_fixup_f32 v21, v24, v21, 1.0
	v_div_scale_f32 v24, s[8:9], v20, v20, 1.0
	v_rcp_f32_e32 v25, v24
	v_fmac_f32_e32 v35, 0x3e000000, v7
; DI void dsa_job(const Params& p, int b, int tq0, char* lds) {
;     ...
; #pragma unroll
;   for (int hd = 0; hd < 8; ++hd) {
;     float mx = NEGL;
; #pragma unroll
;     for (int j = 0; j < 4; ++j) {
;       float v = lg[j][hd] * 0.125f + biasC[bk[j] * 8 + hd];
;       v = (kk[j] == 0xFFFF) ? NEGL : v;
;       lg[j][hd] = v;
;       mx = fmaxf(mx, v);
;     }
;     mx = wmax(mx);
;     float sm = 0.f;
; #pragma unroll
;     for (int j = 0; j < 4; ++j) { float e = __expf(lg[j][hd] - mx); lg[j][hd] = e; sm += e; }
;     sm = wsum(sm);
;     const float inv = 1.f / sm;
; #pragma unroll
;     for (int j = 0; j < 4; ++j) lg[j][hd] *= inv;
;   }
; #pragma unroll
;   for (int j = 0; j < 4; ++j) {
;     f32x4 v0 = {lg[j][0], lg[j][1], lg[j][2], lg[j][3]}, v1 = {lg[j][4], lg[j][5], lg[j][6], lg[j][7]};
;     *(f32x4*)(Pl + (4 * lane + j) * 8) = v0;
;     *(f32x4*)(Pl + (4 * lane + j) * 8 + 4) = v1;
;   }
;   __builtin_amdgcn_wave_barrier();
;   const u16* vb = Hb + HV_C + g * 64 + dc * 8;
	v_cndmask_b32_e64 v11, v31, v203, s[0:1]
	v_cndmask_b32_e64 v23, v35, v203, s[2:3]
	v_fma_f32 v28, -v24, v25, 1.0
	v_fmac_f32_e32 v25, v28, v25
	v_div_scale_f32 v28, vcc, 1.0, v20, 1.0
	v_mul_f32_e32 v29, v28, v25
	v_fma_f32 v32, -v24, v29, v28
	v_fmac_f32_e32 v29, v32, v25
	v_fma_f32 v24, -v24, v29, v28
	v_div_fmas_f32 v24, v24, v25, v29
	v_div_fixup_f32 v20, v24, v20, 1.0
	v_cndmask_b32_e64 v24, v6, v203, s[2:3]
	v_max3_f32 v6, v22, v10, v24
	s_nop 1
	v_mov_b32_dpp v22, v6 quad_perm:[1,0,3,2] row_mask:0xf bank_mask:0xf bound_ctrl:1
	v_max_f32_e32 v22, v22, v22
	v_max_f32_e32 v6, v6, v22
	s_nop 1
	v_mov_b32_dpp v22, v6 quad_perm:[2,3,0,1] row_mask:0xf bank_mask:0xf bound_ctrl:1
	v_max_f32_e32 v22, v22, v22
	v_max_f32_e32 v6, v6, v22
	s_nop 1
	v_mov_b32_dpp v22, v6 row_half_mirror row_mask:0xf bank_mask:0xf bound_ctrl:1
	v_max_f32_e32 v22, v22, v22
	v_max_f32_e32 v6, v6, v22
	s_nop 1
	v_mov_b32_dpp v22, v6 row_mirror row_mask:0xf bank_mask:0xf bound_ctrl:1
	v_max_f32_e32 v22, v22, v22
	v_max_f32_e32 v6, v6, v22
	v_mov_b32_e32 v22, v6
	s_nop 1
	v_permlane16_swap_b32_e32 v6, v22
	v_max_f32_e32 v22, v22, v22
	v_max_f32_e32 v6, v6, v6
	v_max_f32_e32 v6, v6, v22
	v_mov_b32_e32 v22, v6
	s_nop 1
	v_permlane32_swap_b32_e32 v6, v22
	v_max_f32_e32 v22, v22, v22
	v_max_f32_e32 v6, v6, v6
	v_max_f32_e32 v22, v6, v22
	v_sub_f32_e32 v6, v18, v22
	v_mul_f32_e32 v6, 0x3fb8aa3b, v6
	v_sub_f32_e32 v14, v14, v22
	v_exp_f32_e32 v6, v6
	v_mul_f32_e32 v14, 0x3fb8aa3b, v14
	v_sub_f32_e32 v10, v10, v22
	v_exp_f32_e32 v18, v14
	v_mul_f32_e32 v10, 0x3fb8aa3b, v10
	v_exp_f32_e32 v26, v10
	v_add_f32_e32 v25, 0, v6
	v_add_f32_e32 v14, v18, v25
	v_add_f32_e32 v10, v26, v14
	v_sub_f32_e32 v14, v24, v22
	v_max3_f32 v22, v19, s12, v15
	v_max3_f32 v7, v22, v11, v23
	v_mul_f32_e32 v14, 0x3fb8aa3b, v14
	v_exp_f32_e32 v28, v14
	v_mov_b32_dpp v22, v7 quad_perm:[1,0,3,2] row_mask:0xf bank_mask:0xf bound_ctrl:1
	v_max_f32_e32 v22, v22, v22
	v_max_f32_e32 v7, v7, v22
	v_add_f32_e32 v10, v28, v10
	s_nop 0
	v_mov_b32_dpp v22, v7 quad_perm:[2,3,0,1] row_mask:0xf bank_mask:0xf bound_ctrl:1
	v_max_f32_e32 v22, v22, v22
	v_max_f32_e32 v7, v7, v22
	v_add_f32_dpp v10, v10, v10 quad_perm:[1,0,3,2] row_mask:0xf bank_mask:0xf bound_ctrl:1
	s_nop 0
	v_mov_b32_dpp v22, v7 row_half_mirror row_mask:0xf bank_mask:0xf bound_ctrl:1
	v_max_f32_e32 v22, v22, v22
	v_max_f32_e32 v7, v7, v22
	v_add_f32_dpp v10, v10, v10 quad_perm:[2,3,0,1] row_mask:0xf bank_mask:0xf bound_ctrl:1
	s_nop 0
	v_mov_b32_dpp v22, v7 row_mirror row_mask:0xf bank_mask:0xf bound_ctrl:1
	v_max_f32_e32 v22, v22, v22
	v_max_f32_e32 v7, v7, v22
	v_mov_b32_e32 v22, v7
	s_nop 1
	v_permlane16_swap_b32_e32 v7, v22
	v_max_f32_e32 v22, v22, v22
	v_max_f32_e32 v7, v7, v7
	v_max_f32_e32 v7, v7, v22
	v_mov_b32_e32 v22, v7
	s_nop 1
	v_permlane32_swap_b32_e32 v7, v22
	v_max_f32_e32 v22, v22, v22
	v_max_f32_e32 v7, v7, v7
	v_max_f32_e32 v22, v7, v22
	v_sub_f32_e32 v7, v19, v22
	v_mul_f32_e32 v7, 0x3fb8aa3b, v7
	v_sub_f32_e32 v15, v15, v22
	v_exp_f32_e32 v7, v7
	v_mul_f32_e32 v15, 0x3fb8aa3b, v15
	v_sub_f32_e32 v11, v11, v22
	v_exp_f32_e32 v19, v15
	v_mul_f32_e32 v11, 0x3fb8aa3b, v11
	v_exp_f32_e32 v27, v11
	v_add_f32_e32 v24, 0, v7
	v_add_f32_e32 v15, v19, v24
	v_add_f32_dpp v10, v10, v10 row_half_mirror row_mask:0xf bank_mask:0xf bound_ctrl:1
	v_add_f32_e32 v11, v27, v15
	v_sub_f32_e32 v15, v23, v22
	v_mul_f32_e32 v15, 0x3fb8aa3b, v15
	v_exp_f32_e32 v29, v15
	v_add_f32_dpp v10, v10, v10 row_mirror row_mask:0xf bank_mask:0xf bound_ctrl:1
	v_mov_b32_e32 v14, v10
	s_nop 1
	v_permlane16_swap_b32_e32 v10, v14
	v_add_f32_e32 v11, v29, v11
	v_add_f32_e32 v10, v10, v14
	v_mov_b32_e32 v14, v10
	v_add_f32_dpp v11, v11, v11 quad_perm:[1,0,3,2] row_mask:0xf bank_mask:0xf bound_ctrl:1
	s_nop 0
	v_permlane32_swap_b32_e32 v10, v14
	v_add_f32_dpp v11, v11, v11 quad_perm:[2,3,0,1] row_mask:0xf bank_mask:0xf bound_ctrl:1
	s_nop 1
	v_add_f32_dpp v11, v11, v11 row_half_mirror row_mask:0xf bank_mask:0xf bound_ctrl:1
	s_nop 1
	v_add_f32_dpp v11, v11, v11 row_mirror row_mask:0xf bank_mask:0xf bound_ctrl:1
	v_mov_b32_e32 v15, v11
	s_nop 1
	v_permlane16_swap_b32_e32 v11, v15
	v_add_f32_e32 v11, v11, v15
	v_mov_b32_e32 v15, v11
	s_nop 1
	v_permlane32_swap_b32_e32 v11, v15
	v_pk_add_f32 v[10:11], v[10:11], v[14:15]
	s_nop 0
	v_div_scale_f32 v14, s[0:1], v11, v11, 1.0
	v_rcp_f32_e32 v15, v14
	s_nop 0
	v_fma_f32 v22, -v14, v15, 1.0
	v_fmac_f32_e32 v15, v22, v15
	v_div_scale_f32 v22, vcc, 1.0, v11, 1.0
	v_mul_f32_e32 v23, v22, v15
	v_fma_f32 v24, -v14, v23, v22
	v_fmac_f32_e32 v23, v24, v15
	v_fma_f32 v14, -v14, v23, v22
	v_div_fmas_f32 v14, v14, v15, v23
	v_div_fixup_f32 v31, v14, v11, 1.0
	v_div_scale_f32 v11, s[0:1], v10, v10, 1.0
	v_rcp_f32_e32 v14, v11
	v_pk_mul_f32 v[24:25], v[66:67], v[70:71]
	s_mov_b64 s[0:1], 0x1800
	v_fma_f32 v15, -v11, v14, 1.0
	v_fmac_f32_e32 v14, v15, v14
	v_div_scale_f32 v15, vcc, 1.0, v10, 1.0
	v_mul_f32_e32 v22, v15, v14
	v_fma_f32 v23, -v11, v22, v15
	v_fmac_f32_e32 v22, v23, v14
	v_fma_f32 v11, -v11, v22, v15
	v_div_fmas_f32 v11, v11, v14, v22
	v_div_fixup_f32 v30, v11, v10, 1.0
	v_pk_mul_f32 v[22:23], v[64:65], v[68:69]
	v_pk_mul_f32 v[14:15], v[16:17], v[20:21]
	v_pk_mul_f32 v[16:17], v[6:7], v[30:31]
	ds_write_b128 v72, v[22:25]
	ds_write_b128 v72, v[14:17] offset:16
	v_pk_mul_f32 v[14:15], v[60:61], v[68:69]
	v_pk_mul_f32 v[16:17], v[62:63], v[70:71]
	v_pk_mul_f32 v[10:11], v[12:13], v[20:21]
	v_pk_mul_f32 v[12:13], v[18:19], v[30:31]
	ds_write_b128 v72, v[14:17] offset:32
	ds_write_b128 v72, v[10:13] offset:48
	v_pk_mul_f32 v[10:11], v[56:57], v[68:69]
	v_pk_mul_f32 v[12:13], v[58:59], v[70:71]
	v_pk_mul_f32 v[6:7], v[8:9], v[20:21]
	v_pk_mul_f32 v[8:9], v[26:27], v[30:31]
	ds_write_b128 v72, v[10:13] offset:64
	ds_write_b128 v72, v[6:9] offset:80
	v_pk_mul_f32 v[10:11], v[4:5], v[20:21]
	v_lshlrev_b32_e32 v4, 7, v208
	v_mov_b32_e32 v5, v3
	v_lshl_add_u64 v[4:5], s[10:11], 0, v[4:5]
	v_pk_mul_f32 v[6:7], v[52:53], v[68:69]
	v_pk_mul_f32 v[8:9], v[54:55], v[70:71]
	v_lshl_add_u64 v[4:5], v[4:5], 0, v[2:3]
	v_pk_mul_f32 v[12:13], v[28:29], v[30:31]
	ds_write_b128 v72, v[6:9] offset:96
	ds_write_b128 v72, v[10:13] offset:112
	v_lshl_add_u64 v[148:149], v[4:5], 0, s[0:1]
	ds_read_b128 v[158:161], v209
	ds_read2_b32 v[4:5], v210 offset0:32 offset1:36
	s_waitcnt lgkmcnt(0)
; DI float bf_lo(unsigned u) { return __uint_as_float(u << 16); }
; DI float bf_hi(unsigned u) { return __uint_as_float(u & 0xffff0000u); }
; DI void dsa_job(const Params& p, int b, int tq0, char* lds) {
;     ...
;   auto pv_load = [&](int grp, u32x4* dst) {
; #pragma unroll
;     for (int s = 0; s < 16; ++s) dst[s] = *(const u32x4*)(vb + (size_t)kid[4 * (grp * 16 + s) + ksub] * LDH);
;   };
;   auto pv_fma = [&](int grp, const u32x4* src) {
; #pragma unroll
;     for (int s = 0; s < 16; ++s) {
;       const int slot = 4 * (grp * 16 + s) + ksub;
;       const f32x4 pp = *(const f32x4*)(Pl + slot * 8 + g * 4);
;       const u32x4 vv = src[s];
; #pragma unroll
;       for (int hh = 0; hh < 4; ++hh) {
;         const f32x2 ph = {pp[hh], pp[hh]};
; #pragma unroll
;         for (int e = 0; e < 4; ++e) {
;           const f32x2 vf2 = {bf_lo(vv[e]), bf_hi(vv[e])};
;           acc2[hh][e] += ph * vf2;
;         }
	v_mad_i64_i32 v[6:7], s[0:1], v4, s53, v[148:149]
	global_load_dwordx4 v[80:83], v[6:7], off
	v_mad_i64_i32 v[4:5], s[0:1], v5, s53, v[148:149]
	global_load_dwordx4 v[72:75], v[4:5], off
	ds_read2_b32 v[4:5], v210 offset0:40 offset1:44
	s_waitcnt lgkmcnt(0)
	v_mad_i64_i32 v[6:7], s[0:1], v4, s53, v[148:149]
	global_load_dwordx4 v[64:67], v[6:7], off
	v_mad_i64_i32 v[4:5], s[0:1], v5, s53, v[148:149]
	global_load_dwordx4 v[56:59], v[4:5], off
	ds_read2_b32 v[4:5], v210 offset0:48 offset1:52
	s_waitcnt lgkmcnt(0)
	v_mad_i64_i32 v[6:7], s[0:1], v4, s53, v[148:149]
	global_load_dwordx4 v[32:35], v[6:7], off
	v_mad_i64_i32 v[4:5], s[0:1], v5, s53, v[148:149]
	global_load_dwordx4 v[24:27], v[4:5], off
	ds_read2_b32 v[4:5], v210 offset0:56 offset1:60
	s_waitcnt lgkmcnt(0)
	v_mad_i64_i32 v[6:7], s[0:1], v4, s53, v[148:149]
	global_load_dwordx4 v[16:19], v[6:7], off
	v_mad_i64_i32 v[4:5], s[0:1], v5, s53, v[148:149]
	global_load_dwordx4 v[8:11], v[4:5], off
	ds_read2_b32 v[4:5], v210 offset0:64 offset1:68
	s_waitcnt vmcnt(15)
	v_lshlrev_b32_e32 v150, 16, v144
	v_and_b32_e32 v151, 0xffff0000, v144
	v_lshlrev_b32_e32 v144, 16, v145
	v_and_b32_e32 v145, 0xffff0000, v145
	v_lshlrev_b32_e32 v166, 16, v146
	v_and_b32_e32 v167, 0xffff0000, v146
	v_lshlrev_b32_e32 v146, 16, v147
	v_and_b32_e32 v147, 0xffff0000, v147
	v_pk_fma_f32 v[178:179], v[160:161], v[150:151], 0 op_sel_hi:[0,1,0]
	v_pk_fma_f32 v[180:181], v[160:161], v[144:145], 0 op_sel_hi:[0,1,0]
	v_pk_fma_f32 v[182:183], v[160:161], v[166:167], 0 op_sel_hi:[0,1,0]
	v_pk_fma_f32 v[184:185], v[160:161], v[146:147], 0 op_sel_hi:[0,1,0]
	v_mov_b32_e32 v160, v161
	v_pk_fma_f32 v[162:163], v[158:159], v[150:151], 0 op_sel_hi:[0,1,0]
	v_pk_fma_f32 v[164:165], v[158:159], v[144:145], 0 op_sel_hi:[0,1,0]
	v_pk_fma_f32 v[168:169], v[158:159], v[166:167], 0 op_sel_hi:[0,1,0]
	v_pk_fma_f32 v[170:171], v[158:159], v[146:147], 0 op_sel_hi:[0,1,0]
	v_pk_fma_f32 v[172:173], v[158:159], v[150:151], 0 op_sel:[1,0,0] op_sel_hi:[1,1,0]
	v_pk_fma_f32 v[174:175], v[158:159], v[144:145], 0 op_sel:[1,0,0] op_sel_hi:[1,1,0]
	v_pk_fma_f32 v[176:177], v[158:159], v[166:167], 0 op_sel:[1,0,0] op_sel_hi:[1,1,0]
	v_pk_fma_f32 v[158:159], v[158:159], v[146:147], 0 op_sel:[1,0,0] op_sel_hi:[1,1,0]
	v_pk_fma_f32 v[150:151], v[160:161], v[150:151], 0 op_sel_hi:[0,1,0]
	v_pk_fma_f32 v[186:187], v[160:161], v[144:145], 0 op_sel_hi:[0,1,0]
	v_pk_fma_f32 v[166:167], v[160:161], v[166:167], 0 op_sel_hi:[0,1,0]
	v_pk_fma_f32 v[160:161], v[160:161], v[146:147], 0 op_sel_hi:[0,1,0]
	ds_read_b128 v[144:147], v209 offset:128
	s_waitcnt vmcnt(14)
	v_lshlrev_b32_e32 v212, 16, v136
	v_and_b32_e32 v213, 0xffff0000, v136
	v_lshlrev_b32_e32 v136, 16, v137
	v_and_b32_e32 v137, 0xffff0000, v137
	v_lshlrev_b32_e32 v214, 16, v138
	v_and_b32_e32 v215, 0xffff0000, v138
	v_lshlrev_b32_e32 v138, 16, v139
	v_and_b32_e32 v139, 0xffff0000, v139
	s_waitcnt lgkmcnt(0)
	v_pk_fma_f32 v[162:163], v[144:145], v[212:213], v[162:163] op_sel_hi:[0,1,1]
	v_pk_fma_f32 v[164:165], v[144:145], v[136:137], v[164:165] op_sel_hi:[0,1,1]
	v_pk_fma_f32 v[168:169], v[144:145], v[214:215], v[168:169] op_sel_hi:[0,1,1]
	v_pk_fma_f32 v[170:171], v[144:145], v[138:139], v[170:171] op_sel_hi:[0,1,1]
	v_pk_fma_f32 v[172:173], v[144:145], v[212:213], v[172:173] op_sel:[1,0,0]
	v_pk_fma_f32 v[174:175], v[144:145], v[136:137], v[174:175] op_sel:[1,0,0]
	v_pk_fma_f32 v[176:177], v[144:145], v[214:215], v[176:177] op_sel:[1,0,0]
	v_pk_fma_f32 v[144:145], v[144:145], v[138:139], v[158:159] op_sel:[1,0,0]
	v_pk_fma_f32 v[158:159], v[146:147], v[212:213], v[178:179] op_sel_hi:[0,1,1]
	v_pk_fma_f32 v[178:179], v[146:147], v[136:137], v[180:181] op_sel_hi:[0,1,1]
	v_pk_fma_f32 v[180:181], v[146:147], v[214:215], v[182:183] op_sel_hi:[0,1,1]
	v_pk_fma_f32 v[182:183], v[146:147], v[138:139], v[184:185] op_sel_hi:[0,1,1]
	v_mov_b32_e32 v146, v147
	v_pk_fma_f32 v[150:151], v[146:147], v[212:213], v[150:151] op_sel_hi:[0,1,1]
	v_pk_fma_f32 v[184:185], v[146:147], v[136:137], v[186:187] op_sel_hi:[0,1,1]
	v_pk_fma_f32 v[166:167], v[146:147], v[214:215], v[166:167] op_sel_hi:[0,1,1]
	v_pk_fma_f32 v[146:147], v[146:147], v[138:139], v[160:161] op_sel_hi:[0,1,1]
	ds_read_b128 v[136:139], v209 offset:256
	ds_read_b128 v[212:215], v209 offset:2048
	s_waitcnt vmcnt(13)
	v_lshlrev_b32_e32 v160, 16, v128
	v_and_b32_e32 v161, 0xffff0000, v128
	v_lshlrev_b32_e32 v128, 16, v129
	v_and_b32_e32 v129, 0xffff0000, v129
	v_lshlrev_b32_e32 v186, 16, v130
	v_and_b32_e32 v187, 0xffff0000, v130
	v_lshlrev_b32_e32 v130, 16, v131
	v_and_b32_e32 v131, 0xffff0000, v131
	s_waitcnt lgkmcnt(1)
	v_pk_fma_f32 v[162:163], v[136:137], v[160:161], v[162:163] op_sel_hi:[0,1,1]
	v_pk_fma_f32 v[164:165], v[136:137], v[128:129], v[164:165] op_sel_hi:[0,1,1]
	v_pk_fma_f32 v[168:169], v[136:137], v[186:187], v[168:169] op_sel_hi:[0,1,1]
	v_pk_fma_f32 v[170:171], v[136:137], v[130:131], v[170:171] op_sel_hi:[0,1,1]
	v_pk_fma_f32 v[172:173], v[136:137], v[160:161], v[172:173] op_sel:[1,0,0]
	v_pk_fma_f32 v[174:175], v[136:137], v[128:129], v[174:175] op_sel:[1,0,0]
	v_pk_fma_f32 v[176:177], v[136:137], v[186:187], v[176:177] op_sel:[1,0,0]
	v_pk_fma_f32 v[136:137], v[136:137], v[130:131], v[144:145] op_sel:[1,0,0]
	v_pk_fma_f32 v[144:145], v[138:139], v[160:161], v[158:159] op_sel_hi:[0,1,1]
	v_pk_fma_f32 v[158:159], v[138:139], v[128:129], v[178:179] op_sel_hi:[0,1,1]
	v_pk_fma_f32 v[178:179], v[138:139], v[186:187], v[180:181] op_sel_hi:[0,1,1]
	v_pk_fma_f32 v[180:181], v[138:139], v[130:131], v[182:183] op_sel_hi:[0,1,1]
	v_mov_b32_e32 v138, v139
	v_pk_fma_f32 v[150:151], v[138:139], v[160:161], v[150:151] op_sel_hi:[0,1,1]
	v_pk_fma_f32 v[160:161], v[138:139], v[128:129], v[184:185] op_sel_hi:[0,1,1]
	v_pk_fma_f32 v[166:167], v[138:139], v[186:187], v[166:167] op_sel_hi:[0,1,1]
	v_pk_fma_f32 v[138:139], v[138:139], v[130:131], v[146:147] op_sel_hi:[0,1,1]
	ds_read_b128 v[128:131], v209 offset:384
	s_waitcnt vmcnt(12)
; DI float bf_lo(unsigned u) { return __uint_as_float(u << 16); }
; DI float bf_hi(unsigned u) { return __uint_as_float(u & 0xffff0000u); }
; DI void dsa_job(const Params& p, int b, int tq0, char* lds) {
;     ...
;   auto pv_load = [&](int grp, u32x4* dst) {
; #pragma unroll
;     for (int s = 0; s < 16; ++s) dst[s] = *(const u32x4*)(vb + (size_t)kid[4 * (grp * 16 + s) + ksub] * LDH);
;   };
;   auto pv_fma = [&](int grp, const u32x4* src) {
; #pragma unroll
;     for (int s = 0; s < 16; ++s) {
;       const int slot = 4 * (grp * 16 + s) + ksub;
;       const f32x4 pp = *(const f32x4*)(Pl + slot * 8 + g * 4);
;       const u32x4 vv = src[s];
; #pragma unroll
;       for (int hh = 0; hh < 4; ++hh) {
;         const f32x2 ph = {pp[hh], pp[hh]};
; #pragma unroll
;         for (int e = 0; e < 4; ++e) {
;           const f32x2 vf2 = {bf_lo(vv[e]), bf_hi(vv[e])};
;           acc2[hh][e] += ph * vf2;
;         }
;       }
;     }
;   };
;   pv_load(0, vA);
;   pv_load(1, vB);
;   pv_fma(0, vA);
;   pv_load(2, vA);
;   pv_fma(1, vB);
;   pv_load(3, vB);
;   pv_fma(2, vA);
	v_lshlrev_b32_e32 v146, 16, v120
	v_and_b32_e32 v147, 0xffff0000, v120
	v_lshlrev_b32_e32 v120, 16, v121
	v_and_b32_e32 v121, 0xffff0000, v121
	v_lshlrev_b32_e32 v182, 16, v122
	v_and_b32_e32 v183, 0xffff0000, v122
	v_lshlrev_b32_e32 v122, 16, v123
	v_and_b32_e32 v123, 0xffff0000, v123
	s_waitcnt lgkmcnt(0)
	v_pk_fma_f32 v[162:163], v[128:129], v[146:147], v[162:163] op_sel_hi:[0,1,1]
	v_pk_fma_f32 v[164:165], v[128:129], v[120:121], v[164:165] op_sel_hi:[0,1,1]
	v_pk_fma_f32 v[168:169], v[128:129], v[182:183], v[168:169] op_sel_hi:[0,1,1]
	v_pk_fma_f32 v[170:171], v[128:129], v[122:123], v[170:171] op_sel_hi:[0,1,1]
	v_pk_fma_f32 v[172:173], v[128:129], v[146:147], v[172:173] op_sel:[1,0,0]
	v_pk_fma_f32 v[174:175], v[128:129], v[120:121], v[174:175] op_sel:[1,0,0]
	v_pk_fma_f32 v[176:177], v[128:129], v[182:183], v[176:177] op_sel:[1,0,0]
	v_pk_fma_f32 v[128:129], v[128:129], v[122:123], v[136:137] op_sel:[1,0,0]
	v_pk_fma_f32 v[136:137], v[130:131], v[146:147], v[144:145] op_sel_hi:[0,1,1]
	v_pk_fma_f32 v[144:145], v[130:131], v[120:121], v[158:159] op_sel_hi:[0,1,1]
	v_pk_fma_f32 v[158:159], v[130:131], v[182:183], v[178:179] op_sel_hi:[0,1,1]
	v_pk_fma_f32 v[178:179], v[130:131], v[122:123], v[180:181] op_sel_hi:[0,1,1]
	v_mov_b32_e32 v130, v131
	v_mad_i64_i32 v[6:7], s[0:1], v4, s53, v[148:149]
	v_pk_fma_f32 v[146:147], v[130:131], v[146:147], v[150:151] op_sel_hi:[0,1,1]
	v_pk_fma_f32 v[150:151], v[130:131], v[120:121], v[160:161] op_sel_hi:[0,1,1]
	v_pk_fma_f32 v[160:161], v[130:131], v[182:183], v[166:167] op_sel_hi:[0,1,1]
	v_pk_fma_f32 v[130:131], v[130:131], v[122:123], v[138:139] op_sel_hi:[0,1,1]
	ds_read_b128 v[120:123], v209 offset:512
	global_load_dwordx4 v[140:143], v[6:7], off
	s_waitcnt vmcnt(12)
	v_lshlrev_b32_e32 v138, 16, v112
	v_and_b32_e32 v139, 0xffff0000, v112
	v_lshlrev_b32_e32 v112, 16, v113
	v_and_b32_e32 v113, 0xffff0000, v113
	v_lshlrev_b32_e32 v166, 16, v114
	v_and_b32_e32 v167, 0xffff0000, v114
	v_lshlrev_b32_e32 v114, 16, v115
	v_and_b32_e32 v115, 0xffff0000, v115
	s_waitcnt lgkmcnt(0)
	v_pk_fma_f32 v[162:163], v[120:121], v[138:139], v[162:163] op_sel_hi:[0,1,1]
	v_pk_fma_f32 v[164:165], v[120:121], v[112:113], v[164:165] op_sel_hi:[0,1,1]
	v_pk_fma_f32 v[168:169], v[120:121], v[166:167], v[168:169] op_sel_hi:[0,1,1]
	v_pk_fma_f32 v[170:171], v[120:121], v[114:115], v[170:171] op_sel_hi:[0,1,1]
	v_pk_fma_f32 v[172:173], v[120:121], v[138:139], v[172:173] op_sel:[1,0,0]
	v_pk_fma_f32 v[174:175], v[120:121], v[112:113], v[174:175] op_sel:[1,0,0]
	v_pk_fma_f32 v[176:177], v[120:121], v[166:167], v[176:177] op_sel:[1,0,0]
	v_pk_fma_f32 v[120:121], v[120:121], v[114:115], v[128:129] op_sel:[1,0,0]
	v_pk_fma_f32 v[128:129], v[122:123], v[138:139], v[136:137] op_sel_hi:[0,1,1]
	v_pk_fma_f32 v[136:137], v[122:123], v[112:113], v[144:145] op_sel_hi:[0,1,1]
	v_pk_fma_f32 v[144:145], v[122:123], v[166:167], v[158:159] op_sel_hi:[0,1,1]
	v_pk_fma_f32 v[158:159], v[122:123], v[114:115], v[178:179] op_sel_hi:[0,1,1]
	v_mov_b32_e32 v122, v123
	v_mad_i64_i32 v[4:5], s[0:1], v5, s53, v[148:149]
	v_pk_fma_f32 v[138:139], v[122:123], v[138:139], v[146:147] op_sel_hi:[0,1,1]
	v_pk_fma_f32 v[146:147], v[122:123], v[112:113], v[150:151] op_sel_hi:[0,1,1]
	v_pk_fma_f32 v[150:151], v[122:123], v[166:167], v[160:161] op_sel_hi:[0,1,1]
	v_pk_fma_f32 v[122:123], v[122:123], v[114:115], v[130:131] op_sel_hi:[0,1,1]
	ds_read_b128 v[112:115], v209 offset:640
	global_load_dwordx4 v[132:135], v[4:5], off
	ds_read2_b32 v[4:5], v210 offset0:72 offset1:76
	s_waitcnt vmcnt(12)
	v_lshlrev_b32_e32 v130, 16, v104
	v_and_b32_e32 v131, 0xffff0000, v104
	v_lshlrev_b32_e32 v104, 16, v105
	v_and_b32_e32 v105, 0xffff0000, v105
	s_waitcnt lgkmcnt(1)
	v_pk_fma_f32 v[160:161], v[112:113], v[130:131], v[162:163] op_sel_hi:[0,1,1]
	v_pk_fma_f32 v[162:163], v[112:113], v[104:105], v[164:165] op_sel_hi:[0,1,1]
	v_lshlrev_b32_e32 v164, 16, v106
	v_and_b32_e32 v165, 0xffff0000, v106
	v_lshlrev_b32_e32 v106, 16, v107
	v_and_b32_e32 v107, 0xffff0000, v107
	s_waitcnt lgkmcnt(0)
	v_mad_i64_i32 v[6:7], s[0:1], v4, s53, v[148:149]
	v_pk_fma_f32 v[166:167], v[112:113], v[164:165], v[168:169] op_sel_hi:[0,1,1]
	v_pk_fma_f32 v[168:169], v[112:113], v[106:107], v[170:171] op_sel_hi:[0,1,1]
	v_pk_fma_f32 v[170:171], v[112:113], v[130:131], v[172:173] op_sel:[1,0,0]
	v_pk_fma_f32 v[172:173], v[112:113], v[104:105], v[174:175] op_sel:[1,0,0]
	v_pk_fma_f32 v[174:175], v[112:113], v[164:165], v[176:177] op_sel:[1,0,0]
	v_pk_fma_f32 v[112:113], v[112:113], v[106:107], v[120:121] op_sel:[1,0,0]
	v_pk_fma_f32 v[120:121], v[114:115], v[130:131], v[128:129] op_sel_hi:[0,1,1]
	v_pk_fma_f32 v[128:129], v[114:115], v[104:105], v[136:137] op_sel_hi:[0,1,1]
	v_pk_fma_f32 v[136:137], v[114:115], v[164:165], v[144:145] op_sel_hi:[0,1,1]
	v_pk_fma_f32 v[144:145], v[114:115], v[106:107], v[158:159] op_sel_hi:[0,1,1]
	v_mov_b32_e32 v114, v115
	global_load_dwordx4 v[124:127], v[6:7], off
	v_pk_fma_f32 v[130:131], v[114:115], v[130:131], v[138:139] op_sel_hi:[0,1,1]
	v_pk_fma_f32 v[138:139], v[114:115], v[104:105], v[146:147] op_sel_hi:[0,1,1]
	v_pk_fma_f32 v[146:147], v[114:115], v[164:165], v[150:151] op_sel_hi:[0,1,1]
	v_pk_fma_f32 v[114:115], v[114:115], v[106:107], v[122:123] op_sel_hi:[0,1,1]
	ds_read_b128 v[104:107], v209 offset:768
	s_waitcnt vmcnt(12)
	v_lshlrev_b32_e32 v122, 16, v96
	v_and_b32_e32 v123, 0xffff0000, v96
	v_mad_i64_i32 v[4:5], s[0:1], v5, s53, v[148:149]
	s_waitcnt lgkmcnt(0)
; DI float bf_lo(unsigned u) { return __uint_as_float(u << 16); }
; DI float bf_hi(unsigned u) { return __uint_as_float(u & 0xffff0000u); }
; DI void dsa_job(const Params& p, int b, int tq0, char* lds) {
;     ...
;   auto pv_load = [&](int grp, u32x4* dst) {
; #pragma unroll
;     for (int s = 0; s < 16; ++s) dst[s] = *(const u32x4*)(vb + (size_t)kid[4 * (grp * 16 + s) + ksub] * LDH);
;   };
;   auto pv_fma = [&](int grp, const u32x4* src) {
; #pragma unroll
;     for (int s = 0; s < 16; ++s) {
;       const int slot = 4 * (grp * 16 + s) + ksub;
;       const f32x4 pp = *(const f32x4*)(Pl + slot * 8 + g * 4);
;       const u32x4 vv = src[s];
; #pragma unroll
;       for (int hh = 0; hh < 4; ++hh) {
;         const f32x2 ph = {pp[hh], pp[hh]};
; #pragma unroll
;         for (int e = 0; e < 4; ++e) {
;           const f32x2 vf2 = {bf_lo(vv[e]), bf_hi(vv[e])};
;           acc2[hh][e] += ph * vf2;
;         }
;       }
;     }
;   };
;   pv_load(0, vA);
;   pv_load(1, vB);
;   pv_fma(0, vA);
;   pv_load(2, vA);
;   pv_fma(1, vB);
;   pv_load(3, vB);
;   pv_fma(2, vA);
	v_pk_fma_f32 v[150:151], v[104:105], v[122:123], v[160:161] op_sel_hi:[0,1,1]
	v_lshlrev_b32_e32 v96, 16, v97
	v_and_b32_e32 v97, 0xffff0000, v97
	v_lshlrev_b32_e32 v160, 16, v98
	v_and_b32_e32 v161, 0xffff0000, v98
	v_lshlrev_b32_e32 v98, 16, v99
	v_and_b32_e32 v99, 0xffff0000, v99
	global_load_dwordx4 v[116:119], v[4:5], off
	ds_read2_b32 v[4:5], v210 offset0:80 offset1:84
	v_pk_fma_f32 v[158:159], v[104:105], v[96:97], v[162:163] op_sel_hi:[0,1,1]
	v_pk_fma_f32 v[162:163], v[104:105], v[160:161], v[166:167] op_sel_hi:[0,1,1]
	v_pk_fma_f32 v[164:165], v[104:105], v[98:99], v[168:169] op_sel_hi:[0,1,1]
	v_pk_fma_f32 v[166:167], v[104:105], v[122:123], v[170:171] op_sel:[1,0,0]
	v_pk_fma_f32 v[168:169], v[104:105], v[96:97], v[172:173] op_sel:[1,0,0]
	v_pk_fma_f32 v[170:171], v[104:105], v[160:161], v[174:175] op_sel:[1,0,0]
	v_pk_fma_f32 v[104:105], v[104:105], v[98:99], v[112:113] op_sel:[1,0,0]
	v_pk_fma_f32 v[112:113], v[106:107], v[122:123], v[120:121] op_sel_hi:[0,1,1]
	v_pk_fma_f32 v[120:121], v[106:107], v[96:97], v[128:129] op_sel_hi:[0,1,1]
	v_pk_fma_f32 v[128:129], v[106:107], v[160:161], v[136:137] op_sel_hi:[0,1,1]
	v_pk_fma_f32 v[136:137], v[106:107], v[98:99], v[144:145] op_sel_hi:[0,1,1]
	v_mov_b32_e32 v106, v107
	v_pk_fma_f32 v[122:123], v[106:107], v[122:123], v[130:131] op_sel_hi:[0,1,1]
	v_pk_fma_f32 v[130:131], v[106:107], v[96:97], v[138:139] op_sel_hi:[0,1,1]
	v_pk_fma_f32 v[138:139], v[106:107], v[160:161], v[146:147] op_sel_hi:[0,1,1]
	v_pk_fma_f32 v[106:107], v[106:107], v[98:99], v[114:115] op_sel_hi:[0,1,1]
	ds_read_b128 v[96:99], v209 offset:896
	s_waitcnt lgkmcnt(1)
	v_mad_i64_i32 v[6:7], s[0:1], v4, s53, v[148:149]
	s_waitcnt vmcnt(12)
	v_lshlrev_b32_e32 v114, 16, v88
	v_and_b32_e32 v115, 0xffff0000, v88
	global_load_dwordx4 v[108:111], v[6:7], off
	s_waitcnt lgkmcnt(0)
	v_pk_fma_f32 v[144:145], v[96:97], v[114:115], v[150:151] op_sel_hi:[0,1,1]
	v_lshlrev_b32_e32 v88, 16, v89
	v_and_b32_e32 v89, 0xffff0000, v89
	v_lshlrev_b32_e32 v150, 16, v90
	v_and_b32_e32 v151, 0xffff0000, v90
	v_lshlrev_b32_e32 v90, 16, v91
	v_and_b32_e32 v91, 0xffff0000, v91
	v_pk_fma_f32 v[146:147], v[96:97], v[88:89], v[158:159] op_sel_hi:[0,1,1]
	v_pk_fma_f32 v[158:159], v[96:97], v[150:151], v[162:163] op_sel_hi:[0,1,1]
	v_pk_fma_f32 v[160:161], v[96:97], v[90:91], v[164:165] op_sel_hi:[0,1,1]
	v_pk_fma_f32 v[162:163], v[96:97], v[114:115], v[166:167] op_sel:[1,0,0]
	v_pk_fma_f32 v[164:165], v[96:97], v[88:89], v[168:169] op_sel:[1,0,0]
	v_pk_fma_f32 v[166:167], v[96:97], v[150:151], v[170:171] op_sel:[1,0,0]
	v_pk_fma_f32 v[96:97], v[96:97], v[90:91], v[104:105] op_sel:[1,0,0]
	v_pk_fma_f32 v[104:105], v[98:99], v[114:115], v[112:113] op_sel_hi:[0,1,1]
	v_pk_fma_f32 v[112:113], v[98:99], v[88:89], v[120:121] op_sel_hi:[0,1,1]
	v_pk_fma_f32 v[120:121], v[98:99], v[150:151], v[128:129] op_sel_hi:[0,1,1]
	v_pk_fma_f32 v[128:129], v[98:99], v[90:91], v[136:137] op_sel_hi:[0,1,1]
	v_mov_b32_e32 v98, v99
	v_pk_fma_f32 v[114:115], v[98:99], v[114:115], v[122:123] op_sel_hi:[0,1,1]
	v_pk_fma_f32 v[122:123], v[98:99], v[88:89], v[130:131] op_sel_hi:[0,1,1]
	v_pk_fma_f32 v[130:131], v[98:99], v[150:151], v[138:139] op_sel_hi:[0,1,1]
	v_pk_fma_f32 v[98:99], v[98:99], v[90:91], v[106:107] op_sel_hi:[0,1,1]
	ds_read_b128 v[88:91], v209 offset:1024
	v_mad_i64_i32 v[4:5], s[0:1], v5, s53, v[148:149]
	global_load_dwordx4 v[100:103], v[4:5], off
	ds_read2_b32 v[4:5], v210 offset0:88 offset1:92
	s_waitcnt vmcnt(13)
	v_lshlrev_b32_e32 v106, 16, v80
	v_and_b32_e32 v107, 0xffff0000, v80
	s_waitcnt lgkmcnt(1)
	v_pk_fma_f32 v[136:137], v[88:89], v[106:107], v[144:145] op_sel_hi:[0,1,1]
	v_lshlrev_b32_e32 v80, 16, v81
	v_and_b32_e32 v81, 0xffff0000, v81
	v_lshlrev_b32_e32 v144, 16, v82
	v_and_b32_e32 v145, 0xffff0000, v82
	v_lshlrev_b32_e32 v82, 16, v83
	v_and_b32_e32 v83, 0xffff0000, v83
	v_pk_fma_f32 v[138:139], v[88:89], v[80:81], v[146:147] op_sel_hi:[0,1,1]
	v_pk_fma_f32 v[146:147], v[88:89], v[144:145], v[158:159] op_sel_hi:[0,1,1]
	v_pk_fma_f32 v[150:151], v[88:89], v[82:83], v[160:161] op_sel_hi:[0,1,1]
	v_pk_fma_f32 v[158:159], v[88:89], v[106:107], v[162:163] op_sel:[1,0,0]
	v_pk_fma_f32 v[160:161], v[88:89], v[80:81], v[164:165] op_sel:[1,0,0]
	v_pk_fma_f32 v[162:163], v[88:89], v[144:145], v[166:167] op_sel:[1,0,0]
	v_pk_fma_f32 v[88:89], v[88:89], v[82:83], v[96:97] op_sel:[1,0,0]
	v_pk_fma_f32 v[96:97], v[90:91], v[106:107], v[104:105] op_sel_hi:[0,1,1]
	v_pk_fma_f32 v[104:105], v[90:91], v[80:81], v[112:113] op_sel_hi:[0,1,1]
	v_pk_fma_f32 v[112:113], v[90:91], v[144:145], v[120:121] op_sel_hi:[0,1,1]
	v_pk_fma_f32 v[120:121], v[90:91], v[82:83], v[128:129] op_sel_hi:[0,1,1]
	v_mov_b32_e32 v90, v91
	v_pk_fma_f32 v[106:107], v[90:91], v[106:107], v[114:115] op_sel_hi:[0,1,1]
	v_pk_fma_f32 v[114:115], v[90:91], v[80:81], v[122:123] op_sel_hi:[0,1,1]
	v_pk_fma_f32 v[122:123], v[90:91], v[144:145], v[130:131] op_sel_hi:[0,1,1]
	v_pk_fma_f32 v[90:91], v[90:91], v[82:83], v[98:99] op_sel_hi:[0,1,1]
	ds_read_b128 v[80:83], v209 offset:1152
	s_waitcnt lgkmcnt(1)
	v_mad_i64_i32 v[6:7], s[0:1], v4, s53, v[148:149]
	global_load_dwordx4 v[92:95], v[6:7], off
	s_waitcnt vmcnt(13)
	v_lshlrev_b32_e32 v98, 16, v72
	v_and_b32_e32 v99, 0xffff0000, v72
	s_waitcnt lgkmcnt(0)
; DI float bf_lo(unsigned u) { return __uint_as_float(u << 16); }
; DI float bf_hi(unsigned u) { return __uint_as_float(u & 0xffff0000u); }
; DI void dsa_job(const Params& p, int b, int tq0, char* lds) {
;     ...
;   auto pv_load = [&](int grp, u32x4* dst) {
; #pragma unroll
;     for (int s = 0; s < 16; ++s) dst[s] = *(const u32x4*)(vb + (size_t)kid[4 * (grp * 16 + s) + ksub] * LDH);
;   };
;   auto pv_fma = [&](int grp, const u32x4* src) {
; #pragma unroll
;     for (int s = 0; s < 16; ++s) {
;       const int slot = 4 * (grp * 16 + s) + ksub;
;       const f32x4 pp = *(const f32x4*)(Pl + slot * 8 + g * 4);
;       const u32x4 vv = src[s];
; #pragma unroll
;       for (int hh = 0; hh < 4; ++hh) {
;         const f32x2 ph = {pp[hh], pp[hh]};
; #pragma unroll
;         for (int e = 0; e < 4; ++e) {
;           const f32x2 vf2 = {bf_lo(vv[e]), bf_hi(vv[e])};
;           acc2[hh][e] += ph * vf2;
;         }
;       }
;     }
;   };
;   pv_load(0, vA);
;   pv_load(1, vB);
;   pv_fma(0, vA);
;   pv_load(2, vA);
;   pv_fma(1, vB);
;   pv_load(3, vB);
;   pv_fma(2, vA);
	v_pk_fma_f32 v[128:129], v[80:81], v[98:99], v[136:137] op_sel_hi:[0,1,1]
	v_lshlrev_b32_e32 v72, 16, v73
	v_and_b32_e32 v73, 0xffff0000, v73
	v_lshlrev_b32_e32 v136, 16, v74
	v_and_b32_e32 v137, 0xffff0000, v74
	v_lshlrev_b32_e32 v74, 16, v75
	v_and_b32_e32 v75, 0xffff0000, v75
	v_pk_fma_f32 v[130:131], v[80:81], v[72:73], v[138:139] op_sel_hi:[0,1,1]
	v_pk_fma_f32 v[138:139], v[80:81], v[136:137], v[146:147] op_sel_hi:[0,1,1]
	v_pk_fma_f32 v[144:145], v[80:81], v[74:75], v[150:151] op_sel_hi:[0,1,1]
	v_pk_fma_f32 v[146:147], v[80:81], v[98:99], v[158:159] op_sel:[1,0,0]
	v_pk_fma_f32 v[150:151], v[80:81], v[72:73], v[160:161] op_sel:[1,0,0]
	v_pk_fma_f32 v[158:159], v[80:81], v[136:137], v[162:163] op_sel:[1,0,0]
	v_pk_fma_f32 v[80:81], v[80:81], v[74:75], v[88:89] op_sel:[1,0,0]
	v_pk_fma_f32 v[88:89], v[82:83], v[98:99], v[96:97] op_sel_hi:[0,1,1]
	v_pk_fma_f32 v[96:97], v[82:83], v[72:73], v[104:105] op_sel_hi:[0,1,1]
	v_pk_fma_f32 v[104:105], v[82:83], v[136:137], v[112:113] op_sel_hi:[0,1,1]
	v_pk_fma_f32 v[112:113], v[82:83], v[74:75], v[120:121] op_sel_hi:[0,1,1]
	v_mov_b32_e32 v82, v83
	v_pk_fma_f32 v[98:99], v[82:83], v[98:99], v[106:107] op_sel_hi:[0,1,1]
	v_pk_fma_f32 v[106:107], v[82:83], v[72:73], v[114:115] op_sel_hi:[0,1,1]
	v_pk_fma_f32 v[114:115], v[82:83], v[136:137], v[122:123] op_sel_hi:[0,1,1]
	v_pk_fma_f32 v[82:83], v[82:83], v[74:75], v[90:91] op_sel_hi:[0,1,1]
	ds_read_b128 v[72:75], v209 offset:1280
	v_mad_i64_i32 v[4:5], s[0:1], v5, s53, v[148:149]
	global_load_dwordx4 v[84:87], v[4:5], off
	ds_read2_b32 v[4:5], v210 offset0:96 offset1:100
	s_waitcnt vmcnt(13)
	v_lshlrev_b32_e32 v90, 16, v64
	v_and_b32_e32 v91, 0xffff0000, v64
	s_waitcnt lgkmcnt(1)
	v_pk_fma_f32 v[120:121], v[72:73], v[90:91], v[128:129] op_sel_hi:[0,1,1]
	v_lshlrev_b32_e32 v64, 16, v65
	v_and_b32_e32 v65, 0xffff0000, v65
	v_lshlrev_b32_e32 v128, 16, v66
	v_and_b32_e32 v129, 0xffff0000, v66
	v_lshlrev_b32_e32 v66, 16, v67
	v_and_b32_e32 v67, 0xffff0000, v67
	v_pk_fma_f32 v[122:123], v[72:73], v[64:65], v[130:131] op_sel_hi:[0,1,1]
	v_pk_fma_f32 v[130:131], v[72:73], v[128:129], v[138:139] op_sel_hi:[0,1,1]
	v_pk_fma_f32 v[136:137], v[72:73], v[66:67], v[144:145] op_sel_hi:[0,1,1]
	v_pk_fma_f32 v[138:139], v[72:73], v[90:91], v[146:147] op_sel:[1,0,0]
	v_pk_fma_f32 v[144:145], v[72:73], v[64:65], v[150:151] op_sel:[1,0,0]
	v_pk_fma_f32 v[146:147], v[72:73], v[128:129], v[158:159] op_sel:[1,0,0]
	v_pk_fma_f32 v[72:73], v[72:73], v[66:67], v[80:81] op_sel:[1,0,0]
	v_pk_fma_f32 v[80:81], v[74:75], v[90:91], v[88:89] op_sel_hi:[0,1,1]
	v_pk_fma_f32 v[88:89], v[74:75], v[64:65], v[96:97] op_sel_hi:[0,1,1]
	v_pk_fma_f32 v[96:97], v[74:75], v[128:129], v[104:105] op_sel_hi:[0,1,1]
	v_pk_fma_f32 v[104:105], v[74:75], v[66:67], v[112:113] op_sel_hi:[0,1,1]
	v_mov_b32_e32 v74, v75
	v_pk_fma_f32 v[90:91], v[74:75], v[90:91], v[98:99] op_sel_hi:[0,1,1]
	v_pk_fma_f32 v[98:99], v[74:75], v[64:65], v[106:107] op_sel_hi:[0,1,1]
	v_pk_fma_f32 v[106:107], v[74:75], v[128:129], v[114:115] op_sel_hi:[0,1,1]
	v_pk_fma_f32 v[74:75], v[74:75], v[66:67], v[82:83] op_sel_hi:[0,1,1]
	ds_read_b128 v[64:67], v209 offset:1408
	s_waitcnt lgkmcnt(1)
	v_mad_i64_i32 v[6:7], s[0:1], v4, s53, v[148:149]
	global_load_dwordx4 v[76:79], v[6:7], off
	s_waitcnt vmcnt(13)
	v_lshlrev_b32_e32 v82, 16, v56
	v_and_b32_e32 v83, 0xffff0000, v56
	s_waitcnt lgkmcnt(0)
	v_pk_fma_f32 v[112:113], v[64:65], v[82:83], v[120:121] op_sel_hi:[0,1,1]
	v_lshlrev_b32_e32 v56, 16, v57
	v_and_b32_e32 v57, 0xffff0000, v57
	v_lshlrev_b32_e32 v120, 16, v58
	v_and_b32_e32 v121, 0xffff0000, v58
	v_lshlrev_b32_e32 v58, 16, v59
	v_and_b32_e32 v59, 0xffff0000, v59
	v_pk_fma_f32 v[114:115], v[64:65], v[56:57], v[122:123] op_sel_hi:[0,1,1]
	v_pk_fma_f32 v[122:123], v[64:65], v[120:121], v[130:131] op_sel_hi:[0,1,1]
	v_pk_fma_f32 v[128:129], v[64:65], v[58:59], v[136:137] op_sel_hi:[0,1,1]
	v_pk_fma_f32 v[130:131], v[64:65], v[82:83], v[138:139] op_sel:[1,0,0]
	v_pk_fma_f32 v[136:137], v[64:65], v[56:57], v[144:145] op_sel:[1,0,0]
	v_pk_fma_f32 v[138:139], v[64:65], v[120:121], v[146:147] op_sel:[1,0,0]
	v_pk_fma_f32 v[64:65], v[64:65], v[58:59], v[72:73] op_sel:[1,0,0]
	v_pk_fma_f32 v[72:73], v[66:67], v[82:83], v[80:81] op_sel_hi:[0,1,1]
	v_pk_fma_f32 v[80:81], v[66:67], v[56:57], v[88:89] op_sel_hi:[0,1,1]
	v_pk_fma_f32 v[88:89], v[66:67], v[120:121], v[96:97] op_sel_hi:[0,1,1]
	v_pk_fma_f32 v[96:97], v[66:67], v[58:59], v[104:105] op_sel_hi:[0,1,1]
	v_mov_b32_e32 v66, v67
	v_pk_fma_f32 v[82:83], v[66:67], v[82:83], v[90:91] op_sel_hi:[0,1,1]
	v_pk_fma_f32 v[90:91], v[66:67], v[56:57], v[98:99] op_sel_hi:[0,1,1]
	v_pk_fma_f32 v[98:99], v[66:67], v[120:121], v[106:107] op_sel_hi:[0,1,1]
	v_pk_fma_f32 v[66:67], v[66:67], v[58:59], v[74:75] op_sel_hi:[0,1,1]
	ds_read_b128 v[56:59], v209 offset:1536
	v_mad_i64_i32 v[4:5], s[0:1], v5, s53, v[148:149]
	global_load_dwordx4 v[68:71], v[4:5], off
	ds_read2_b32 v[4:5], v210 offset0:104 offset1:108
	s_waitcnt vmcnt(13)
	v_lshlrev_b32_e32 v74, 16, v32
	v_and_b32_e32 v75, 0xffff0000, v32
	s_waitcnt lgkmcnt(1)
; DI float bf_lo(unsigned u) { return __uint_as_float(u << 16); }
; DI float bf_hi(unsigned u) { return __uint_as_float(u & 0xffff0000u); }
; DI void dsa_job(const Params& p, int b, int tq0, char* lds) {
;     ...
;   auto pv_load = [&](int grp, u32x4* dst) {
; #pragma unroll
;     for (int s = 0; s < 16; ++s) dst[s] = *(const u32x4*)(vb + (size_t)kid[4 * (grp * 16 + s) + ksub] * LDH);
;   };
;   auto pv_fma = [&](int grp, const u32x4* src) {
; #pragma unroll
;     for (int s = 0; s < 16; ++s) {
;       const int slot = 4 * (grp * 16 + s) + ksub;
;       const f32x4 pp = *(const f32x4*)(Pl + slot * 8 + g * 4);
;       const u32x4 vv = src[s];
; #pragma unroll
;       for (int hh = 0; hh < 4; ++hh) {
;         const f32x2 ph = {pp[hh], pp[hh]};
; #pragma unroll
;         for (int e = 0; e < 4; ++e) {
;           const f32x2 vf2 = {bf_lo(vv[e]), bf_hi(vv[e])};
;           acc2[hh][e] += ph * vf2;
;         }
;       }
;     }
;   };
;   pv_load(0, vA);
;   pv_load(1, vB);
;   pv_fma(0, vA);
;   pv_load(2, vA);
;   pv_fma(1, vB);
;   pv_load(3, vB);
;   pv_fma(2, vA);
	v_pk_fma_f32 v[104:105], v[56:57], v[74:75], v[112:113] op_sel_hi:[0,1,1]
	v_lshlrev_b32_e32 v32, 16, v33
	v_and_b32_e32 v33, 0xffff0000, v33
	v_lshlrev_b32_e32 v112, 16, v34
	v_and_b32_e32 v113, 0xffff0000, v34
	v_lshlrev_b32_e32 v34, 16, v35
	v_and_b32_e32 v35, 0xffff0000, v35
	v_pk_fma_f32 v[106:107], v[56:57], v[32:33], v[114:115] op_sel_hi:[0,1,1]
	v_pk_fma_f32 v[114:115], v[56:57], v[112:113], v[122:123] op_sel_hi:[0,1,1]
	v_pk_fma_f32 v[120:121], v[56:57], v[34:35], v[128:129] op_sel_hi:[0,1,1]
	v_pk_fma_f32 v[122:123], v[56:57], v[74:75], v[130:131] op_sel:[1,0,0]
	v_pk_fma_f32 v[128:129], v[56:57], v[32:33], v[136:137] op_sel:[1,0,0]
	v_pk_fma_f32 v[130:131], v[56:57], v[112:113], v[138:139] op_sel:[1,0,0]
	v_pk_fma_f32 v[56:57], v[56:57], v[34:35], v[64:65] op_sel:[1,0,0]
	v_pk_fma_f32 v[64:65], v[58:59], v[74:75], v[72:73] op_sel_hi:[0,1,1]
	v_pk_fma_f32 v[72:73], v[58:59], v[32:33], v[80:81] op_sel_hi:[0,1,1]
	v_pk_fma_f32 v[80:81], v[58:59], v[112:113], v[88:89] op_sel_hi:[0,1,1]
	v_pk_fma_f32 v[88:89], v[58:59], v[34:35], v[96:97] op_sel_hi:[0,1,1]
	v_mov_b32_e32 v58, v59
	v_pk_fma_f32 v[74:75], v[58:59], v[74:75], v[82:83] op_sel_hi:[0,1,1]
	v_pk_fma_f32 v[82:83], v[58:59], v[32:33], v[90:91] op_sel_hi:[0,1,1]
	v_pk_fma_f32 v[90:91], v[58:59], v[112:113], v[98:99] op_sel_hi:[0,1,1]
	v_pk_fma_f32 v[58:59], v[58:59], v[34:35], v[66:67] op_sel_hi:[0,1,1]
	ds_read_b128 v[32:35], v209 offset:1664
	s_waitcnt lgkmcnt(1)
	v_mad_i64_i32 v[6:7], s[0:1], v4, s53, v[148:149]
	global_load_dwordx4 v[60:63], v[6:7], off
	s_waitcnt vmcnt(13)
	v_lshlrev_b32_e32 v66, 16, v24
	v_and_b32_e32 v67, 0xffff0000, v24
	s_waitcnt lgkmcnt(0)
	v_pk_fma_f32 v[96:97], v[32:33], v[66:67], v[104:105] op_sel_hi:[0,1,1]
	v_lshlrev_b32_e32 v24, 16, v25
	v_and_b32_e32 v25, 0xffff0000, v25
	v_lshlrev_b32_e32 v104, 16, v26
	v_and_b32_e32 v105, 0xffff0000, v26
	v_lshlrev_b32_e32 v26, 16, v27
	v_and_b32_e32 v27, 0xffff0000, v27
	v_pk_fma_f32 v[98:99], v[32:33], v[24:25], v[106:107] op_sel_hi:[0,1,1]
	v_pk_fma_f32 v[106:107], v[32:33], v[104:105], v[114:115] op_sel_hi:[0,1,1]
	v_pk_fma_f32 v[112:113], v[32:33], v[26:27], v[120:121] op_sel_hi:[0,1,1]
	v_pk_fma_f32 v[114:115], v[32:33], v[66:67], v[122:123] op_sel:[1,0,0]
	v_pk_fma_f32 v[120:121], v[32:33], v[24:25], v[128:129] op_sel:[1,0,0]
	v_pk_fma_f32 v[122:123], v[32:33], v[104:105], v[130:131] op_sel:[1,0,0]
	v_pk_fma_f32 v[32:33], v[32:33], v[26:27], v[56:57] op_sel:[1,0,0]
	v_pk_fma_f32 v[56:57], v[34:35], v[66:67], v[64:65] op_sel_hi:[0,1,1]
	v_pk_fma_f32 v[64:65], v[34:35], v[24:25], v[72:73] op_sel_hi:[0,1,1]
	v_pk_fma_f32 v[72:73], v[34:35], v[104:105], v[80:81] op_sel_hi:[0,1,1]
	v_pk_fma_f32 v[80:81], v[34:35], v[26:27], v[88:89] op_sel_hi:[0,1,1]
	v_mov_b32_e32 v34, v35
	v_pk_fma_f32 v[66:67], v[34:35], v[66:67], v[74:75] op_sel_hi:[0,1,1]
	v_pk_fma_f32 v[74:75], v[34:35], v[24:25], v[82:83] op_sel_hi:[0,1,1]
	v_pk_fma_f32 v[82:83], v[34:35], v[104:105], v[90:91] op_sel_hi:[0,1,1]
	v_pk_fma_f32 v[34:35], v[34:35], v[26:27], v[58:59] op_sel_hi:[0,1,1]
	ds_read_b128 v[24:27], v209 offset:1792
	v_mad_i64_i32 v[4:5], s[0:1], v5, s53, v[148:149]
	global_load_dwordx4 v[52:55], v[4:5], off
	ds_read2_b32 v[4:5], v210 offset0:112 offset1:116
	s_waitcnt vmcnt(13)
	v_lshlrev_b32_e32 v58, 16, v16
	v_and_b32_e32 v59, 0xffff0000, v16
	s_waitcnt lgkmcnt(1)
	v_pk_fma_f32 v[88:89], v[24:25], v[58:59], v[96:97] op_sel_hi:[0,1,1]
	v_lshlrev_b32_e32 v16, 16, v17
	v_and_b32_e32 v17, 0xffff0000, v17
	v_lshlrev_b32_e32 v96, 16, v18
	v_and_b32_e32 v97, 0xffff0000, v18
	v_lshlrev_b32_e32 v18, 16, v19
	v_and_b32_e32 v19, 0xffff0000, v19
	v_pk_fma_f32 v[90:91], v[24:25], v[16:17], v[98:99] op_sel_hi:[0,1,1]
	v_pk_fma_f32 v[98:99], v[24:25], v[96:97], v[106:107] op_sel_hi:[0,1,1]
	v_pk_fma_f32 v[104:105], v[24:25], v[18:19], v[112:113] op_sel_hi:[0,1,1]
	v_pk_fma_f32 v[106:107], v[24:25], v[58:59], v[114:115] op_sel:[1,0,0]
	v_pk_fma_f32 v[112:113], v[24:25], v[16:17], v[120:121] op_sel:[1,0,0]
	v_pk_fma_f32 v[114:115], v[24:25], v[96:97], v[122:123] op_sel:[1,0,0]
	v_pk_fma_f32 v[24:25], v[24:25], v[18:19], v[32:33] op_sel:[1,0,0]
	v_pk_fma_f32 v[32:33], v[26:27], v[58:59], v[56:57] op_sel_hi:[0,1,1]
	v_pk_fma_f32 v[56:57], v[26:27], v[16:17], v[64:65] op_sel_hi:[0,1,1]
	v_pk_fma_f32 v[64:65], v[26:27], v[96:97], v[72:73] op_sel_hi:[0,1,1]
	v_pk_fma_f32 v[72:73], v[26:27], v[18:19], v[80:81] op_sel_hi:[0,1,1]
	v_mov_b32_e32 v26, v27
	v_pk_fma_f32 v[58:59], v[26:27], v[58:59], v[66:67] op_sel_hi:[0,1,1]
	v_pk_fma_f32 v[66:67], v[26:27], v[16:17], v[74:75] op_sel_hi:[0,1,1]
	v_pk_fma_f32 v[74:75], v[26:27], v[96:97], v[82:83] op_sel_hi:[0,1,1]
	v_pk_fma_f32 v[26:27], v[26:27], v[18:19], v[34:35] op_sel_hi:[0,1,1]
	ds_read_b128 v[16:19], v209 offset:1920
	s_waitcnt lgkmcnt(1)
	v_mad_i64_i32 v[6:7], s[0:1], v4, s53, v[148:149]
	global_load_dwordx4 v[28:31], v[6:7], off
	s_waitcnt vmcnt(13)
	v_lshlrev_b32_e32 v34, 16, v8
	v_and_b32_e32 v35, 0xffff0000, v8
	v_lshlrev_b32_e32 v8, 16, v9
	v_and_b32_e32 v9, 0xffff0000, v9
	v_lshlrev_b32_e32 v80, 16, v10
	v_and_b32_e32 v81, 0xffff0000, v10
	v_lshlrev_b32_e32 v10, 16, v11
	v_and_b32_e32 v11, 0xffff0000, v11
	s_waitcnt lgkmcnt(0)
	v_pk_fma_f32 v[150:151], v[16:17], v[34:35], v[88:89] op_sel_hi:[0,1,1]
	v_pk_fma_f32 v[158:159], v[16:17], v[8:9], v[90:91] op_sel_hi:[0,1,1]
	v_pk_fma_f32 v[160:161], v[16:17], v[80:81], v[98:99] op_sel_hi:[0,1,1]
	v_pk_fma_f32 v[162:163], v[16:17], v[10:11], v[104:105] op_sel_hi:[0,1,1]
	v_pk_fma_f32 v[164:165], v[16:17], v[34:35], v[106:107] op_sel:[1,0,0]
	v_pk_fma_f32 v[166:167], v[16:17], v[8:9], v[112:113] op_sel:[1,0,0]
	v_pk_fma_f32 v[168:169], v[16:17], v[80:81], v[114:115] op_sel:[1,0,0]
	v_pk_fma_f32 v[170:171], v[16:17], v[10:11], v[24:25] op_sel:[1,0,0]
	v_mov_b32_e32 v16, v19
	s_waitcnt vmcnt(12)
; DI float bf_lo(unsigned u) { return __uint_as_float(u << 16); }
; DI float bf_hi(unsigned u) { return __uint_as_float(u & 0xffff0000u); }
; DI void dsa_job(const Params& p, int b, int tq0, char* lds) {
;     ...
;   auto pv_load = [&](int grp, u32x4* dst) {
; #pragma unroll
;     for (int s = 0; s < 16; ++s) dst[s] = *(const u32x4*)(vb + (size_t)kid[4 * (grp * 16 + s) + ksub] * LDH);
;   };
;   auto pv_fma = [&](int grp, const u32x4* src) {
; #pragma unroll
;     for (int s = 0; s < 16; ++s) {
;       const int slot = 4 * (grp * 16 + s) + ksub;
;       const f32x4 pp = *(const f32x4*)(Pl + slot * 8 + g * 4);
;       const u32x4 vv = src[s];
; #pragma unroll
;       for (int hh = 0; hh < 4; ++hh) {
;         const f32x2 ph = {pp[hh], pp[hh]};
; #pragma unroll
;         for (int e = 0; e < 4; ++e) {
;           const f32x2 vf2 = {bf_lo(vv[e]), bf_hi(vv[e])};
;           acc2[hh][e] += ph * vf2;
;         }
;       }
;     }
;   };
;   pv_load(0, vA);
;   pv_load(1, vB);
;   pv_fma(0, vA);
;   pv_load(2, vA);
;   pv_fma(1, vB);
;   pv_load(3, vB);
;   pv_fma(2, vA);
	v_lshlrev_b32_e32 v216, 16, v140
	v_and_b32_e32 v217, 0xffff0000, v140
	v_lshlrev_b32_e32 v140, 16, v141
	v_and_b32_e32 v141, 0xffff0000, v141
	v_lshlrev_b32_e32 v218, 16, v142
	v_and_b32_e32 v219, 0xffff0000, v142
	v_lshlrev_b32_e32 v142, 16, v143
	v_and_b32_e32 v143, 0xffff0000, v143
	v_pk_fma_f32 v[174:175], v[18:19], v[8:9], v[56:57] op_sel_hi:[0,1,1]
	v_pk_fma_f32 v[178:179], v[18:19], v[10:11], v[72:73] op_sel_hi:[0,1,1]
	v_pk_fma_f32 v[182:183], v[16:17], v[8:9], v[66:67] op_sel_hi:[0,1,1]
	v_pk_fma_f32 v[186:187], v[16:17], v[10:11], v[26:27] op_sel_hi:[0,1,1]
	v_pk_fma_f32 v[150:151], v[212:213], v[216:217], v[150:151] op_sel_hi:[0,1,1]
	v_pk_fma_f32 v[158:159], v[212:213], v[140:141], v[158:159] op_sel_hi:[0,1,1]
	v_pk_fma_f32 v[160:161], v[212:213], v[218:219], v[160:161] op_sel_hi:[0,1,1]
	v_pk_fma_f32 v[162:163], v[212:213], v[142:143], v[162:163] op_sel_hi:[0,1,1]
	v_pk_fma_f32 v[164:165], v[212:213], v[216:217], v[164:165] op_sel:[1,0,0]
	v_pk_fma_f32 v[166:167], v[212:213], v[140:141], v[166:167] op_sel:[1,0,0]
	v_pk_fma_f32 v[168:169], v[212:213], v[218:219], v[168:169] op_sel:[1,0,0]
	v_pk_fma_f32 v[170:171], v[212:213], v[142:143], v[170:171] op_sel:[1,0,0]
	v_mov_b32_e32 v212, v215
	v_pk_fma_f32 v[174:175], v[214:215], v[140:141], v[174:175] op_sel_hi:[0,1,1]
	v_pk_fma_f32 v[178:179], v[214:215], v[142:143], v[178:179] op_sel_hi:[0,1,1]
	v_pk_fma_f32 v[182:183], v[212:213], v[140:141], v[182:183] op_sel_hi:[0,1,1]
	v_pk_fma_f32 v[186:187], v[212:213], v[142:143], v[186:187] op_sel_hi:[0,1,1]
	ds_read_b128 v[140:143], v209 offset:2176
	v_mad_i64_i32 v[4:5], s[0:1], v5, s53, v[148:149]
	global_load_dwordx4 v[20:23], v[4:5], off
	ds_read2_b32 v[4:5], v210 offset0:120 offset1:124
	v_pk_fma_f32 v[172:173], v[18:19], v[34:35], v[32:33] op_sel_hi:[0,1,1]
	v_pk_fma_f32 v[176:177], v[18:19], v[80:81], v[64:65] op_sel_hi:[0,1,1]
	v_pk_fma_f32 v[180:181], v[16:17], v[34:35], v[58:59] op_sel_hi:[0,1,1]
	v_pk_fma_f32 v[184:185], v[16:17], v[80:81], v[74:75] op_sel_hi:[0,1,1]
	v_pk_fma_f32 v[172:173], v[214:215], v[216:217], v[172:173] op_sel_hi:[0,1,1]
	v_pk_fma_f32 v[176:177], v[214:215], v[218:219], v[176:177] op_sel_hi:[0,1,1]
	v_pk_fma_f32 v[180:181], v[212:213], v[216:217], v[180:181] op_sel_hi:[0,1,1]
	v_pk_fma_f32 v[184:185], v[212:213], v[218:219], v[184:185] op_sel_hi:[0,1,1]
	s_waitcnt vmcnt(12)
	v_lshlrev_b32_e32 v212, 16, v132
	v_and_b32_e32 v213, 0xffff0000, v132
	v_lshlrev_b32_e32 v132, 16, v133
	v_and_b32_e32 v133, 0xffff0000, v133
	v_lshlrev_b32_e32 v214, 16, v134
	v_and_b32_e32 v215, 0xffff0000, v134
	v_lshlrev_b32_e32 v134, 16, v135
	v_and_b32_e32 v135, 0xffff0000, v135
	s_waitcnt lgkmcnt(1)
	v_pk_fma_f32 v[150:151], v[140:141], v[212:213], v[150:151] op_sel_hi:[0,1,1]
	v_pk_fma_f32 v[158:159], v[140:141], v[132:133], v[158:159] op_sel_hi:[0,1,1]
	v_pk_fma_f32 v[160:161], v[140:141], v[214:215], v[160:161] op_sel_hi:[0,1,1]
	v_pk_fma_f32 v[162:163], v[140:141], v[134:135], v[162:163] op_sel_hi:[0,1,1]
	v_pk_fma_f32 v[164:165], v[140:141], v[212:213], v[164:165] op_sel:[1,0,0]
	v_pk_fma_f32 v[166:167], v[140:141], v[132:133], v[166:167] op_sel:[1,0,0]
	v_pk_fma_f32 v[168:169], v[140:141], v[214:215], v[168:169] op_sel:[1,0,0]
	v_pk_fma_f32 v[140:141], v[140:141], v[134:135], v[170:171] op_sel:[1,0,0]
	v_pk_fma_f32 v[170:171], v[142:143], v[212:213], v[172:173] op_sel_hi:[0,1,1]
	v_pk_fma_f32 v[172:173], v[142:143], v[132:133], v[174:175] op_sel_hi:[0,1,1]
	v_pk_fma_f32 v[174:175], v[142:143], v[214:215], v[176:177] op_sel_hi:[0,1,1]
	v_pk_fma_f32 v[176:177], v[142:143], v[134:135], v[178:179] op_sel_hi:[0,1,1]
	v_mov_b32_e32 v142, v143
	v_pk_fma_f32 v[178:179], v[142:143], v[212:213], v[180:181] op_sel_hi:[0,1,1]
	v_pk_fma_f32 v[180:181], v[142:143], v[132:133], v[182:183] op_sel_hi:[0,1,1]
	v_pk_fma_f32 v[182:183], v[142:143], v[214:215], v[184:185] op_sel_hi:[0,1,1]
	v_pk_fma_f32 v[142:143], v[142:143], v[134:135], v[186:187] op_sel_hi:[0,1,1]
	ds_read_b128 v[132:135], v209 offset:2304
	s_waitcnt lgkmcnt(1)
	v_mad_i64_i32 v[6:7], s[0:1], v4, s53, v[148:149]
	global_load_dwordx4 v[12:15], v[6:7], off
	ds_read2_b32 v[8:9], v210 offset0:128 offset1:132
	s_waitcnt vmcnt(12)
	v_lshlrev_b32_e32 v184, 16, v124
	v_and_b32_e32 v185, 0xffff0000, v124
	v_lshlrev_b32_e32 v124, 16, v125
	v_and_b32_e32 v125, 0xffff0000, v125
	v_lshlrev_b32_e32 v186, 16, v126
	v_and_b32_e32 v187, 0xffff0000, v126
	v_lshlrev_b32_e32 v126, 16, v127
	v_and_b32_e32 v127, 0xffff0000, v127
	s_waitcnt lgkmcnt(1)
	v_pk_fma_f32 v[150:151], v[132:133], v[184:185], v[150:151] op_sel_hi:[0,1,1]
	v_pk_fma_f32 v[158:159], v[132:133], v[124:125], v[158:159] op_sel_hi:[0,1,1]
	v_pk_fma_f32 v[160:161], v[132:133], v[186:187], v[160:161] op_sel_hi:[0,1,1]
	v_pk_fma_f32 v[162:163], v[132:133], v[126:127], v[162:163] op_sel_hi:[0,1,1]
	v_pk_fma_f32 v[164:165], v[132:133], v[184:185], v[164:165] op_sel:[1,0,0]
	v_pk_fma_f32 v[166:167], v[132:133], v[124:125], v[166:167] op_sel:[1,0,0]
	v_pk_fma_f32 v[168:169], v[132:133], v[186:187], v[168:169] op_sel:[1,0,0]
	v_pk_fma_f32 v[132:133], v[132:133], v[126:127], v[140:141] op_sel:[1,0,0]
	v_pk_fma_f32 v[140:141], v[134:135], v[184:185], v[170:171] op_sel_hi:[0,1,1]
	v_pk_fma_f32 v[170:171], v[134:135], v[124:125], v[172:173] op_sel_hi:[0,1,1]
	v_pk_fma_f32 v[172:173], v[134:135], v[186:187], v[174:175] op_sel_hi:[0,1,1]
	v_pk_fma_f32 v[174:175], v[134:135], v[126:127], v[176:177] op_sel_hi:[0,1,1]
	v_mov_b32_e32 v134, v135
	v_pk_fma_f32 v[176:177], v[134:135], v[184:185], v[178:179] op_sel_hi:[0,1,1]
	v_pk_fma_f32 v[178:179], v[134:135], v[124:125], v[180:181] op_sel_hi:[0,1,1]
	v_pk_fma_f32 v[180:181], v[134:135], v[186:187], v[182:183] op_sel_hi:[0,1,1]
	v_pk_fma_f32 v[134:135], v[134:135], v[126:127], v[142:143] op_sel_hi:[0,1,1]
	ds_read_b128 v[124:127], v209 offset:2432
	v_mad_i64_i32 v[4:5], s[0:1], v5, s53, v[148:149]
	s_waitcnt lgkmcnt(1)
; DI float bf_lo(unsigned u) { return __uint_as_float(u << 16); }
; DI float bf_hi(unsigned u) { return __uint_as_float(u & 0xffff0000u); }
; DI void dsa_job(const Params& p, int b, int tq0, char* lds) {
;     ...
;   auto pv_load = [&](int grp, u32x4* dst) {
; #pragma unroll
;     for (int s = 0; s < 16; ++s) dst[s] = *(const u32x4*)(vb + (size_t)kid[4 * (grp * 16 + s) + ksub] * LDH);
;   };
;   auto pv_fma = [&](int grp, const u32x4* src) {
; #pragma unroll
;     for (int s = 0; s < 16; ++s) {
;       const int slot = 4 * (grp * 16 + s) + ksub;
;       const f32x4 pp = *(const f32x4*)(Pl + slot * 8 + g * 4);
;       const u32x4 vv = src[s];
; #pragma unroll
;       for (int hh = 0; hh < 4; ++hh) {
;         const f32x2 ph = {pp[hh], pp[hh]};
; #pragma unroll
;         for (int e = 0; e < 4; ++e) {
;           const f32x2 vf2 = {bf_lo(vv[e]), bf_hi(vv[e])};
;           acc2[hh][e] += ph * vf2;
;         }
;       }
;     }
;   };
;   pv_load(0, vA);
;   pv_load(1, vB);
;   pv_fma(0, vA);
;   pv_load(2, vA);
;   pv_fma(1, vB);
;   pv_load(3, vB);
;   pv_fma(2, vA);
	v_mad_i64_i32 v[10:11], s[0:1], v8, s53, v[148:149]
	global_load_dwordx4 v[144:147], v[10:11], off
	s_waitcnt vmcnt(12)
	v_lshlrev_b32_e32 v142, 16, v116
	global_load_dwordx4 v[4:7], v[4:5], off
	v_and_b32_e32 v143, 0xffff0000, v116
	v_lshlrev_b32_e32 v116, 16, v117
	v_and_b32_e32 v117, 0xffff0000, v117
	v_lshlrev_b32_e32 v182, 16, v118
	v_and_b32_e32 v183, 0xffff0000, v118
	v_lshlrev_b32_e32 v118, 16, v119
	v_and_b32_e32 v119, 0xffff0000, v119
	s_waitcnt lgkmcnt(0)
	v_pk_fma_f32 v[150:151], v[124:125], v[142:143], v[150:151] op_sel_hi:[0,1,1]
	v_pk_fma_f32 v[158:159], v[124:125], v[116:117], v[158:159] op_sel_hi:[0,1,1]
	v_pk_fma_f32 v[160:161], v[124:125], v[182:183], v[160:161] op_sel_hi:[0,1,1]
	v_pk_fma_f32 v[162:163], v[124:125], v[118:119], v[162:163] op_sel_hi:[0,1,1]
	v_pk_fma_f32 v[164:165], v[124:125], v[142:143], v[164:165] op_sel:[1,0,0]
	v_pk_fma_f32 v[166:167], v[124:125], v[116:117], v[166:167] op_sel:[1,0,0]
	v_pk_fma_f32 v[168:169], v[124:125], v[182:183], v[168:169] op_sel:[1,0,0]
	v_pk_fma_f32 v[124:125], v[124:125], v[118:119], v[132:133] op_sel:[1,0,0]
	v_pk_fma_f32 v[132:133], v[126:127], v[142:143], v[140:141] op_sel_hi:[0,1,1]
	v_pk_fma_f32 v[140:141], v[126:127], v[116:117], v[170:171] op_sel_hi:[0,1,1]
	v_pk_fma_f32 v[170:171], v[126:127], v[182:183], v[172:173] op_sel_hi:[0,1,1]
	v_pk_fma_f32 v[172:173], v[126:127], v[118:119], v[174:175] op_sel_hi:[0,1,1]
	v_mov_b32_e32 v126, v127
	v_pk_fma_f32 v[142:143], v[126:127], v[142:143], v[176:177] op_sel_hi:[0,1,1]
	v_pk_fma_f32 v[174:175], v[126:127], v[116:117], v[178:179] op_sel_hi:[0,1,1]
	v_pk_fma_f32 v[176:177], v[126:127], v[182:183], v[180:181] op_sel_hi:[0,1,1]
	v_pk_fma_f32 v[126:127], v[126:127], v[118:119], v[134:135] op_sel_hi:[0,1,1]
	ds_read_b128 v[116:119], v209 offset:2560
	s_waitcnt vmcnt(12)
	v_lshlrev_b32_e32 v134, 16, v108
	v_and_b32_e32 v135, 0xffff0000, v108
	v_lshlrev_b32_e32 v108, 16, v109
	v_and_b32_e32 v109, 0xffff0000, v109
	v_lshlrev_b32_e32 v178, 16, v110
	v_and_b32_e32 v179, 0xffff0000, v110
	v_lshlrev_b32_e32 v110, 16, v111
	v_and_b32_e32 v111, 0xffff0000, v111
	s_waitcnt lgkmcnt(0)
	v_pk_fma_f32 v[150:151], v[116:117], v[134:135], v[150:151] op_sel_hi:[0,1,1]
	v_pk_fma_f32 v[158:159], v[116:117], v[108:109], v[158:159] op_sel_hi:[0,1,1]
	v_pk_fma_f32 v[160:161], v[116:117], v[178:179], v[160:161] op_sel_hi:[0,1,1]
	v_pk_fma_f32 v[162:163], v[116:117], v[110:111], v[162:163] op_sel_hi:[0,1,1]
	v_pk_fma_f32 v[164:165], v[116:117], v[134:135], v[164:165] op_sel:[1,0,0]
	v_pk_fma_f32 v[166:167], v[116:117], v[108:109], v[166:167] op_sel:[1,0,0]
	v_pk_fma_f32 v[168:169], v[116:117], v[178:179], v[168:169] op_sel:[1,0,0]
	v_pk_fma_f32 v[116:117], v[116:117], v[110:111], v[124:125] op_sel:[1,0,0]
	v_pk_fma_f32 v[124:125], v[118:119], v[134:135], v[132:133] op_sel_hi:[0,1,1]
	v_pk_fma_f32 v[132:133], v[118:119], v[108:109], v[140:141] op_sel_hi:[0,1,1]
	v_pk_fma_f32 v[140:141], v[118:119], v[178:179], v[170:171] op_sel_hi:[0,1,1]
	v_pk_fma_f32 v[170:171], v[118:119], v[110:111], v[172:173] op_sel_hi:[0,1,1]
	v_mov_b32_e32 v118, v119
	v_pk_fma_f32 v[134:135], v[118:119], v[134:135], v[142:143] op_sel_hi:[0,1,1]
	v_pk_fma_f32 v[142:143], v[118:119], v[108:109], v[174:175] op_sel_hi:[0,1,1]
	v_pk_fma_f32 v[172:173], v[118:119], v[178:179], v[176:177] op_sel_hi:[0,1,1]
	v_pk_fma_f32 v[118:119], v[118:119], v[110:111], v[126:127] op_sel_hi:[0,1,1]
	ds_read_b128 v[108:111], v209 offset:2688
	s_waitcnt vmcnt(11)
	v_lshlrev_b32_e32 v126, 16, v100
	v_and_b32_e32 v127, 0xffff0000, v100
	v_lshlrev_b32_e32 v100, 16, v101
	v_and_b32_e32 v101, 0xffff0000, v101
	v_lshlrev_b32_e32 v174, 16, v102
	v_and_b32_e32 v175, 0xffff0000, v102
	v_lshlrev_b32_e32 v102, 16, v103
	v_and_b32_e32 v103, 0xffff0000, v103
	s_waitcnt lgkmcnt(0)
	v_pk_fma_f32 v[150:151], v[108:109], v[126:127], v[150:151] op_sel_hi:[0,1,1]
	v_pk_fma_f32 v[158:159], v[108:109], v[100:101], v[158:159] op_sel_hi:[0,1,1]
	v_pk_fma_f32 v[160:161], v[108:109], v[174:175], v[160:161] op_sel_hi:[0,1,1]
	v_pk_fma_f32 v[162:163], v[108:109], v[102:103], v[162:163] op_sel_hi:[0,1,1]
	v_pk_fma_f32 v[164:165], v[108:109], v[126:127], v[164:165] op_sel:[1,0,0]
	v_pk_fma_f32 v[166:167], v[108:109], v[100:101], v[166:167] op_sel:[1,0,0]
	v_pk_fma_f32 v[168:169], v[108:109], v[174:175], v[168:169] op_sel:[1,0,0]
	v_pk_fma_f32 v[108:109], v[108:109], v[102:103], v[116:117] op_sel:[1,0,0]
	v_pk_fma_f32 v[116:117], v[110:111], v[126:127], v[124:125] op_sel_hi:[0,1,1]
	v_pk_fma_f32 v[124:125], v[110:111], v[100:101], v[132:133] op_sel_hi:[0,1,1]
	v_pk_fma_f32 v[132:133], v[110:111], v[174:175], v[140:141] op_sel_hi:[0,1,1]
	v_pk_fma_f32 v[140:141], v[110:111], v[102:103], v[170:171] op_sel_hi:[0,1,1]
	v_mov_b32_e32 v110, v111
	v_pk_fma_f32 v[126:127], v[110:111], v[126:127], v[134:135] op_sel_hi:[0,1,1]
	v_pk_fma_f32 v[134:135], v[110:111], v[100:101], v[142:143] op_sel_hi:[0,1,1]
	v_pk_fma_f32 v[142:143], v[110:111], v[174:175], v[172:173] op_sel_hi:[0,1,1]
	v_pk_fma_f32 v[110:111], v[110:111], v[102:103], v[118:119] op_sel_hi:[0,1,1]
	ds_read_b128 v[100:103], v209 offset:2816
	s_waitcnt vmcnt(10)
	v_lshlrev_b32_e32 v118, 16, v92
	v_and_b32_e32 v119, 0xffff0000, v92
	v_lshlrev_b32_e32 v92, 16, v93
	v_and_b32_e32 v93, 0xffff0000, v93
	v_lshlrev_b32_e32 v170, 16, v94
	v_and_b32_e32 v171, 0xffff0000, v94
	v_lshlrev_b32_e32 v94, 16, v95
	v_and_b32_e32 v95, 0xffff0000, v95
	s_waitcnt lgkmcnt(0)
; DI float bf_lo(unsigned u) { return __uint_as_float(u << 16); }
; DI float bf_hi(unsigned u) { return __uint_as_float(u & 0xffff0000u); }
; DI void dsa_job(const Params& p, int b, int tq0, char* lds) {
;     ...
;   auto pv_load = [&](int grp, u32x4* dst) {
; #pragma unroll
;     for (int s = 0; s < 16; ++s) dst[s] = *(const u32x4*)(vb + (size_t)kid[4 * (grp * 16 + s) + ksub] * LDH);
;   };
;   auto pv_fma = [&](int grp, const u32x4* src) {
; #pragma unroll
;     for (int s = 0; s < 16; ++s) {
;       const int slot = 4 * (grp * 16 + s) + ksub;
;       const f32x4 pp = *(const f32x4*)(Pl + slot * 8 + g * 4);
;       const u32x4 vv = src[s];
; #pragma unroll
;       for (int hh = 0; hh < 4; ++hh) {
;         const f32x2 ph = {pp[hh], pp[hh]};
; #pragma unroll
;         for (int e = 0; e < 4; ++e) {
;           const f32x2 vf2 = {bf_lo(vv[e]), bf_hi(vv[e])};
;           acc2[hh][e] += ph * vf2;
;         }
;       }
;     }
;   };
;   pv_load(0, vA);
;   pv_load(1, vB);
;   pv_fma(0, vA);
;   pv_load(2, vA);
;   pv_fma(1, vB);
;   pv_load(3, vB);
;   pv_fma(2, vA);
	v_pk_fma_f32 v[150:151], v[100:101], v[118:119], v[150:151] op_sel_hi:[0,1,1]
	v_pk_fma_f32 v[158:159], v[100:101], v[92:93], v[158:159] op_sel_hi:[0,1,1]
	v_pk_fma_f32 v[160:161], v[100:101], v[170:171], v[160:161] op_sel_hi:[0,1,1]
	v_pk_fma_f32 v[162:163], v[100:101], v[94:95], v[162:163] op_sel_hi:[0,1,1]
	v_pk_fma_f32 v[164:165], v[100:101], v[118:119], v[164:165] op_sel:[1,0,0]
	v_pk_fma_f32 v[166:167], v[100:101], v[92:93], v[166:167] op_sel:[1,0,0]
	v_pk_fma_f32 v[168:169], v[100:101], v[170:171], v[168:169] op_sel:[1,0,0]
	v_pk_fma_f32 v[100:101], v[100:101], v[94:95], v[108:109] op_sel:[1,0,0]
	v_pk_fma_f32 v[108:109], v[102:103], v[118:119], v[116:117] op_sel_hi:[0,1,1]
	v_pk_fma_f32 v[116:117], v[102:103], v[92:93], v[124:125] op_sel_hi:[0,1,1]
	v_pk_fma_f32 v[124:125], v[102:103], v[170:171], v[132:133] op_sel_hi:[0,1,1]
	v_pk_fma_f32 v[132:133], v[102:103], v[94:95], v[140:141] op_sel_hi:[0,1,1]
	v_mov_b32_e32 v102, v103
	v_pk_fma_f32 v[118:119], v[102:103], v[118:119], v[126:127] op_sel_hi:[0,1,1]
	v_pk_fma_f32 v[126:127], v[102:103], v[92:93], v[134:135] op_sel_hi:[0,1,1]
	v_pk_fma_f32 v[134:135], v[102:103], v[170:171], v[142:143] op_sel_hi:[0,1,1]
	v_pk_fma_f32 v[102:103], v[102:103], v[94:95], v[110:111] op_sel_hi:[0,1,1]
	ds_read_b128 v[92:95], v209 offset:2944
	s_waitcnt vmcnt(9)
	v_lshlrev_b32_e32 v110, 16, v84
	v_and_b32_e32 v111, 0xffff0000, v84
	v_lshlrev_b32_e32 v84, 16, v85
	v_and_b32_e32 v85, 0xffff0000, v85
	s_waitcnt lgkmcnt(0)
	v_pk_fma_f32 v[140:141], v[92:93], v[110:111], v[150:151] op_sel_hi:[0,1,1]
	v_lshlrev_b32_e32 v150, 16, v86
	v_and_b32_e32 v151, 0xffff0000, v86
	v_lshlrev_b32_e32 v86, 16, v87
	v_and_b32_e32 v87, 0xffff0000, v87
	v_pk_fma_f32 v[142:143], v[92:93], v[84:85], v[158:159] op_sel_hi:[0,1,1]
	v_pk_fma_f32 v[158:159], v[92:93], v[150:151], v[160:161] op_sel_hi:[0,1,1]
	v_pk_fma_f32 v[160:161], v[92:93], v[86:87], v[162:163] op_sel_hi:[0,1,1]
	v_pk_fma_f32 v[162:163], v[92:93], v[110:111], v[164:165] op_sel:[1,0,0]
	v_pk_fma_f32 v[164:165], v[92:93], v[84:85], v[166:167] op_sel:[1,0,0]
	v_pk_fma_f32 v[166:167], v[92:93], v[150:151], v[168:169] op_sel:[1,0,0]
	v_pk_fma_f32 v[92:93], v[92:93], v[86:87], v[100:101] op_sel:[1,0,0]
	v_pk_fma_f32 v[100:101], v[94:95], v[110:111], v[108:109] op_sel_hi:[0,1,1]
	v_pk_fma_f32 v[108:109], v[94:95], v[84:85], v[116:117] op_sel_hi:[0,1,1]
	v_pk_fma_f32 v[116:117], v[94:95], v[150:151], v[124:125] op_sel_hi:[0,1,1]
	v_pk_fma_f32 v[124:125], v[94:95], v[86:87], v[132:133] op_sel_hi:[0,1,1]
	v_mov_b32_e32 v94, v95
	v_pk_fma_f32 v[110:111], v[94:95], v[110:111], v[118:119] op_sel_hi:[0,1,1]
	v_pk_fma_f32 v[118:119], v[94:95], v[84:85], v[126:127] op_sel_hi:[0,1,1]
	v_pk_fma_f32 v[126:127], v[94:95], v[150:151], v[134:135] op_sel_hi:[0,1,1]
	v_pk_fma_f32 v[94:95], v[94:95], v[86:87], v[102:103] op_sel_hi:[0,1,1]
	ds_read_b128 v[84:87], v209 offset:3072
	s_waitcnt vmcnt(8)
	v_lshlrev_b32_e32 v102, 16, v76
	v_and_b32_e32 v103, 0xffff0000, v76
	v_lshlrev_b32_e32 v76, 16, v77
	v_and_b32_e32 v77, 0xffff0000, v77
	s_waitcnt lgkmcnt(0)
	v_pk_fma_f32 v[132:133], v[84:85], v[102:103], v[140:141] op_sel_hi:[0,1,1]
	v_lshlrev_b32_e32 v140, 16, v78
	v_and_b32_e32 v141, 0xffff0000, v78
	v_lshlrev_b32_e32 v78, 16, v79
	v_and_b32_e32 v79, 0xffff0000, v79
	v_pk_fma_f32 v[134:135], v[84:85], v[76:77], v[142:143] op_sel_hi:[0,1,1]
	v_pk_fma_f32 v[142:143], v[84:85], v[140:141], v[158:159] op_sel_hi:[0,1,1]
	v_pk_fma_f32 v[150:151], v[84:85], v[78:79], v[160:161] op_sel_hi:[0,1,1]
	v_pk_fma_f32 v[158:159], v[84:85], v[102:103], v[162:163] op_sel:[1,0,0]
	v_pk_fma_f32 v[160:161], v[84:85], v[76:77], v[164:165] op_sel:[1,0,0]
	v_pk_fma_f32 v[162:163], v[84:85], v[140:141], v[166:167] op_sel:[1,0,0]
	v_pk_fma_f32 v[84:85], v[84:85], v[78:79], v[92:93] op_sel:[1,0,0]
	v_pk_fma_f32 v[92:93], v[86:87], v[102:103], v[100:101] op_sel_hi:[0,1,1]
	v_pk_fma_f32 v[100:101], v[86:87], v[76:77], v[108:109] op_sel_hi:[0,1,1]
	v_pk_fma_f32 v[108:109], v[86:87], v[140:141], v[116:117] op_sel_hi:[0,1,1]
	v_pk_fma_f32 v[116:117], v[86:87], v[78:79], v[124:125] op_sel_hi:[0,1,1]
	v_mov_b32_e32 v86, v87
	v_pk_fma_f32 v[102:103], v[86:87], v[102:103], v[110:111] op_sel_hi:[0,1,1]
	v_pk_fma_f32 v[110:111], v[86:87], v[76:77], v[118:119] op_sel_hi:[0,1,1]
	v_pk_fma_f32 v[118:119], v[86:87], v[140:141], v[126:127] op_sel_hi:[0,1,1]
	v_pk_fma_f32 v[86:87], v[86:87], v[78:79], v[94:95] op_sel_hi:[0,1,1]
	ds_read_b128 v[76:79], v209 offset:3200
	s_waitcnt vmcnt(7)
	v_lshlrev_b32_e32 v94, 16, v68
	v_and_b32_e32 v95, 0xffff0000, v68
	v_lshlrev_b32_e32 v68, 16, v69
	v_and_b32_e32 v69, 0xffff0000, v69
	s_waitcnt lgkmcnt(0)
	v_pk_fma_f32 v[124:125], v[76:77], v[94:95], v[132:133] op_sel_hi:[0,1,1]
	v_lshlrev_b32_e32 v132, 16, v70
	v_and_b32_e32 v133, 0xffff0000, v70
	v_lshlrev_b32_e32 v70, 16, v71
	v_and_b32_e32 v71, 0xffff0000, v71
	v_pk_fma_f32 v[126:127], v[76:77], v[68:69], v[134:135] op_sel_hi:[0,1,1]
	v_pk_fma_f32 v[134:135], v[76:77], v[132:133], v[142:143] op_sel_hi:[0,1,1]
	v_pk_fma_f32 v[140:141], v[76:77], v[70:71], v[150:151] op_sel_hi:[0,1,1]
	v_pk_fma_f32 v[142:143], v[76:77], v[94:95], v[158:159] op_sel:[1,0,0]
	v_pk_fma_f32 v[150:151], v[76:77], v[68:69], v[160:161] op_sel:[1,0,0]
	v_pk_fma_f32 v[158:159], v[76:77], v[132:133], v[162:163] op_sel:[1,0,0]
	v_pk_fma_f32 v[76:77], v[76:77], v[70:71], v[84:85] op_sel:[1,0,0]
	v_pk_fma_f32 v[84:85], v[78:79], v[94:95], v[92:93] op_sel_hi:[0,1,1]
	v_pk_fma_f32 v[92:93], v[78:79], v[68:69], v[100:101] op_sel_hi:[0,1,1]
	v_pk_fma_f32 v[100:101], v[78:79], v[132:133], v[108:109] op_sel_hi:[0,1,1]
	v_pk_fma_f32 v[108:109], v[78:79], v[70:71], v[116:117] op_sel_hi:[0,1,1]
	v_mov_b32_e32 v78, v79
	v_pk_fma_f32 v[94:95], v[78:79], v[94:95], v[102:103] op_sel_hi:[0,1,1]
	v_pk_fma_f32 v[102:103], v[78:79], v[68:69], v[110:111] op_sel_hi:[0,1,1]
	v_pk_fma_f32 v[110:111], v[78:79], v[132:133], v[118:119] op_sel_hi:[0,1,1]
	v_pk_fma_f32 v[78:79], v[78:79], v[70:71], v[86:87] op_sel_hi:[0,1,1]
	ds_read_b128 v[68:71], v209 offset:3328
	s_waitcnt vmcnt(6)
; DI float bf_lo(unsigned u) { return __uint_as_float(u << 16); }
; DI float bf_hi(unsigned u) { return __uint_as_float(u & 0xffff0000u); }
; DI void dsa_job(const Params& p, int b, int tq0, char* lds) {
;     ...
;   auto pv_load = [&](int grp, u32x4* dst) {
; #pragma unroll
;     for (int s = 0; s < 16; ++s) dst[s] = *(const u32x4*)(vb + (size_t)kid[4 * (grp * 16 + s) + ksub] * LDH);
;   };
;   auto pv_fma = [&](int grp, const u32x4* src) {
; #pragma unroll
;     for (int s = 0; s < 16; ++s) {
;       const int slot = 4 * (grp * 16 + s) + ksub;
;       const f32x4 pp = *(const f32x4*)(Pl + slot * 8 + g * 4);
;       const u32x4 vv = src[s];
; #pragma unroll
;       for (int hh = 0; hh < 4; ++hh) {
;         const f32x2 ph = {pp[hh], pp[hh]};
; #pragma unroll
;         for (int e = 0; e < 4; ++e) {
;           const f32x2 vf2 = {bf_lo(vv[e]), bf_hi(vv[e])};
;           acc2[hh][e] += ph * vf2;
;         }
;       }
;     }
;   };
;   pv_load(0, vA);
;   pv_load(1, vB);
;   pv_fma(0, vA);
;   pv_load(2, vA);
;   pv_fma(1, vB);
;   pv_load(3, vB);
;   pv_fma(2, vA);
	v_lshlrev_b32_e32 v86, 16, v60
	v_and_b32_e32 v87, 0xffff0000, v60
	v_lshlrev_b32_e32 v60, 16, v61
	v_and_b32_e32 v61, 0xffff0000, v61
	s_waitcnt lgkmcnt(0)
	v_pk_fma_f32 v[116:117], v[68:69], v[86:87], v[124:125] op_sel_hi:[0,1,1]
	v_lshlrev_b32_e32 v124, 16, v62
	v_and_b32_e32 v125, 0xffff0000, v62
	v_lshlrev_b32_e32 v62, 16, v63
	v_and_b32_e32 v63, 0xffff0000, v63
	v_pk_fma_f32 v[118:119], v[68:69], v[60:61], v[126:127] op_sel_hi:[0,1,1]
	v_pk_fma_f32 v[126:127], v[68:69], v[124:125], v[134:135] op_sel_hi:[0,1,1]
	v_pk_fma_f32 v[132:133], v[68:69], v[62:63], v[140:141] op_sel_hi:[0,1,1]
	v_pk_fma_f32 v[134:135], v[68:69], v[86:87], v[142:143] op_sel:[1,0,0]
	v_pk_fma_f32 v[140:141], v[68:69], v[60:61], v[150:151] op_sel:[1,0,0]
	v_pk_fma_f32 v[142:143], v[68:69], v[124:125], v[158:159] op_sel:[1,0,0]
	v_pk_fma_f32 v[68:69], v[68:69], v[62:63], v[76:77] op_sel:[1,0,0]
	v_pk_fma_f32 v[76:77], v[70:71], v[86:87], v[84:85] op_sel_hi:[0,1,1]
	v_pk_fma_f32 v[84:85], v[70:71], v[60:61], v[92:93] op_sel_hi:[0,1,1]
	v_pk_fma_f32 v[92:93], v[70:71], v[124:125], v[100:101] op_sel_hi:[0,1,1]
	v_pk_fma_f32 v[100:101], v[70:71], v[62:63], v[108:109] op_sel_hi:[0,1,1]
	v_mov_b32_e32 v70, v71
	v_pk_fma_f32 v[86:87], v[70:71], v[86:87], v[94:95] op_sel_hi:[0,1,1]
	v_pk_fma_f32 v[94:95], v[70:71], v[60:61], v[102:103] op_sel_hi:[0,1,1]
	v_pk_fma_f32 v[102:103], v[70:71], v[124:125], v[110:111] op_sel_hi:[0,1,1]
	v_pk_fma_f32 v[70:71], v[70:71], v[62:63], v[78:79] op_sel_hi:[0,1,1]
	ds_read_b128 v[60:63], v209 offset:3456
	s_waitcnt vmcnt(5)
	v_lshlrev_b32_e32 v78, 16, v52
	v_and_b32_e32 v79, 0xffff0000, v52
	v_lshlrev_b32_e32 v52, 16, v53
	v_and_b32_e32 v53, 0xffff0000, v53
	s_waitcnt lgkmcnt(0)
	v_pk_fma_f32 v[108:109], v[60:61], v[78:79], v[116:117] op_sel_hi:[0,1,1]
	v_lshlrev_b32_e32 v116, 16, v54
	v_and_b32_e32 v117, 0xffff0000, v54
	v_lshlrev_b32_e32 v54, 16, v55
	v_and_b32_e32 v55, 0xffff0000, v55
	v_pk_fma_f32 v[110:111], v[60:61], v[52:53], v[118:119] op_sel_hi:[0,1,1]
	v_pk_fma_f32 v[118:119], v[60:61], v[116:117], v[126:127] op_sel_hi:[0,1,1]
	v_pk_fma_f32 v[124:125], v[60:61], v[54:55], v[132:133] op_sel_hi:[0,1,1]
	v_pk_fma_f32 v[126:127], v[60:61], v[78:79], v[134:135] op_sel:[1,0,0]
	v_pk_fma_f32 v[132:133], v[60:61], v[52:53], v[140:141] op_sel:[1,0,0]
	v_pk_fma_f32 v[134:135], v[60:61], v[116:117], v[142:143] op_sel:[1,0,0]
	v_pk_fma_f32 v[60:61], v[60:61], v[54:55], v[68:69] op_sel:[1,0,0]
	v_pk_fma_f32 v[68:69], v[62:63], v[78:79], v[76:77] op_sel_hi:[0,1,1]
	v_pk_fma_f32 v[76:77], v[62:63], v[52:53], v[84:85] op_sel_hi:[0,1,1]
	v_pk_fma_f32 v[84:85], v[62:63], v[116:117], v[92:93] op_sel_hi:[0,1,1]
	v_pk_fma_f32 v[92:93], v[62:63], v[54:55], v[100:101] op_sel_hi:[0,1,1]
	v_mov_b32_e32 v62, v63
	v_pk_fma_f32 v[78:79], v[62:63], v[78:79], v[86:87] op_sel_hi:[0,1,1]
	v_pk_fma_f32 v[86:87], v[62:63], v[52:53], v[94:95] op_sel_hi:[0,1,1]
	v_pk_fma_f32 v[94:95], v[62:63], v[116:117], v[102:103] op_sel_hi:[0,1,1]
	v_pk_fma_f32 v[62:63], v[62:63], v[54:55], v[70:71] op_sel_hi:[0,1,1]
	ds_read_b128 v[52:55], v209 offset:3584
	s_waitcnt vmcnt(4)
	v_lshlrev_b32_e32 v70, 16, v28
	v_and_b32_e32 v71, 0xffff0000, v28
	v_lshlrev_b32_e32 v28, 16, v29
	v_and_b32_e32 v29, 0xffff0000, v29
	s_waitcnt lgkmcnt(0)
	v_pk_fma_f32 v[100:101], v[52:53], v[70:71], v[108:109] op_sel_hi:[0,1,1]
	v_lshlrev_b32_e32 v108, 16, v30
	v_and_b32_e32 v109, 0xffff0000, v30
	v_lshlrev_b32_e32 v30, 16, v31
	v_and_b32_e32 v31, 0xffff0000, v31
	v_pk_fma_f32 v[102:103], v[52:53], v[28:29], v[110:111] op_sel_hi:[0,1,1]
	v_pk_fma_f32 v[110:111], v[52:53], v[108:109], v[118:119] op_sel_hi:[0,1,1]
	v_pk_fma_f32 v[116:117], v[52:53], v[30:31], v[124:125] op_sel_hi:[0,1,1]
	v_pk_fma_f32 v[118:119], v[52:53], v[70:71], v[126:127] op_sel:[1,0,0]
	v_pk_fma_f32 v[124:125], v[52:53], v[28:29], v[132:133] op_sel:[1,0,0]
	v_pk_fma_f32 v[126:127], v[52:53], v[108:109], v[134:135] op_sel:[1,0,0]
	v_pk_fma_f32 v[52:53], v[52:53], v[30:31], v[60:61] op_sel:[1,0,0]
	v_pk_fma_f32 v[60:61], v[54:55], v[70:71], v[68:69] op_sel_hi:[0,1,1]
	v_pk_fma_f32 v[68:69], v[54:55], v[28:29], v[76:77] op_sel_hi:[0,1,1]
	v_pk_fma_f32 v[76:77], v[54:55], v[108:109], v[84:85] op_sel_hi:[0,1,1]
	v_pk_fma_f32 v[84:85], v[54:55], v[30:31], v[92:93] op_sel_hi:[0,1,1]
	v_mov_b32_e32 v54, v55
	v_pk_fma_f32 v[70:71], v[54:55], v[70:71], v[78:79] op_sel_hi:[0,1,1]
	v_pk_fma_f32 v[78:79], v[54:55], v[28:29], v[86:87] op_sel_hi:[0,1,1]
	v_pk_fma_f32 v[86:87], v[54:55], v[108:109], v[94:95] op_sel_hi:[0,1,1]
	v_pk_fma_f32 v[54:55], v[54:55], v[30:31], v[62:63] op_sel_hi:[0,1,1]
	ds_read_b128 v[28:31], v209 offset:3712
	s_waitcnt vmcnt(3)
	v_lshlrev_b32_e32 v62, 16, v20
	v_and_b32_e32 v63, 0xffff0000, v20
	v_lshlrev_b32_e32 v20, 16, v21
	v_and_b32_e32 v21, 0xffff0000, v21
	s_waitcnt lgkmcnt(0)
	v_pk_fma_f32 v[92:93], v[28:29], v[62:63], v[100:101] op_sel_hi:[0,1,1]
	v_lshlrev_b32_e32 v100, 16, v22
	v_and_b32_e32 v101, 0xffff0000, v22
	v_lshlrev_b32_e32 v22, 16, v23
	v_and_b32_e32 v23, 0xffff0000, v23
	v_pk_fma_f32 v[94:95], v[28:29], v[20:21], v[102:103] op_sel_hi:[0,1,1]
	v_pk_fma_f32 v[102:103], v[28:29], v[100:101], v[110:111] op_sel_hi:[0,1,1]
	v_pk_fma_f32 v[108:109], v[28:29], v[22:23], v[116:117] op_sel_hi:[0,1,1]
	v_pk_fma_f32 v[110:111], v[28:29], v[62:63], v[118:119] op_sel:[1,0,0]
	v_pk_fma_f32 v[116:117], v[28:29], v[20:21], v[124:125] op_sel:[1,0,0]
	v_pk_fma_f32 v[118:119], v[28:29], v[100:101], v[126:127] op_sel:[1,0,0]
	v_pk_fma_f32 v[28:29], v[28:29], v[22:23], v[52:53] op_sel:[1,0,0]
	v_pk_fma_f32 v[52:53], v[30:31], v[62:63], v[60:61] op_sel_hi:[0,1,1]
	v_pk_fma_f32 v[60:61], v[30:31], v[20:21], v[68:69] op_sel_hi:[0,1,1]
	v_pk_fma_f32 v[68:69], v[30:31], v[100:101], v[76:77] op_sel_hi:[0,1,1]
	v_pk_fma_f32 v[76:77], v[30:31], v[22:23], v[84:85] op_sel_hi:[0,1,1]
	v_mov_b32_e32 v30, v31
	v_pk_fma_f32 v[62:63], v[30:31], v[62:63], v[70:71] op_sel_hi:[0,1,1]
	v_pk_fma_f32 v[70:71], v[30:31], v[20:21], v[78:79] op_sel_hi:[0,1,1]
	v_pk_fma_f32 v[78:79], v[30:31], v[100:101], v[86:87] op_sel_hi:[0,1,1]
	v_pk_fma_f32 v[30:31], v[30:31], v[22:23], v[54:55] op_sel_hi:[0,1,1]
	ds_read_b128 v[20:23], v209 offset:3840
	s_waitcnt vmcnt(2)
; DI float bf_lo(unsigned u) { return __uint_as_float(u << 16); }
; DI float bf_hi(unsigned u) { return __uint_as_float(u & 0xffff0000u); }
; DI void dsa_job(const Params& p, int b, int tq0, char* lds) {
;     ...
;   auto pv_load = [&](int grp, u32x4* dst) {
; #pragma unroll
;     for (int s = 0; s < 16; ++s) dst[s] = *(const u32x4*)(vb + (size_t)kid[4 * (grp * 16 + s) + ksub] * LDH);
;   };
;   auto pv_fma = [&](int grp, const u32x4* src) {
; #pragma unroll
;     for (int s = 0; s < 16; ++s) {
;       const int slot = 4 * (grp * 16 + s) + ksub;
;       const f32x4 pp = *(const f32x4*)(Pl + slot * 8 + g * 4);
;       const u32x4 vv = src[s];
; #pragma unroll
;       for (int hh = 0; hh < 4; ++hh) {
;         const f32x2 ph = {pp[hh], pp[hh]};
; #pragma unroll
;         for (int e = 0; e < 4; ++e) {
;           const f32x2 vf2 = {bf_lo(vv[e]), bf_hi(vv[e])};
;           acc2[hh][e] += ph * vf2;
;         }
;       }
;     }
;   };
;   pv_load(0, vA);
;   pv_load(1, vB);
;   pv_fma(0, vA);
;   pv_load(2, vA);
;   pv_fma(1, vB);
;   pv_load(3, vB);
;   pv_fma(2, vA);
	v_lshlrev_b32_e32 v54, 16, v12
	v_and_b32_e32 v55, 0xffff0000, v12
	v_lshlrev_b32_e32 v12, 16, v13
	v_and_b32_e32 v13, 0xffff0000, v13
	s_waitcnt lgkmcnt(0)
	v_pk_fma_f32 v[84:85], v[20:21], v[54:55], v[92:93] op_sel_hi:[0,1,1]
	v_lshlrev_b32_e32 v92, 16, v14
	v_and_b32_e32 v93, 0xffff0000, v14
	v_lshlrev_b32_e32 v14, 16, v15
	v_and_b32_e32 v15, 0xffff0000, v15
	v_pk_fma_f32 v[86:87], v[20:21], v[12:13], v[94:95] op_sel_hi:[0,1,1]
	v_pk_fma_f32 v[94:95], v[20:21], v[92:93], v[102:103] op_sel_hi:[0,1,1]
	v_pk_fma_f32 v[100:101], v[20:21], v[14:15], v[108:109] op_sel_hi:[0,1,1]
	v_pk_fma_f32 v[102:103], v[20:21], v[54:55], v[110:111] op_sel:[1,0,0]
	v_pk_fma_f32 v[108:109], v[20:21], v[12:13], v[116:117] op_sel:[1,0,0]
	v_pk_fma_f32 v[110:111], v[20:21], v[92:93], v[118:119] op_sel:[1,0,0]
	v_pk_fma_f32 v[20:21], v[20:21], v[14:15], v[28:29] op_sel:[1,0,0]
	v_pk_fma_f32 v[28:29], v[22:23], v[54:55], v[52:53] op_sel_hi:[0,1,1]
	v_pk_fma_f32 v[52:53], v[22:23], v[12:13], v[60:61] op_sel_hi:[0,1,1]
	v_pk_fma_f32 v[60:61], v[22:23], v[92:93], v[68:69] op_sel_hi:[0,1,1]
	v_pk_fma_f32 v[68:69], v[22:23], v[14:15], v[76:77] op_sel_hi:[0,1,1]
	v_mov_b32_e32 v22, v23
	v_pk_fma_f32 v[54:55], v[22:23], v[54:55], v[62:63] op_sel_hi:[0,1,1]
	v_pk_fma_f32 v[62:63], v[22:23], v[12:13], v[70:71] op_sel_hi:[0,1,1]
	v_pk_fma_f32 v[70:71], v[22:23], v[92:93], v[78:79] op_sel_hi:[0,1,1]
	v_pk_fma_f32 v[22:23], v[22:23], v[14:15], v[30:31] op_sel_hi:[0,1,1]
	ds_read_b128 v[12:15], v209 offset:3968
	v_mad_i64_i32 v[8:9], s[0:1], v9, s53, v[148:149]
	global_load_dwordx4 v[136:139], v[8:9], off
	s_waitcnt vmcnt(1)
	v_lshlrev_b32_e32 v30, 16, v4
	v_and_b32_e32 v31, 0xffff0000, v4
	v_lshlrev_b32_e32 v4, 16, v5
	v_and_b32_e32 v5, 0xffff0000, v5
	v_lshlrev_b32_e32 v76, 16, v6
	v_and_b32_e32 v77, 0xffff0000, v6
	v_lshlrev_b32_e32 v6, 16, v7
	v_and_b32_e32 v7, 0xffff0000, v7
	s_waitcnt lgkmcnt(0)
	v_pk_fma_f32 v[150:151], v[12:13], v[30:31], v[84:85] op_sel_hi:[0,1,1]
	v_pk_fma_f32 v[158:159], v[12:13], v[4:5], v[86:87] op_sel_hi:[0,1,1]
	v_pk_fma_f32 v[160:161], v[12:13], v[76:77], v[94:95] op_sel_hi:[0,1,1]
	v_pk_fma_f32 v[162:163], v[12:13], v[6:7], v[100:101] op_sel_hi:[0,1,1]
	v_pk_fma_f32 v[164:165], v[12:13], v[30:31], v[102:103] op_sel:[1,0,0]
	v_pk_fma_f32 v[166:167], v[12:13], v[4:5], v[108:109] op_sel:[1,0,0]
	v_pk_fma_f32 v[168:169], v[12:13], v[76:77], v[110:111] op_sel:[1,0,0]
	v_pk_fma_f32 v[170:171], v[12:13], v[6:7], v[20:21] op_sel:[1,0,0]
	v_mov_b32_e32 v12, v15
	v_pk_fma_f32 v[174:175], v[14:15], v[4:5], v[52:53] op_sel_hi:[0,1,1]
	v_pk_fma_f32 v[182:183], v[12:13], v[4:5], v[62:63] op_sel_hi:[0,1,1]
	ds_read2_b32 v[4:5], v210 offset0:192 offset1:196
	v_pk_fma_f32 v[178:179], v[14:15], v[6:7], v[68:69] op_sel_hi:[0,1,1]
	v_pk_fma_f32 v[186:187], v[12:13], v[6:7], v[22:23] op_sel_hi:[0,1,1]
	v_pk_fma_f32 v[176:177], v[14:15], v[76:77], v[60:61] op_sel_hi:[0,1,1]
	v_pk_fma_f32 v[184:185], v[12:13], v[76:77], v[70:71] op_sel_hi:[0,1,1]
	s_waitcnt lgkmcnt(0)
	v_mad_i64_i32 v[6:7], s[0:1], v4, s53, v[148:149]
	v_mad_i64_i32 v[4:5], s[0:1], v5, s53, v[148:149]
	global_load_dwordx4 v[140:143], v[6:7], off
	global_load_dwordx4 v[132:135], v[4:5], off
	ds_read2_b32 v[4:5], v210 offset0:200 offset1:204
	ds_read2_b32 v[8:9], v210 offset0:136 offset1:140
	v_pk_fma_f32 v[180:181], v[12:13], v[30:31], v[54:55] op_sel_hi:[0,1,1]
	v_pk_fma_f32 v[172:173], v[14:15], v[30:31], v[28:29] op_sel_hi:[0,1,1]
	v_lshlrev_b32_e32 v214, 16, v146
	s_waitcnt lgkmcnt(1)
	v_mad_i64_i32 v[6:7], s[0:1], v4, s53, v[148:149]
	v_mad_i64_i32 v[4:5], s[0:1], v5, s53, v[148:149]
	global_load_dwordx4 v[124:127], v[6:7], off
	global_load_dwordx4 v[116:119], v[4:5], off
	ds_read2_b32 v[4:5], v210 offset0:208 offset1:212
	s_waitcnt lgkmcnt(1)
	v_mad_i64_i32 v[10:11], s[0:1], v8, s53, v[148:149]
	global_load_dwordx4 v[128:131], v[10:11], off
	v_mad_i64_i32 v[8:9], s[0:1], v9, s53, v[148:149]
	s_waitcnt lgkmcnt(0)
	v_mad_i64_i32 v[6:7], s[0:1], v4, s53, v[148:149]
	v_mad_i64_i32 v[4:5], s[0:1], v5, s53, v[148:149]
	global_load_dwordx4 v[108:111], v[6:7], off
	global_load_dwordx4 v[100:103], v[4:5], off
	ds_read2_b32 v[4:5], v210 offset0:216 offset1:220
	global_load_dwordx4 v[120:123], v[8:9], off
	v_and_b32_e32 v215, 0xffff0000, v146
	v_lshlrev_b32_e32 v146, 16, v147
	v_and_b32_e32 v147, 0xffff0000, v147
	s_waitcnt lgkmcnt(0)
	v_mad_i64_i32 v[6:7], s[0:1], v4, s53, v[148:149]
	v_mad_i64_i32 v[4:5], s[0:1], v5, s53, v[148:149]
	global_load_dwordx4 v[92:95], v[6:7], off
	global_load_dwordx4 v[84:87], v[4:5], off
	ds_read2_b32 v[4:5], v210 offset0:224 offset1:228
	s_waitcnt lgkmcnt(0)
	v_mad_i64_i32 v[6:7], s[0:1], v4, s53, v[148:149]
	v_mad_i64_i32 v[4:5], s[0:1], v5, s53, v[148:149]
	global_load_dwordx4 v[76:79], v[6:7], off
	global_load_dwordx4 v[68:71], v[4:5], off
	ds_read2_b32 v[4:5], v210 offset0:232 offset1:236
	s_waitcnt lgkmcnt(0)
	v_mad_i64_i32 v[6:7], s[0:1], v4, s53, v[148:149]
	v_mad_i64_i32 v[4:5], s[0:1], v5, s53, v[148:149]
	global_load_dwordx4 v[60:63], v[6:7], off
	global_load_dwordx4 v[52:55], v[4:5], off
	ds_read2_b32 v[4:5], v210 offset0:240 offset1:244
	s_waitcnt lgkmcnt(0)
	v_mad_i64_i32 v[6:7], s[0:1], v4, s53, v[148:149]
	v_mad_i64_i32 v[4:5], s[0:1], v5, s53, v[148:149]
	global_load_dwordx4 v[28:31], v[6:7], off
	global_load_dwordx4 v[20:23], v[4:5], off
	ds_read2_b32 v[4:5], v210 offset0:248 offset1:252
	s_waitcnt lgkmcnt(0)
	v_mad_i64_i32 v[6:7], s[0:1], v4, s53, v[148:149]
	v_mad_i64_i32 v[4:5], s[0:1], v5, s53, v[148:149]
	global_load_dwordx4 v[12:15], v[6:7], off
	s_nop 0
	global_load_dwordx4 v[4:7], v[4:5], off
	ds_read2_b32 v[8:9], v210 offset0:144 offset1:148
	s_waitcnt lgkmcnt(0)
; DI float bf_lo(unsigned u) { return __uint_as_float(u << 16); }
; DI float bf_hi(unsigned u) { return __uint_as_float(u & 0xffff0000u); }
; DI void dsa_job(const Params& p, int b, int tq0, char* lds) {
;     ...
;   auto pv_load = [&](int grp, u32x4* dst) {
; #pragma unroll
;     for (int s = 0; s < 16; ++s) dst[s] = *(const u32x4*)(vb + (size_t)kid[4 * (grp * 16 + s) + ksub] * LDH);
;   };
;   auto pv_fma = [&](int grp, const u32x4* src) {
; #pragma unroll
;     for (int s = 0; s < 16; ++s) {
;       const int slot = 4 * (grp * 16 + s) + ksub;
;       const f32x4 pp = *(const f32x4*)(Pl + slot * 8 + g * 4);
;       const u32x4 vv = src[s];
; #pragma unroll
;       for (int hh = 0; hh < 4; ++hh) {
;         const f32x2 ph = {pp[hh], pp[hh]};
; #pragma unroll
;         for (int e = 0; e < 4; ++e) {
;           const f32x2 vf2 = {bf_lo(vv[e]), bf_hi(vv[e])};
;           acc2[hh][e] += ph * vf2;
;         }
;       }
;     }
;   };
;   pv_load(0, vA);
;   pv_load(1, vB);
;   pv_fma(0, vA);
;   pv_load(2, vA);
;   pv_fma(1, vB);
;   pv_load(3, vB);
;   pv_fma(2, vA);
	v_mad_i64_i32 v[10:11], s[0:1], v8, s53, v[148:149]
	global_load_dwordx4 v[112:115], v[10:11], off
	v_mad_i64_i32 v[8:9], s[0:1], v9, s53, v[148:149]
	global_load_dwordx4 v[104:107], v[8:9], off
	ds_read2_b32 v[8:9], v210 offset0:152 offset1:156
	s_waitcnt lgkmcnt(0)
	v_mad_i64_i32 v[10:11], s[0:1], v8, s53, v[148:149]
	global_load_dwordx4 v[96:99], v[10:11], off
	v_mad_i64_i32 v[8:9], s[0:1], v9, s53, v[148:149]
	global_load_dwordx4 v[88:91], v[8:9], off
	ds_read2_b32 v[8:9], v210 offset0:160 offset1:164
	s_waitcnt lgkmcnt(0)
	v_mad_i64_i32 v[10:11], s[0:1], v8, s53, v[148:149]
	global_load_dwordx4 v[80:83], v[10:11], off
	v_mad_i64_i32 v[8:9], s[0:1], v9, s53, v[148:149]
	global_load_dwordx4 v[72:75], v[8:9], off
	ds_read2_b32 v[8:9], v210 offset0:168 offset1:172
	s_waitcnt lgkmcnt(0)
	v_mad_i64_i32 v[10:11], s[0:1], v8, s53, v[148:149]
	global_load_dwordx4 v[64:67], v[10:11], off
	v_mad_i64_i32 v[8:9], s[0:1], v9, s53, v[148:149]
	global_load_dwordx4 v[56:59], v[8:9], off
	ds_read2_b32 v[8:9], v210 offset0:176 offset1:180
	s_waitcnt lgkmcnt(0)
	v_mad_i64_i32 v[10:11], s[0:1], v8, s53, v[148:149]
	v_mad_i64_i32 v[8:9], s[0:1], v9, s53, v[148:149]
	global_load_dwordx4 v[32:35], v[10:11], off
	global_load_dwordx4 v[24:27], v[8:9], off
	ds_read2_b32 v[8:9], v210 offset0:184 offset1:188
	ds_read_b128 v[210:213], v209 offset:4096
	s_waitcnt lgkmcnt(1)
	v_mad_i64_i32 v[10:11], s[0:1], v8, s53, v[148:149]
	v_mad_i64_i32 v[8:9], s[0:1], v9, s53, v[148:149]
	v_lshlrev_b32_e32 v148, 16, v144
	v_and_b32_e32 v149, 0xffff0000, v144
	v_lshlrev_b32_e32 v144, 16, v145
	v_and_b32_e32 v145, 0xffff0000, v145
	s_waitcnt lgkmcnt(0)
	v_pk_fma_f32 v[150:151], v[210:211], v[148:149], v[150:151] op_sel_hi:[0,1,1]
	v_pk_fma_f32 v[158:159], v[210:211], v[144:145], v[158:159] op_sel_hi:[0,1,1]
	v_pk_fma_f32 v[160:161], v[210:211], v[214:215], v[160:161] op_sel_hi:[0,1,1]
	v_pk_fma_f32 v[162:163], v[210:211], v[146:147], v[162:163] op_sel_hi:[0,1,1]
	v_pk_fma_f32 v[164:165], v[210:211], v[148:149], v[164:165] op_sel:[1,0,0]
	v_pk_fma_f32 v[166:167], v[210:211], v[144:145], v[166:167] op_sel:[1,0,0]
	v_pk_fma_f32 v[168:169], v[210:211], v[214:215], v[168:169] op_sel:[1,0,0]
	v_pk_fma_f32 v[170:171], v[210:211], v[146:147], v[170:171] op_sel:[1,0,0]
	v_mov_b32_e32 v210, v213
	v_pk_fma_f32 v[172:173], v[212:213], v[148:149], v[172:173] op_sel_hi:[0,1,1]
	v_pk_fma_f32 v[174:175], v[212:213], v[144:145], v[174:175] op_sel_hi:[0,1,1]
	v_pk_fma_f32 v[178:179], v[212:213], v[146:147], v[178:179] op_sel_hi:[0,1,1]
	v_pk_fma_f32 v[148:149], v[210:211], v[148:149], v[180:181] op_sel_hi:[0,1,1]
	v_pk_fma_f32 v[180:181], v[210:211], v[144:145], v[182:183] op_sel_hi:[0,1,1]
	v_pk_fma_f32 v[182:183], v[210:211], v[214:215], v[184:185] op_sel_hi:[0,1,1]
	v_pk_fma_f32 v[184:185], v[210:211], v[146:147], v[186:187] op_sel_hi:[0,1,1]
	ds_read_b128 v[144:147], v209 offset:4224
	v_pk_fma_f32 v[176:177], v[212:213], v[214:215], v[176:177] op_sel_hi:[0,1,1]
	s_waitcnt vmcnt(28)
	v_lshlrev_b32_e32 v186, 16, v136
	v_and_b32_e32 v187, 0xffff0000, v136
	v_lshlrev_b32_e32 v136, 16, v137
	v_and_b32_e32 v137, 0xffff0000, v137
	v_lshlrev_b32_e32 v210, 16, v138
	v_and_b32_e32 v211, 0xffff0000, v138
	v_lshlrev_b32_e32 v138, 16, v139
	v_and_b32_e32 v139, 0xffff0000, v139
	s_waitcnt lgkmcnt(0)
	v_pk_fma_f32 v[150:151], v[144:145], v[186:187], v[150:151] op_sel_hi:[0,1,1]
	v_pk_fma_f32 v[158:159], v[144:145], v[136:137], v[158:159] op_sel_hi:[0,1,1]
	v_pk_fma_f32 v[160:161], v[144:145], v[210:211], v[160:161] op_sel_hi:[0,1,1]
	v_pk_fma_f32 v[162:163], v[144:145], v[138:139], v[162:163] op_sel_hi:[0,1,1]
	v_pk_fma_f32 v[164:165], v[144:145], v[186:187], v[164:165] op_sel:[1,0,0]
	v_pk_fma_f32 v[166:167], v[144:145], v[136:137], v[166:167] op_sel:[1,0,0]
	v_pk_fma_f32 v[168:169], v[144:145], v[210:211], v[168:169] op_sel:[1,0,0]
	v_pk_fma_f32 v[144:145], v[144:145], v[138:139], v[170:171] op_sel:[1,0,0]
	v_pk_fma_f32 v[170:171], v[146:147], v[186:187], v[172:173] op_sel_hi:[0,1,1]
	v_pk_fma_f32 v[172:173], v[146:147], v[136:137], v[174:175] op_sel_hi:[0,1,1]
	v_pk_fma_f32 v[174:175], v[146:147], v[210:211], v[176:177] op_sel_hi:[0,1,1]
	v_pk_fma_f32 v[176:177], v[146:147], v[138:139], v[178:179] op_sel_hi:[0,1,1]
	v_mov_b32_e32 v146, v147
	v_pk_fma_f32 v[148:149], v[146:147], v[186:187], v[148:149] op_sel_hi:[0,1,1]
	v_pk_fma_f32 v[178:179], v[146:147], v[136:137], v[180:181] op_sel_hi:[0,1,1]
	v_pk_fma_f32 v[180:181], v[146:147], v[210:211], v[182:183] op_sel_hi:[0,1,1]
	v_pk_fma_f32 v[146:147], v[146:147], v[138:139], v[184:185] op_sel_hi:[0,1,1]
	ds_read_b128 v[136:139], v209 offset:4352
	global_load_dwordx4 v[16:19], v[10:11], off
	s_waitcnt vmcnt(24)
	v_lshlrev_b32_e32 v182, 16, v128
	v_and_b32_e32 v183, 0xffff0000, v128
	v_lshlrev_b32_e32 v128, 16, v129
	v_and_b32_e32 v129, 0xffff0000, v129
	v_lshlrev_b32_e32 v184, 16, v130
	v_and_b32_e32 v185, 0xffff0000, v130
	v_lshlrev_b32_e32 v130, 16, v131
	v_and_b32_e32 v131, 0xffff0000, v131
	s_waitcnt lgkmcnt(0)
; DI float bf_lo(unsigned u) { return __uint_as_float(u << 16); }
; DI float bf_hi(unsigned u) { return __uint_as_float(u & 0xffff0000u); }
; DI void dsa_job(const Params& p, int b, int tq0, char* lds) {
;     ...
;   auto pv_load = [&](int grp, u32x4* dst) {
; #pragma unroll
;     for (int s = 0; s < 16; ++s) dst[s] = *(const u32x4*)(vb + (size_t)kid[4 * (grp * 16 + s) + ksub] * LDH);
;   };
;   auto pv_fma = [&](int grp, const u32x4* src) {
; #pragma unroll
;     for (int s = 0; s < 16; ++s) {
;       const int slot = 4 * (grp * 16 + s) + ksub;
;       const f32x4 pp = *(const f32x4*)(Pl + slot * 8 + g * 4);
;       const u32x4 vv = src[s];
; #pragma unroll
;       for (int hh = 0; hh < 4; ++hh) {
;         const f32x2 ph = {pp[hh], pp[hh]};
; #pragma unroll
;         for (int e = 0; e < 4; ++e) {
;           const f32x2 vf2 = {bf_lo(vv[e]), bf_hi(vv[e])};
;           acc2[hh][e] += ph * vf2;
;         }
;       }
;     }
;   };
;   pv_load(0, vA);
;   pv_load(1, vB);
;   pv_fma(0, vA);
;   pv_load(2, vA);
;   pv_fma(1, vB);
;   pv_load(3, vB);
;   pv_fma(2, vA);
	v_pk_fma_f32 v[150:151], v[136:137], v[182:183], v[150:151] op_sel_hi:[0,1,1]
	v_pk_fma_f32 v[158:159], v[136:137], v[128:129], v[158:159] op_sel_hi:[0,1,1]
	v_pk_fma_f32 v[160:161], v[136:137], v[184:185], v[160:161] op_sel_hi:[0,1,1]
	v_pk_fma_f32 v[162:163], v[136:137], v[130:131], v[162:163] op_sel_hi:[0,1,1]
	v_pk_fma_f32 v[164:165], v[136:137], v[182:183], v[164:165] op_sel:[1,0,0]
	v_pk_fma_f32 v[166:167], v[136:137], v[128:129], v[166:167] op_sel:[1,0,0]
	v_pk_fma_f32 v[168:169], v[136:137], v[184:185], v[168:169] op_sel:[1,0,0]
	v_pk_fma_f32 v[136:137], v[136:137], v[130:131], v[144:145] op_sel:[1,0,0]
	v_pk_fma_f32 v[144:145], v[138:139], v[182:183], v[170:171] op_sel_hi:[0,1,1]
	v_pk_fma_f32 v[170:171], v[138:139], v[128:129], v[172:173] op_sel_hi:[0,1,1]
	v_pk_fma_f32 v[172:173], v[138:139], v[184:185], v[174:175] op_sel_hi:[0,1,1]
	v_pk_fma_f32 v[174:175], v[138:139], v[130:131], v[176:177] op_sel_hi:[0,1,1]
	v_mov_b32_e32 v138, v139
	v_pk_fma_f32 v[148:149], v[138:139], v[182:183], v[148:149] op_sel_hi:[0,1,1]
	v_pk_fma_f32 v[176:177], v[138:139], v[128:129], v[178:179] op_sel_hi:[0,1,1]
	v_pk_fma_f32 v[178:179], v[138:139], v[184:185], v[180:181] op_sel_hi:[0,1,1]
	v_pk_fma_f32 v[138:139], v[138:139], v[130:131], v[146:147] op_sel_hi:[0,1,1]
	ds_read_b128 v[128:131], v209 offset:4480
	s_waitcnt vmcnt(21)
	v_lshlrev_b32_e32 v146, 16, v120
	v_and_b32_e32 v147, 0xffff0000, v120
	v_lshlrev_b32_e32 v120, 16, v121
	v_and_b32_e32 v121, 0xffff0000, v121
	v_lshlrev_b32_e32 v180, 16, v122
	v_and_b32_e32 v181, 0xffff0000, v122
	v_lshlrev_b32_e32 v122, 16, v123
	v_and_b32_e32 v123, 0xffff0000, v123
	global_load_dwordx4 v[8:11], v[8:9], off
	s_waitcnt lgkmcnt(0)
	v_pk_fma_f32 v[150:151], v[128:129], v[146:147], v[150:151] op_sel_hi:[0,1,1]
	v_pk_fma_f32 v[158:159], v[128:129], v[120:121], v[158:159] op_sel_hi:[0,1,1]
	v_pk_fma_f32 v[160:161], v[128:129], v[180:181], v[160:161] op_sel_hi:[0,1,1]
	v_pk_fma_f32 v[162:163], v[128:129], v[122:123], v[162:163] op_sel_hi:[0,1,1]
	v_pk_fma_f32 v[164:165], v[128:129], v[146:147], v[164:165] op_sel:[1,0,0]
	v_pk_fma_f32 v[166:167], v[128:129], v[120:121], v[166:167] op_sel:[1,0,0]
	v_pk_fma_f32 v[168:169], v[128:129], v[180:181], v[168:169] op_sel:[1,0,0]
	v_pk_fma_f32 v[128:129], v[128:129], v[122:123], v[136:137] op_sel:[1,0,0]
	v_pk_fma_f32 v[136:137], v[130:131], v[146:147], v[144:145] op_sel_hi:[0,1,1]
	v_pk_fma_f32 v[144:145], v[130:131], v[120:121], v[170:171] op_sel_hi:[0,1,1]
	v_pk_fma_f32 v[170:171], v[130:131], v[180:181], v[172:173] op_sel_hi:[0,1,1]
	v_pk_fma_f32 v[172:173], v[130:131], v[122:123], v[174:175] op_sel_hi:[0,1,1]
	v_mov_b32_e32 v130, v131
	v_pk_fma_f32 v[146:147], v[130:131], v[146:147], v[148:149] op_sel_hi:[0,1,1]
	v_pk_fma_f32 v[148:149], v[130:131], v[120:121], v[176:177] op_sel_hi:[0,1,1]
	v_pk_fma_f32 v[174:175], v[130:131], v[180:181], v[178:179] op_sel_hi:[0,1,1]
	v_pk_fma_f32 v[130:131], v[130:131], v[122:123], v[138:139] op_sel_hi:[0,1,1]
	ds_read_b128 v[120:123], v209 offset:4608
	s_waitcnt vmcnt(11)
	v_lshlrev_b32_e32 v138, 16, v112
	v_and_b32_e32 v139, 0xffff0000, v112
	v_lshlrev_b32_e32 v112, 16, v113
	v_and_b32_e32 v113, 0xffff0000, v113
	v_lshlrev_b32_e32 v176, 16, v114
	v_and_b32_e32 v177, 0xffff0000, v114
	v_lshlrev_b32_e32 v114, 16, v115
	v_and_b32_e32 v115, 0xffff0000, v115
	s_waitcnt lgkmcnt(0)
	v_pk_fma_f32 v[150:151], v[120:121], v[138:139], v[150:151] op_sel_hi:[0,1,1]
	v_pk_fma_f32 v[158:159], v[120:121], v[112:113], v[158:159] op_sel_hi:[0,1,1]
	v_pk_fma_f32 v[160:161], v[120:121], v[176:177], v[160:161] op_sel_hi:[0,1,1]
	v_pk_fma_f32 v[162:163], v[120:121], v[114:115], v[162:163] op_sel_hi:[0,1,1]
	v_pk_fma_f32 v[164:165], v[120:121], v[138:139], v[164:165] op_sel:[1,0,0]
	v_pk_fma_f32 v[166:167], v[120:121], v[112:113], v[166:167] op_sel:[1,0,0]
	v_pk_fma_f32 v[168:169], v[120:121], v[176:177], v[168:169] op_sel:[1,0,0]
	v_pk_fma_f32 v[120:121], v[120:121], v[114:115], v[128:129] op_sel:[1,0,0]
	v_pk_fma_f32 v[128:129], v[122:123], v[138:139], v[136:137] op_sel_hi:[0,1,1]
	v_pk_fma_f32 v[136:137], v[122:123], v[112:113], v[144:145] op_sel_hi:[0,1,1]
	v_pk_fma_f32 v[144:145], v[122:123], v[176:177], v[170:171] op_sel_hi:[0,1,1]
	v_pk_fma_f32 v[170:171], v[122:123], v[114:115], v[172:173] op_sel_hi:[0,1,1]
	v_mov_b32_e32 v122, v123
	v_pk_fma_f32 v[138:139], v[122:123], v[138:139], v[146:147] op_sel_hi:[0,1,1]
	v_pk_fma_f32 v[146:147], v[122:123], v[112:113], v[148:149] op_sel_hi:[0,1,1]
	v_pk_fma_f32 v[148:149], v[122:123], v[176:177], v[174:175] op_sel_hi:[0,1,1]
	v_pk_fma_f32 v[122:123], v[122:123], v[114:115], v[130:131] op_sel_hi:[0,1,1]
	ds_read_b128 v[112:115], v209 offset:4736
	s_waitcnt vmcnt(10)
	v_lshlrev_b32_e32 v130, 16, v104
	v_and_b32_e32 v131, 0xffff0000, v104
	v_lshlrev_b32_e32 v104, 16, v105
	v_and_b32_e32 v105, 0xffff0000, v105
	v_lshlrev_b32_e32 v172, 16, v106
	v_and_b32_e32 v173, 0xffff0000, v106
	v_lshlrev_b32_e32 v106, 16, v107
	v_and_b32_e32 v107, 0xffff0000, v107
	s_waitcnt lgkmcnt(0)
; DI float bf_lo(unsigned u) { return __uint_as_float(u << 16); }
; DI float bf_hi(unsigned u) { return __uint_as_float(u & 0xffff0000u); }
; DI void dsa_job(const Params& p, int b, int tq0, char* lds) {
;     ...
;   auto pv_fma = [&](int grp, const u32x4* src) {
; #pragma unroll
;     for (int s = 0; s < 16; ++s) {
;       const int slot = 4 * (grp * 16 + s) + ksub;
;       const f32x4 pp = *(const f32x4*)(Pl + slot * 8 + g * 4);
;       const u32x4 vv = src[s];
; #pragma unroll
;       for (int hh = 0; hh < 4; ++hh) {
;         const f32x2 ph = {pp[hh], pp[hh]};
; #pragma unroll
;         for (int e = 0; e < 4; ++e) {
;           const f32x2 vf2 = {bf_lo(vv[e]), bf_hi(vv[e])};
;           acc2[hh][e] += ph * vf2;
;         }
;       }
;     }
;   };
;   pv_load(0, vA);
;   pv_load(1, vB);
;   pv_fma(0, vA);
;   pv_load(2, vA);
;   pv_fma(1, vB);
;   pv_load(3, vB);
;   pv_fma(2, vA);
;   pv_fma(3, vB);
	v_pk_fma_f32 v[150:151], v[112:113], v[130:131], v[150:151] op_sel_hi:[0,1,1]
	v_pk_fma_f32 v[158:159], v[112:113], v[104:105], v[158:159] op_sel_hi:[0,1,1]
	v_pk_fma_f32 v[160:161], v[112:113], v[172:173], v[160:161] op_sel_hi:[0,1,1]
	v_pk_fma_f32 v[162:163], v[112:113], v[106:107], v[162:163] op_sel_hi:[0,1,1]
	v_pk_fma_f32 v[164:165], v[112:113], v[130:131], v[164:165] op_sel:[1,0,0]
	v_pk_fma_f32 v[166:167], v[112:113], v[104:105], v[166:167] op_sel:[1,0,0]
	v_pk_fma_f32 v[168:169], v[112:113], v[172:173], v[168:169] op_sel:[1,0,0]
	v_pk_fma_f32 v[112:113], v[112:113], v[106:107], v[120:121] op_sel:[1,0,0]
	v_pk_fma_f32 v[120:121], v[114:115], v[130:131], v[128:129] op_sel_hi:[0,1,1]
	v_pk_fma_f32 v[128:129], v[114:115], v[104:105], v[136:137] op_sel_hi:[0,1,1]
	v_pk_fma_f32 v[136:137], v[114:115], v[172:173], v[144:145] op_sel_hi:[0,1,1]
	v_pk_fma_f32 v[144:145], v[114:115], v[106:107], v[170:171] op_sel_hi:[0,1,1]
	v_mov_b32_e32 v114, v115
	v_pk_fma_f32 v[130:131], v[114:115], v[130:131], v[138:139] op_sel_hi:[0,1,1]
	v_pk_fma_f32 v[138:139], v[114:115], v[104:105], v[146:147] op_sel_hi:[0,1,1]
	v_pk_fma_f32 v[146:147], v[114:115], v[172:173], v[148:149] op_sel_hi:[0,1,1]
	v_pk_fma_f32 v[114:115], v[114:115], v[106:107], v[122:123] op_sel_hi:[0,1,1]
	ds_read_b128 v[104:107], v209 offset:4864
	s_waitcnt vmcnt(9)
	v_lshlrev_b32_e32 v122, 16, v96
	v_and_b32_e32 v123, 0xffff0000, v96
	v_lshlrev_b32_e32 v96, 16, v97
	v_and_b32_e32 v97, 0xffff0000, v97
	s_waitcnt lgkmcnt(0)
	v_pk_fma_f32 v[148:149], v[104:105], v[122:123], v[150:151] op_sel_hi:[0,1,1]
	v_pk_fma_f32 v[150:151], v[104:105], v[96:97], v[158:159] op_sel_hi:[0,1,1]
	v_lshlrev_b32_e32 v158, 16, v98
	v_and_b32_e32 v159, 0xffff0000, v98
	v_lshlrev_b32_e32 v98, 16, v99
	v_and_b32_e32 v99, 0xffff0000, v99
	v_pk_fma_f32 v[160:161], v[104:105], v[158:159], v[160:161] op_sel_hi:[0,1,1]
	v_pk_fma_f32 v[162:163], v[104:105], v[98:99], v[162:163] op_sel_hi:[0,1,1]
	v_pk_fma_f32 v[164:165], v[104:105], v[122:123], v[164:165] op_sel:[1,0,0]
	v_pk_fma_f32 v[166:167], v[104:105], v[96:97], v[166:167] op_sel:[1,0,0]
	v_pk_fma_f32 v[168:169], v[104:105], v[158:159], v[168:169] op_sel:[1,0,0]
	v_pk_fma_f32 v[104:105], v[104:105], v[98:99], v[112:113] op_sel:[1,0,0]
	v_pk_fma_f32 v[112:113], v[106:107], v[122:123], v[120:121] op_sel_hi:[0,1,1]
	v_pk_fma_f32 v[120:121], v[106:107], v[96:97], v[128:129] op_sel_hi:[0,1,1]
	v_pk_fma_f32 v[128:129], v[106:107], v[158:159], v[136:137] op_sel_hi:[0,1,1]
	v_pk_fma_f32 v[136:137], v[106:107], v[98:99], v[144:145] op_sel_hi:[0,1,1]
	v_mov_b32_e32 v106, v107
	v_pk_fma_f32 v[122:123], v[106:107], v[122:123], v[130:131] op_sel_hi:[0,1,1]
	v_pk_fma_f32 v[130:131], v[106:107], v[96:97], v[138:139] op_sel_hi:[0,1,1]
	v_pk_fma_f32 v[138:139], v[106:107], v[158:159], v[146:147] op_sel_hi:[0,1,1]
	v_pk_fma_f32 v[106:107], v[106:107], v[98:99], v[114:115] op_sel_hi:[0,1,1]
	ds_read_b128 v[96:99], v209 offset:4992
	s_waitcnt vmcnt(8)
	v_lshlrev_b32_e32 v114, 16, v88
	v_and_b32_e32 v115, 0xffff0000, v88
	v_lshlrev_b32_e32 v88, 16, v89
	v_and_b32_e32 v89, 0xffff0000, v89
	s_waitcnt lgkmcnt(0)
	v_pk_fma_f32 v[144:145], v[96:97], v[114:115], v[148:149] op_sel_hi:[0,1,1]
	v_lshlrev_b32_e32 v148, 16, v90
	v_and_b32_e32 v149, 0xffff0000, v90
	v_lshlrev_b32_e32 v90, 16, v91
	v_and_b32_e32 v91, 0xffff0000, v91
	v_pk_fma_f32 v[146:147], v[96:97], v[88:89], v[150:151] op_sel_hi:[0,1,1]
	v_pk_fma_f32 v[150:151], v[96:97], v[148:149], v[160:161] op_sel_hi:[0,1,1]
	v_pk_fma_f32 v[158:159], v[96:97], v[90:91], v[162:163] op_sel_hi:[0,1,1]
	v_pk_fma_f32 v[160:161], v[96:97], v[114:115], v[164:165] op_sel:[1,0,0]
	v_pk_fma_f32 v[162:163], v[96:97], v[88:89], v[166:167] op_sel:[1,0,0]
	v_pk_fma_f32 v[164:165], v[96:97], v[148:149], v[168:169] op_sel:[1,0,0]
	v_pk_fma_f32 v[96:97], v[96:97], v[90:91], v[104:105] op_sel:[1,0,0]
	v_pk_fma_f32 v[104:105], v[98:99], v[114:115], v[112:113] op_sel_hi:[0,1,1]
	v_pk_fma_f32 v[112:113], v[98:99], v[88:89], v[120:121] op_sel_hi:[0,1,1]
	v_pk_fma_f32 v[120:121], v[98:99], v[148:149], v[128:129] op_sel_hi:[0,1,1]
	v_pk_fma_f32 v[128:129], v[98:99], v[90:91], v[136:137] op_sel_hi:[0,1,1]
	v_mov_b32_e32 v98, v99
	v_pk_fma_f32 v[114:115], v[98:99], v[114:115], v[122:123] op_sel_hi:[0,1,1]
	v_pk_fma_f32 v[122:123], v[98:99], v[88:89], v[130:131] op_sel_hi:[0,1,1]
	v_pk_fma_f32 v[130:131], v[98:99], v[148:149], v[138:139] op_sel_hi:[0,1,1]
	v_pk_fma_f32 v[98:99], v[98:99], v[90:91], v[106:107] op_sel_hi:[0,1,1]
	ds_read_b128 v[88:91], v209 offset:5120
	s_waitcnt vmcnt(7)
	v_lshlrev_b32_e32 v106, 16, v80
	v_and_b32_e32 v107, 0xffff0000, v80
	v_lshlrev_b32_e32 v80, 16, v81
	v_and_b32_e32 v81, 0xffff0000, v81
	s_waitcnt lgkmcnt(0)
	v_pk_fma_f32 v[136:137], v[88:89], v[106:107], v[144:145] op_sel_hi:[0,1,1]
	v_lshlrev_b32_e32 v144, 16, v82
	v_and_b32_e32 v145, 0xffff0000, v82
	v_lshlrev_b32_e32 v82, 16, v83
	v_and_b32_e32 v83, 0xffff0000, v83
	v_pk_fma_f32 v[138:139], v[88:89], v[80:81], v[146:147] op_sel_hi:[0,1,1]
	v_pk_fma_f32 v[146:147], v[88:89], v[144:145], v[150:151] op_sel_hi:[0,1,1]
	v_pk_fma_f32 v[148:149], v[88:89], v[82:83], v[158:159] op_sel_hi:[0,1,1]
	v_pk_fma_f32 v[150:151], v[88:89], v[106:107], v[160:161] op_sel:[1,0,0]
	v_pk_fma_f32 v[158:159], v[88:89], v[80:81], v[162:163] op_sel:[1,0,0]
	v_pk_fma_f32 v[160:161], v[88:89], v[144:145], v[164:165] op_sel:[1,0,0]
	v_pk_fma_f32 v[88:89], v[88:89], v[82:83], v[96:97] op_sel:[1,0,0]
	v_pk_fma_f32 v[96:97], v[90:91], v[106:107], v[104:105] op_sel_hi:[0,1,1]
	v_pk_fma_f32 v[104:105], v[90:91], v[80:81], v[112:113] op_sel_hi:[0,1,1]
	v_pk_fma_f32 v[112:113], v[90:91], v[144:145], v[120:121] op_sel_hi:[0,1,1]
	v_pk_fma_f32 v[120:121], v[90:91], v[82:83], v[128:129] op_sel_hi:[0,1,1]
	v_mov_b32_e32 v90, v91
	v_pk_fma_f32 v[106:107], v[90:91], v[106:107], v[114:115] op_sel_hi:[0,1,1]
	v_pk_fma_f32 v[114:115], v[90:91], v[80:81], v[122:123] op_sel_hi:[0,1,1]
	v_pk_fma_f32 v[122:123], v[90:91], v[144:145], v[130:131] op_sel_hi:[0,1,1]
	v_pk_fma_f32 v[90:91], v[90:91], v[82:83], v[98:99] op_sel_hi:[0,1,1]
	ds_read_b128 v[80:83], v209 offset:5248
	s_waitcnt vmcnt(6)
; DI float bf_lo(unsigned u) { return __uint_as_float(u << 16); }
; DI float bf_hi(unsigned u) { return __uint_as_float(u & 0xffff0000u); }
; DI void dsa_job(const Params& p, int b, int tq0, char* lds) {
;     ...
;   auto pv_fma = [&](int grp, const u32x4* src) {
; #pragma unroll
;     for (int s = 0; s < 16; ++s) {
;       const int slot = 4 * (grp * 16 + s) + ksub;
;       const f32x4 pp = *(const f32x4*)(Pl + slot * 8 + g * 4);
;       const u32x4 vv = src[s];
; #pragma unroll
;       for (int hh = 0; hh < 4; ++hh) {
;         const f32x2 ph = {pp[hh], pp[hh]};
; #pragma unroll
;         for (int e = 0; e < 4; ++e) {
;           const f32x2 vf2 = {bf_lo(vv[e]), bf_hi(vv[e])};
;           acc2[hh][e] += ph * vf2;
;         }
;       }
;     }
;   };
;   pv_load(0, vA);
;   pv_load(1, vB);
;   pv_fma(0, vA);
;   pv_load(2, vA);
;   pv_fma(1, vB);
;   pv_load(3, vB);
;   pv_fma(2, vA);
;   pv_fma(3, vB);
	v_lshlrev_b32_e32 v98, 16, v72
	v_and_b32_e32 v99, 0xffff0000, v72
	v_lshlrev_b32_e32 v72, 16, v73
	v_and_b32_e32 v73, 0xffff0000, v73
	s_waitcnt lgkmcnt(0)
	v_pk_fma_f32 v[128:129], v[80:81], v[98:99], v[136:137] op_sel_hi:[0,1,1]
	v_lshlrev_b32_e32 v136, 16, v74
	v_and_b32_e32 v137, 0xffff0000, v74
	v_lshlrev_b32_e32 v74, 16, v75
	v_and_b32_e32 v75, 0xffff0000, v75
	v_pk_fma_f32 v[130:131], v[80:81], v[72:73], v[138:139] op_sel_hi:[0,1,1]
	v_pk_fma_f32 v[138:139], v[80:81], v[136:137], v[146:147] op_sel_hi:[0,1,1]
	v_pk_fma_f32 v[144:145], v[80:81], v[74:75], v[148:149] op_sel_hi:[0,1,1]
	v_pk_fma_f32 v[146:147], v[80:81], v[98:99], v[150:151] op_sel:[1,0,0]
	v_pk_fma_f32 v[148:149], v[80:81], v[72:73], v[158:159] op_sel:[1,0,0]
	v_pk_fma_f32 v[150:151], v[80:81], v[136:137], v[160:161] op_sel:[1,0,0]
	v_pk_fma_f32 v[80:81], v[80:81], v[74:75], v[88:89] op_sel:[1,0,0]
	v_pk_fma_f32 v[88:89], v[82:83], v[98:99], v[96:97] op_sel_hi:[0,1,1]
	v_pk_fma_f32 v[96:97], v[82:83], v[72:73], v[104:105] op_sel_hi:[0,1,1]
	v_pk_fma_f32 v[104:105], v[82:83], v[136:137], v[112:113] op_sel_hi:[0,1,1]
	v_pk_fma_f32 v[112:113], v[82:83], v[74:75], v[120:121] op_sel_hi:[0,1,1]
	v_mov_b32_e32 v82, v83
	v_pk_fma_f32 v[98:99], v[82:83], v[98:99], v[106:107] op_sel_hi:[0,1,1]
	v_pk_fma_f32 v[106:107], v[82:83], v[72:73], v[114:115] op_sel_hi:[0,1,1]
	v_pk_fma_f32 v[114:115], v[82:83], v[136:137], v[122:123] op_sel_hi:[0,1,1]
	v_pk_fma_f32 v[82:83], v[82:83], v[74:75], v[90:91] op_sel_hi:[0,1,1]
	ds_read_b128 v[72:75], v209 offset:5376
	s_waitcnt vmcnt(5)
	v_lshlrev_b32_e32 v90, 16, v64
	v_and_b32_e32 v91, 0xffff0000, v64
	v_lshlrev_b32_e32 v64, 16, v65
	v_and_b32_e32 v65, 0xffff0000, v65
	s_waitcnt lgkmcnt(0)
	v_pk_fma_f32 v[120:121], v[72:73], v[90:91], v[128:129] op_sel_hi:[0,1,1]
	v_lshlrev_b32_e32 v128, 16, v66
	v_and_b32_e32 v129, 0xffff0000, v66
	v_lshlrev_b32_e32 v66, 16, v67
	v_and_b32_e32 v67, 0xffff0000, v67
	v_pk_fma_f32 v[122:123], v[72:73], v[64:65], v[130:131] op_sel_hi:[0,1,1]
	v_pk_fma_f32 v[130:131], v[72:73], v[128:129], v[138:139] op_sel_hi:[0,1,1]
	v_pk_fma_f32 v[136:137], v[72:73], v[66:67], v[144:145] op_sel_hi:[0,1,1]
	v_pk_fma_f32 v[138:139], v[72:73], v[90:91], v[146:147] op_sel:[1,0,0]
	v_pk_fma_f32 v[144:145], v[72:73], v[64:65], v[148:149] op_sel:[1,0,0]
	v_pk_fma_f32 v[146:147], v[72:73], v[128:129], v[150:151] op_sel:[1,0,0]
	v_pk_fma_f32 v[72:73], v[72:73], v[66:67], v[80:81] op_sel:[1,0,0]
	v_pk_fma_f32 v[80:81], v[74:75], v[90:91], v[88:89] op_sel_hi:[0,1,1]
	v_pk_fma_f32 v[88:89], v[74:75], v[64:65], v[96:97] op_sel_hi:[0,1,1]
	v_pk_fma_f32 v[96:97], v[74:75], v[128:129], v[104:105] op_sel_hi:[0,1,1]
	v_pk_fma_f32 v[104:105], v[74:75], v[66:67], v[112:113] op_sel_hi:[0,1,1]
	v_mov_b32_e32 v74, v75
	v_pk_fma_f32 v[90:91], v[74:75], v[90:91], v[98:99] op_sel_hi:[0,1,1]
	v_pk_fma_f32 v[98:99], v[74:75], v[64:65], v[106:107] op_sel_hi:[0,1,1]
	v_pk_fma_f32 v[106:107], v[74:75], v[128:129], v[114:115] op_sel_hi:[0,1,1]
	v_pk_fma_f32 v[74:75], v[74:75], v[66:67], v[82:83] op_sel_hi:[0,1,1]
	ds_read_b128 v[64:67], v209 offset:5504
	s_waitcnt vmcnt(4)
	v_lshlrev_b32_e32 v82, 16, v56
	v_and_b32_e32 v83, 0xffff0000, v56
	v_lshlrev_b32_e32 v56, 16, v57
	v_and_b32_e32 v57, 0xffff0000, v57
	s_waitcnt lgkmcnt(0)
	v_pk_fma_f32 v[112:113], v[64:65], v[82:83], v[120:121] op_sel_hi:[0,1,1]
	v_lshlrev_b32_e32 v120, 16, v58
	v_and_b32_e32 v121, 0xffff0000, v58
	v_lshlrev_b32_e32 v58, 16, v59
	v_and_b32_e32 v59, 0xffff0000, v59
	v_pk_fma_f32 v[114:115], v[64:65], v[56:57], v[122:123] op_sel_hi:[0,1,1]
	v_pk_fma_f32 v[122:123], v[64:65], v[120:121], v[130:131] op_sel_hi:[0,1,1]
	v_pk_fma_f32 v[128:129], v[64:65], v[58:59], v[136:137] op_sel_hi:[0,1,1]
	v_pk_fma_f32 v[130:131], v[64:65], v[82:83], v[138:139] op_sel:[1,0,0]
	v_pk_fma_f32 v[136:137], v[64:65], v[56:57], v[144:145] op_sel:[1,0,0]
	v_pk_fma_f32 v[138:139], v[64:65], v[120:121], v[146:147] op_sel:[1,0,0]
	v_pk_fma_f32 v[64:65], v[64:65], v[58:59], v[72:73] op_sel:[1,0,0]
	v_pk_fma_f32 v[72:73], v[66:67], v[82:83], v[80:81] op_sel_hi:[0,1,1]
	v_pk_fma_f32 v[80:81], v[66:67], v[56:57], v[88:89] op_sel_hi:[0,1,1]
	v_pk_fma_f32 v[88:89], v[66:67], v[120:121], v[96:97] op_sel_hi:[0,1,1]
	v_pk_fma_f32 v[96:97], v[66:67], v[58:59], v[104:105] op_sel_hi:[0,1,1]
	v_mov_b32_e32 v66, v67
	v_pk_fma_f32 v[82:83], v[66:67], v[82:83], v[90:91] op_sel_hi:[0,1,1]
	v_pk_fma_f32 v[90:91], v[66:67], v[56:57], v[98:99] op_sel_hi:[0,1,1]
	v_pk_fma_f32 v[98:99], v[66:67], v[120:121], v[106:107] op_sel_hi:[0,1,1]
	v_pk_fma_f32 v[66:67], v[66:67], v[58:59], v[74:75] op_sel_hi:[0,1,1]
	ds_read_b128 v[56:59], v209 offset:5632
	s_waitcnt vmcnt(3)
	v_lshlrev_b32_e32 v74, 16, v32
	v_and_b32_e32 v75, 0xffff0000, v32
	v_lshlrev_b32_e32 v32, 16, v33
	v_and_b32_e32 v33, 0xffff0000, v33
	s_waitcnt lgkmcnt(0)
	v_pk_fma_f32 v[104:105], v[56:57], v[74:75], v[112:113] op_sel_hi:[0,1,1]
	v_lshlrev_b32_e32 v112, 16, v34
	v_and_b32_e32 v113, 0xffff0000, v34
	v_lshlrev_b32_e32 v34, 16, v35
	v_and_b32_e32 v35, 0xffff0000, v35
	v_pk_fma_f32 v[106:107], v[56:57], v[32:33], v[114:115] op_sel_hi:[0,1,1]
	v_pk_fma_f32 v[114:115], v[56:57], v[112:113], v[122:123] op_sel_hi:[0,1,1]
	v_pk_fma_f32 v[120:121], v[56:57], v[34:35], v[128:129] op_sel_hi:[0,1,1]
	v_pk_fma_f32 v[122:123], v[56:57], v[74:75], v[130:131] op_sel:[1,0,0]
	v_pk_fma_f32 v[128:129], v[56:57], v[32:33], v[136:137] op_sel:[1,0,0]
	v_pk_fma_f32 v[130:131], v[56:57], v[112:113], v[138:139] op_sel:[1,0,0]
	v_pk_fma_f32 v[56:57], v[56:57], v[34:35], v[64:65] op_sel:[1,0,0]
	v_pk_fma_f32 v[64:65], v[58:59], v[74:75], v[72:73] op_sel_hi:[0,1,1]
	v_pk_fma_f32 v[72:73], v[58:59], v[32:33], v[80:81] op_sel_hi:[0,1,1]
	v_pk_fma_f32 v[80:81], v[58:59], v[112:113], v[88:89] op_sel_hi:[0,1,1]
	v_pk_fma_f32 v[88:89], v[58:59], v[34:35], v[96:97] op_sel_hi:[0,1,1]
	v_mov_b32_e32 v58, v59
	v_pk_fma_f32 v[74:75], v[58:59], v[74:75], v[82:83] op_sel_hi:[0,1,1]
	v_pk_fma_f32 v[82:83], v[58:59], v[32:33], v[90:91] op_sel_hi:[0,1,1]
	v_pk_fma_f32 v[90:91], v[58:59], v[112:113], v[98:99] op_sel_hi:[0,1,1]
	v_pk_fma_f32 v[58:59], v[58:59], v[34:35], v[66:67] op_sel_hi:[0,1,1]
	ds_read_b128 v[32:35], v209 offset:5760
	s_waitcnt vmcnt(2)
; DI float bf_lo(unsigned u) { return __uint_as_float(u << 16); }
; DI float bf_hi(unsigned u) { return __uint_as_float(u & 0xffff0000u); }
; DI void dsa_job(const Params& p, int b, int tq0, char* lds) {
;     ...
;   auto pv_fma = [&](int grp, const u32x4* src) {
; #pragma unroll
;     for (int s = 0; s < 16; ++s) {
;       const int slot = 4 * (grp * 16 + s) + ksub;
;       const f32x4 pp = *(const f32x4*)(Pl + slot * 8 + g * 4);
;       const u32x4 vv = src[s];
; #pragma unroll
;       for (int hh = 0; hh < 4; ++hh) {
;         const f32x2 ph = {pp[hh], pp[hh]};
; #pragma unroll
;         for (int e = 0; e < 4; ++e) {
;           const f32x2 vf2 = {bf_lo(vv[e]), bf_hi(vv[e])};
;           acc2[hh][e] += ph * vf2;
;         }
;       }
;     }
;   };
;   pv_load(0, vA);
;   pv_load(1, vB);
;   pv_fma(0, vA);
;   pv_load(2, vA);
;   pv_fma(1, vB);
;   pv_load(3, vB);
;   pv_fma(2, vA);
;   pv_fma(3, vB);
	v_lshlrev_b32_e32 v66, 16, v24
	v_and_b32_e32 v67, 0xffff0000, v24
	v_lshlrev_b32_e32 v24, 16, v25
	v_and_b32_e32 v25, 0xffff0000, v25
	s_waitcnt lgkmcnt(0)
	v_pk_fma_f32 v[96:97], v[32:33], v[66:67], v[104:105] op_sel_hi:[0,1,1]
	v_lshlrev_b32_e32 v104, 16, v26
	v_and_b32_e32 v105, 0xffff0000, v26
	v_lshlrev_b32_e32 v26, 16, v27
	v_and_b32_e32 v27, 0xffff0000, v27
	v_pk_fma_f32 v[98:99], v[32:33], v[24:25], v[106:107] op_sel_hi:[0,1,1]
	v_pk_fma_f32 v[106:107], v[32:33], v[104:105], v[114:115] op_sel_hi:[0,1,1]
	v_pk_fma_f32 v[112:113], v[32:33], v[26:27], v[120:121] op_sel_hi:[0,1,1]
	v_pk_fma_f32 v[114:115], v[32:33], v[66:67], v[122:123] op_sel:[1,0,0]
	v_pk_fma_f32 v[120:121], v[32:33], v[24:25], v[128:129] op_sel:[1,0,0]
	v_pk_fma_f32 v[122:123], v[32:33], v[104:105], v[130:131] op_sel:[1,0,0]
	v_pk_fma_f32 v[32:33], v[32:33], v[26:27], v[56:57] op_sel:[1,0,0]
	v_pk_fma_f32 v[56:57], v[34:35], v[66:67], v[64:65] op_sel_hi:[0,1,1]
	v_pk_fma_f32 v[64:65], v[34:35], v[24:25], v[72:73] op_sel_hi:[0,1,1]
	v_pk_fma_f32 v[72:73], v[34:35], v[104:105], v[80:81] op_sel_hi:[0,1,1]
	v_pk_fma_f32 v[80:81], v[34:35], v[26:27], v[88:89] op_sel_hi:[0,1,1]
	v_mov_b32_e32 v34, v35
	v_pk_fma_f32 v[66:67], v[34:35], v[66:67], v[74:75] op_sel_hi:[0,1,1]
	v_pk_fma_f32 v[74:75], v[34:35], v[24:25], v[82:83] op_sel_hi:[0,1,1]
	v_pk_fma_f32 v[82:83], v[34:35], v[104:105], v[90:91] op_sel_hi:[0,1,1]
	v_pk_fma_f32 v[34:35], v[34:35], v[26:27], v[58:59] op_sel_hi:[0,1,1]
	ds_read_b128 v[24:27], v209 offset:5888
	s_waitcnt vmcnt(1)
	v_lshlrev_b32_e32 v58, 16, v16
	v_and_b32_e32 v59, 0xffff0000, v16
	v_lshlrev_b32_e32 v16, 16, v17
	v_and_b32_e32 v17, 0xffff0000, v17
	s_waitcnt lgkmcnt(0)
	v_pk_fma_f32 v[88:89], v[24:25], v[58:59], v[96:97] op_sel_hi:[0,1,1]
	v_lshlrev_b32_e32 v96, 16, v18
	v_and_b32_e32 v97, 0xffff0000, v18
	v_lshlrev_b32_e32 v18, 16, v19
	v_and_b32_e32 v19, 0xffff0000, v19
	v_pk_fma_f32 v[90:91], v[24:25], v[16:17], v[98:99] op_sel_hi:[0,1,1]
	v_pk_fma_f32 v[98:99], v[24:25], v[96:97], v[106:107] op_sel_hi:[0,1,1]
	v_pk_fma_f32 v[104:105], v[24:25], v[18:19], v[112:113] op_sel_hi:[0,1,1]
	v_pk_fma_f32 v[106:107], v[24:25], v[58:59], v[114:115] op_sel:[1,0,0]
	v_pk_fma_f32 v[112:113], v[24:25], v[16:17], v[120:121] op_sel:[1,0,0]
	v_pk_fma_f32 v[114:115], v[24:25], v[96:97], v[122:123] op_sel:[1,0,0]
	v_pk_fma_f32 v[24:25], v[24:25], v[18:19], v[32:33] op_sel:[1,0,0]
	v_pk_fma_f32 v[32:33], v[26:27], v[58:59], v[56:57] op_sel_hi:[0,1,1]
	v_pk_fma_f32 v[56:57], v[26:27], v[16:17], v[64:65] op_sel_hi:[0,1,1]
	v_pk_fma_f32 v[64:65], v[26:27], v[96:97], v[72:73] op_sel_hi:[0,1,1]
	v_pk_fma_f32 v[72:73], v[26:27], v[18:19], v[80:81] op_sel_hi:[0,1,1]
	v_mov_b32_e32 v26, v27
	v_pk_fma_f32 v[58:59], v[26:27], v[58:59], v[66:67] op_sel_hi:[0,1,1]
	v_pk_fma_f32 v[66:67], v[26:27], v[16:17], v[74:75] op_sel_hi:[0,1,1]
	v_pk_fma_f32 v[74:75], v[26:27], v[96:97], v[82:83] op_sel_hi:[0,1,1]
	v_pk_fma_f32 v[26:27], v[26:27], v[18:19], v[34:35] op_sel_hi:[0,1,1]
	ds_read_b128 v[16:19], v209 offset:6016
	s_waitcnt vmcnt(0)
	v_lshlrev_b32_e32 v34, 16, v8
	v_and_b32_e32 v35, 0xffff0000, v8
	v_lshlrev_b32_e32 v8, 16, v9
	v_and_b32_e32 v9, 0xffff0000, v9
	s_waitcnt lgkmcnt(0)
	v_pk_fma_f32 v[80:81], v[16:17], v[34:35], v[88:89] op_sel_hi:[0,1,1]
	v_lshlrev_b32_e32 v88, 16, v10
	v_and_b32_e32 v89, 0xffff0000, v10
	v_lshlrev_b32_e32 v10, 16, v11
	v_and_b32_e32 v11, 0xffff0000, v11
	v_pk_fma_f32 v[82:83], v[16:17], v[8:9], v[90:91] op_sel_hi:[0,1,1]
	v_pk_fma_f32 v[90:91], v[16:17], v[88:89], v[98:99] op_sel_hi:[0,1,1]
	v_pk_fma_f32 v[96:97], v[16:17], v[10:11], v[104:105] op_sel_hi:[0,1,1]
	v_pk_fma_f32 v[98:99], v[16:17], v[34:35], v[106:107] op_sel:[1,0,0]
	v_pk_fma_f32 v[104:105], v[16:17], v[8:9], v[112:113] op_sel:[1,0,0]
	v_pk_fma_f32 v[106:107], v[16:17], v[88:89], v[114:115] op_sel:[1,0,0]
	v_pk_fma_f32 v[16:17], v[16:17], v[10:11], v[24:25] op_sel:[1,0,0]
	v_pk_fma_f32 v[24:25], v[18:19], v[34:35], v[32:33] op_sel_hi:[0,1,1]
	v_pk_fma_f32 v[32:33], v[18:19], v[8:9], v[56:57] op_sel_hi:[0,1,1]
	v_pk_fma_f32 v[56:57], v[18:19], v[88:89], v[64:65] op_sel_hi:[0,1,1]
	v_pk_fma_f32 v[64:65], v[18:19], v[10:11], v[72:73] op_sel_hi:[0,1,1]
	v_mov_b32_e32 v18, v19
	v_pk_fma_f32 v[34:35], v[18:19], v[34:35], v[58:59] op_sel_hi:[0,1,1]
	v_pk_fma_f32 v[58:59], v[18:19], v[8:9], v[66:67] op_sel_hi:[0,1,1]
	v_pk_fma_f32 v[66:67], v[18:19], v[88:89], v[74:75] op_sel_hi:[0,1,1]
	v_pk_fma_f32 v[18:19], v[18:19], v[10:11], v[26:27] op_sel_hi:[0,1,1]
	ds_read_b128 v[8:11], v209 offset:6144
	v_lshlrev_b32_e32 v26, 16, v140
	v_and_b32_e32 v27, 0xffff0000, v140
	v_lshlrev_b32_e32 v74, 16, v141
	v_and_b32_e32 v75, 0xffff0000, v141
	s_waitcnt lgkmcnt(0)
	v_pk_fma_f32 v[72:73], v[8:9], v[26:27], v[80:81] op_sel_hi:[0,1,1]
	v_pk_fma_f32 v[80:81], v[8:9], v[74:75], v[82:83] op_sel_hi:[0,1,1]
	v_lshlrev_b32_e32 v82, 16, v142
	v_and_b32_e32 v83, 0xffff0000, v142
	v_pk_fma_f32 v[88:89], v[8:9], v[82:83], v[90:91] op_sel_hi:[0,1,1]
	v_lshlrev_b32_e32 v90, 16, v143
	v_and_b32_e32 v91, 0xffff0000, v143
	v_pk_fma_f32 v[96:97], v[8:9], v[90:91], v[96:97] op_sel_hi:[0,1,1]
	v_pk_fma_f32 v[98:99], v[8:9], v[26:27], v[98:99] op_sel:[1,0,0]
	v_pk_fma_f32 v[104:105], v[8:9], v[74:75], v[104:105] op_sel:[1,0,0]
	v_pk_fma_f32 v[106:107], v[8:9], v[82:83], v[106:107] op_sel:[1,0,0]
	v_pk_fma_f32 v[16:17], v[8:9], v[90:91], v[16:17] op_sel:[1,0,0]
	v_mov_b32_e32 v8, v11
	v_pk_fma_f32 v[24:25], v[10:11], v[26:27], v[24:25] op_sel_hi:[0,1,1]
	v_pk_fma_f32 v[32:33], v[10:11], v[74:75], v[32:33] op_sel_hi:[0,1,1]
	v_pk_fma_f32 v[56:57], v[10:11], v[82:83], v[56:57] op_sel_hi:[0,1,1]
	v_pk_fma_f32 v[64:65], v[10:11], v[90:91], v[64:65] op_sel_hi:[0,1,1]
	v_pk_fma_f32 v[26:27], v[8:9], v[26:27], v[34:35] op_sel_hi:[0,1,1]
	v_pk_fma_f32 v[34:35], v[8:9], v[74:75], v[58:59] op_sel_hi:[0,1,1]
	v_pk_fma_f32 v[58:59], v[8:9], v[82:83], v[66:67] op_sel_hi:[0,1,1]
	v_pk_fma_f32 v[18:19], v[8:9], v[90:91], v[18:19] op_sel_hi:[0,1,1]
	ds_read_b128 v[8:11], v209 offset:6272
	v_lshlrev_b32_e32 v66, 16, v132
	v_and_b32_e32 v67, 0xffff0000, v132
	v_lshlrev_b32_e32 v74, 16, v133
	v_and_b32_e32 v75, 0xffff0000, v133
	v_lshlrev_b32_e32 v82, 16, v134
	v_and_b32_e32 v83, 0xffff0000, v134
	v_lshlrev_b32_e32 v90, 16, v135
	v_and_b32_e32 v91, 0xffff0000, v135
	s_waitcnt lgkmcnt(0)
; DI float bf_lo(unsigned u) { return __uint_as_float(u << 16); }
; DI float bf_hi(unsigned u) { return __uint_as_float(u & 0xffff0000u); }
; DI void dsa_job(const Params& p, int b, int tq0, char* lds) {
;     ...
;   auto pv_fma = [&](int grp, const u32x4* src) {
; #pragma unroll
;     for (int s = 0; s < 16; ++s) {
;       const int slot = 4 * (grp * 16 + s) + ksub;
;       const f32x4 pp = *(const f32x4*)(Pl + slot * 8 + g * 4);
;       const u32x4 vv = src[s];
; #pragma unroll
;       for (int hh = 0; hh < 4; ++hh) {
;         const f32x2 ph = {pp[hh], pp[hh]};
; #pragma unroll
;         for (int e = 0; e < 4; ++e) {
;           const f32x2 vf2 = {bf_lo(vv[e]), bf_hi(vv[e])};
;           acc2[hh][e] += ph * vf2;
;         }
;       }
;     }
;   };
;   pv_load(0, vA);
;   pv_load(1, vB);
;   pv_fma(0, vA);
;   pv_load(2, vA);
;   pv_fma(1, vB);
;   pv_load(3, vB);
;   pv_fma(2, vA);
;   pv_fma(3, vB);
	v_pk_fma_f32 v[72:73], v[8:9], v[66:67], v[72:73] op_sel_hi:[0,1,1]
	v_pk_fma_f32 v[80:81], v[8:9], v[74:75], v[80:81] op_sel_hi:[0,1,1]
	v_pk_fma_f32 v[88:89], v[8:9], v[82:83], v[88:89] op_sel_hi:[0,1,1]
	v_pk_fma_f32 v[96:97], v[8:9], v[90:91], v[96:97] op_sel_hi:[0,1,1]
	v_pk_fma_f32 v[98:99], v[8:9], v[66:67], v[98:99] op_sel:[1,0,0]
	v_pk_fma_f32 v[104:105], v[8:9], v[74:75], v[104:105] op_sel:[1,0,0]
	v_pk_fma_f32 v[106:107], v[8:9], v[82:83], v[106:107] op_sel:[1,0,0]
	v_pk_fma_f32 v[16:17], v[8:9], v[90:91], v[16:17] op_sel:[1,0,0]
	v_mov_b32_e32 v8, v11
	v_pk_fma_f32 v[24:25], v[10:11], v[66:67], v[24:25] op_sel_hi:[0,1,1]
	v_pk_fma_f32 v[32:33], v[10:11], v[74:75], v[32:33] op_sel_hi:[0,1,1]
	v_pk_fma_f32 v[56:57], v[10:11], v[82:83], v[56:57] op_sel_hi:[0,1,1]
	v_pk_fma_f32 v[64:65], v[10:11], v[90:91], v[64:65] op_sel_hi:[0,1,1]
	v_pk_fma_f32 v[26:27], v[8:9], v[66:67], v[26:27] op_sel_hi:[0,1,1]
	v_pk_fma_f32 v[34:35], v[8:9], v[74:75], v[34:35] op_sel_hi:[0,1,1]
	v_pk_fma_f32 v[58:59], v[8:9], v[82:83], v[58:59] op_sel_hi:[0,1,1]
	v_pk_fma_f32 v[18:19], v[8:9], v[90:91], v[18:19] op_sel_hi:[0,1,1]
	ds_read_b128 v[8:11], v209 offset:6400
	v_lshlrev_b32_e32 v66, 16, v124
	v_and_b32_e32 v67, 0xffff0000, v124
	v_lshlrev_b32_e32 v74, 16, v125
	v_and_b32_e32 v75, 0xffff0000, v125
	v_lshlrev_b32_e32 v82, 16, v126
	v_and_b32_e32 v83, 0xffff0000, v126
	v_lshlrev_b32_e32 v90, 16, v127
	v_and_b32_e32 v91, 0xffff0000, v127
	s_waitcnt lgkmcnt(0)
	v_pk_fma_f32 v[72:73], v[8:9], v[66:67], v[72:73] op_sel_hi:[0,1,1]
	v_pk_fma_f32 v[80:81], v[8:9], v[74:75], v[80:81] op_sel_hi:[0,1,1]
	v_pk_fma_f32 v[88:89], v[8:9], v[82:83], v[88:89] op_sel_hi:[0,1,1]
	v_pk_fma_f32 v[96:97], v[8:9], v[90:91], v[96:97] op_sel_hi:[0,1,1]
	v_pk_fma_f32 v[98:99], v[8:9], v[66:67], v[98:99] op_sel:[1,0,0]
	v_pk_fma_f32 v[104:105], v[8:9], v[74:75], v[104:105] op_sel:[1,0,0]
	v_pk_fma_f32 v[106:107], v[8:9], v[82:83], v[106:107] op_sel:[1,0,0]
	v_pk_fma_f32 v[16:17], v[8:9], v[90:91], v[16:17] op_sel:[1,0,0]
	v_mov_b32_e32 v8, v11
	v_pk_fma_f32 v[24:25], v[10:11], v[66:67], v[24:25] op_sel_hi:[0,1,1]
	v_pk_fma_f32 v[32:33], v[10:11], v[74:75], v[32:33] op_sel_hi:[0,1,1]
	v_pk_fma_f32 v[56:57], v[10:11], v[82:83], v[56:57] op_sel_hi:[0,1,1]
	v_pk_fma_f32 v[64:65], v[10:11], v[90:91], v[64:65] op_sel_hi:[0,1,1]
	v_pk_fma_f32 v[26:27], v[8:9], v[66:67], v[26:27] op_sel_hi:[0,1,1]
	v_pk_fma_f32 v[34:35], v[8:9], v[74:75], v[34:35] op_sel_hi:[0,1,1]
	v_pk_fma_f32 v[58:59], v[8:9], v[82:83], v[58:59] op_sel_hi:[0,1,1]
	v_pk_fma_f32 v[18:19], v[8:9], v[90:91], v[18:19] op_sel_hi:[0,1,1]
	ds_read_b128 v[8:11], v209 offset:6528
	v_lshlrev_b32_e32 v66, 16, v116
	v_and_b32_e32 v67, 0xffff0000, v116
	v_lshlrev_b32_e32 v74, 16, v117
	v_and_b32_e32 v75, 0xffff0000, v117
	v_lshlrev_b32_e32 v82, 16, v118
	v_and_b32_e32 v83, 0xffff0000, v118
	v_lshlrev_b32_e32 v90, 16, v119
	v_and_b32_e32 v91, 0xffff0000, v119
	s_waitcnt lgkmcnt(0)
	v_pk_fma_f32 v[72:73], v[8:9], v[66:67], v[72:73] op_sel_hi:[0,1,1]
	v_pk_fma_f32 v[80:81], v[8:9], v[74:75], v[80:81] op_sel_hi:[0,1,1]
	v_pk_fma_f32 v[88:89], v[8:9], v[82:83], v[88:89] op_sel_hi:[0,1,1]
	v_pk_fma_f32 v[96:97], v[8:9], v[90:91], v[96:97] op_sel_hi:[0,1,1]
	v_pk_fma_f32 v[98:99], v[8:9], v[66:67], v[98:99] op_sel:[1,0,0]
	v_pk_fma_f32 v[104:105], v[8:9], v[74:75], v[104:105] op_sel:[1,0,0]
	v_pk_fma_f32 v[106:107], v[8:9], v[82:83], v[106:107] op_sel:[1,0,0]
	v_pk_fma_f32 v[16:17], v[8:9], v[90:91], v[16:17] op_sel:[1,0,0]
	v_mov_b32_e32 v8, v11
	v_pk_fma_f32 v[24:25], v[10:11], v[66:67], v[24:25] op_sel_hi:[0,1,1]
	v_pk_fma_f32 v[32:33], v[10:11], v[74:75], v[32:33] op_sel_hi:[0,1,1]
	v_pk_fma_f32 v[56:57], v[10:11], v[82:83], v[56:57] op_sel_hi:[0,1,1]
	v_pk_fma_f32 v[64:65], v[10:11], v[90:91], v[64:65] op_sel_hi:[0,1,1]
	v_pk_fma_f32 v[26:27], v[8:9], v[66:67], v[26:27] op_sel_hi:[0,1,1]
	v_pk_fma_f32 v[34:35], v[8:9], v[74:75], v[34:35] op_sel_hi:[0,1,1]
	v_pk_fma_f32 v[58:59], v[8:9], v[82:83], v[58:59] op_sel_hi:[0,1,1]
	v_pk_fma_f32 v[18:19], v[8:9], v[90:91], v[18:19] op_sel_hi:[0,1,1]
	ds_read_b128 v[8:11], v209 offset:6656
	v_lshlrev_b32_e32 v66, 16, v108
	v_and_b32_e32 v67, 0xffff0000, v108
	v_lshlrev_b32_e32 v74, 16, v109
	v_and_b32_e32 v75, 0xffff0000, v109
	v_lshlrev_b32_e32 v82, 16, v110
	v_and_b32_e32 v83, 0xffff0000, v110
	v_lshlrev_b32_e32 v90, 16, v111
	v_and_b32_e32 v91, 0xffff0000, v111
	s_waitcnt lgkmcnt(0)
	v_pk_fma_f32 v[72:73], v[8:9], v[66:67], v[72:73] op_sel_hi:[0,1,1]
	v_pk_fma_f32 v[80:81], v[8:9], v[74:75], v[80:81] op_sel_hi:[0,1,1]
	v_pk_fma_f32 v[88:89], v[8:9], v[82:83], v[88:89] op_sel_hi:[0,1,1]
	v_pk_fma_f32 v[96:97], v[8:9], v[90:91], v[96:97] op_sel_hi:[0,1,1]
	v_pk_fma_f32 v[98:99], v[8:9], v[66:67], v[98:99] op_sel:[1,0,0]
	v_pk_fma_f32 v[104:105], v[8:9], v[74:75], v[104:105] op_sel:[1,0,0]
	v_pk_fma_f32 v[106:107], v[8:9], v[82:83], v[106:107] op_sel:[1,0,0]
	v_pk_fma_f32 v[16:17], v[8:9], v[90:91], v[16:17] op_sel:[1,0,0]
	v_mov_b32_e32 v8, v11
	v_pk_fma_f32 v[24:25], v[10:11], v[66:67], v[24:25] op_sel_hi:[0,1,1]
	v_pk_fma_f32 v[32:33], v[10:11], v[74:75], v[32:33] op_sel_hi:[0,1,1]
	v_pk_fma_f32 v[56:57], v[10:11], v[82:83], v[56:57] op_sel_hi:[0,1,1]
	v_pk_fma_f32 v[64:65], v[10:11], v[90:91], v[64:65] op_sel_hi:[0,1,1]
	v_pk_fma_f32 v[26:27], v[8:9], v[66:67], v[26:27] op_sel_hi:[0,1,1]
	v_pk_fma_f32 v[34:35], v[8:9], v[74:75], v[34:35] op_sel_hi:[0,1,1]
	v_pk_fma_f32 v[58:59], v[8:9], v[82:83], v[58:59] op_sel_hi:[0,1,1]
	v_pk_fma_f32 v[18:19], v[8:9], v[90:91], v[18:19] op_sel_hi:[0,1,1]
	ds_read_b128 v[8:11], v209 offset:6784
	v_lshlrev_b32_e32 v66, 16, v100
	v_and_b32_e32 v67, 0xffff0000, v100
	v_lshlrev_b32_e32 v74, 16, v101
	v_and_b32_e32 v75, 0xffff0000, v101
	v_lshlrev_b32_e32 v82, 16, v102
	v_and_b32_e32 v83, 0xffff0000, v102
	v_lshlrev_b32_e32 v90, 16, v103
	v_and_b32_e32 v91, 0xffff0000, v103
	s_waitcnt lgkmcnt(0)
; DI float bf_lo(unsigned u) { return __uint_as_float(u << 16); }
; DI float bf_hi(unsigned u) { return __uint_as_float(u & 0xffff0000u); }
; DI void dsa_job(const Params& p, int b, int tq0, char* lds) {
;     ...
;   auto pv_fma = [&](int grp, const u32x4* src) {
; #pragma unroll
;     for (int s = 0; s < 16; ++s) {
;       const int slot = 4 * (grp * 16 + s) + ksub;
;       const f32x4 pp = *(const f32x4*)(Pl + slot * 8 + g * 4);
;       const u32x4 vv = src[s];
; #pragma unroll
;       for (int hh = 0; hh < 4; ++hh) {
;         const f32x2 ph = {pp[hh], pp[hh]};
; #pragma unroll
;         for (int e = 0; e < 4; ++e) {
;           const f32x2 vf2 = {bf_lo(vv[e]), bf_hi(vv[e])};
;           acc2[hh][e] += ph * vf2;
;         }
;       }
;     }
;   };
;   pv_load(0, vA);
;   pv_load(1, vB);
;   pv_fma(0, vA);
;   pv_load(2, vA);
;   pv_fma(1, vB);
;   pv_load(3, vB);
;   pv_fma(2, vA);
;   pv_fma(3, vB);
	v_pk_fma_f32 v[72:73], v[8:9], v[66:67], v[72:73] op_sel_hi:[0,1,1]
	v_pk_fma_f32 v[80:81], v[8:9], v[74:75], v[80:81] op_sel_hi:[0,1,1]
	v_pk_fma_f32 v[88:89], v[8:9], v[82:83], v[88:89] op_sel_hi:[0,1,1]
	v_pk_fma_f32 v[96:97], v[8:9], v[90:91], v[96:97] op_sel_hi:[0,1,1]
	v_pk_fma_f32 v[98:99], v[8:9], v[66:67], v[98:99] op_sel:[1,0,0]
	v_pk_fma_f32 v[100:101], v[8:9], v[74:75], v[104:105] op_sel:[1,0,0]
	v_pk_fma_f32 v[102:103], v[8:9], v[82:83], v[106:107] op_sel:[1,0,0]
	v_pk_fma_f32 v[16:17], v[8:9], v[90:91], v[16:17] op_sel:[1,0,0]
	v_mov_b32_e32 v8, v11
	v_pk_fma_f32 v[24:25], v[10:11], v[66:67], v[24:25] op_sel_hi:[0,1,1]
	v_pk_fma_f32 v[32:33], v[10:11], v[74:75], v[32:33] op_sel_hi:[0,1,1]
	v_pk_fma_f32 v[56:57], v[10:11], v[82:83], v[56:57] op_sel_hi:[0,1,1]
	v_pk_fma_f32 v[64:65], v[10:11], v[90:91], v[64:65] op_sel_hi:[0,1,1]
	v_pk_fma_f32 v[26:27], v[8:9], v[66:67], v[26:27] op_sel_hi:[0,1,1]
	v_pk_fma_f32 v[34:35], v[8:9], v[74:75], v[34:35] op_sel_hi:[0,1,1]
	v_pk_fma_f32 v[58:59], v[8:9], v[82:83], v[58:59] op_sel_hi:[0,1,1]
	v_pk_fma_f32 v[18:19], v[8:9], v[90:91], v[18:19] op_sel_hi:[0,1,1]
	ds_read_b128 v[8:11], v209 offset:6912
	v_lshlrev_b32_e32 v66, 16, v92
	v_and_b32_e32 v67, 0xffff0000, v92
	v_lshlrev_b32_e32 v74, 16, v93
	v_and_b32_e32 v75, 0xffff0000, v93
	v_lshlrev_b32_e32 v82, 16, v94
	v_and_b32_e32 v83, 0xffff0000, v94
	v_lshlrev_b32_e32 v90, 16, v95
	v_and_b32_e32 v91, 0xffff0000, v95
	s_waitcnt lgkmcnt(0)
	v_pk_fma_f32 v[72:73], v[8:9], v[66:67], v[72:73] op_sel_hi:[0,1,1]
	v_pk_fma_f32 v[80:81], v[8:9], v[74:75], v[80:81] op_sel_hi:[0,1,1]
	v_pk_fma_f32 v[88:89], v[8:9], v[82:83], v[88:89] op_sel_hi:[0,1,1]
	v_pk_fma_f32 v[92:93], v[8:9], v[90:91], v[96:97] op_sel_hi:[0,1,1]
	v_pk_fma_f32 v[94:95], v[8:9], v[66:67], v[98:99] op_sel:[1,0,0]
	v_pk_fma_f32 v[96:97], v[8:9], v[74:75], v[100:101] op_sel:[1,0,0]
	v_pk_fma_f32 v[98:99], v[8:9], v[82:83], v[102:103] op_sel:[1,0,0]
	v_pk_fma_f32 v[16:17], v[8:9], v[90:91], v[16:17] op_sel:[1,0,0]
	v_mov_b32_e32 v8, v11
	v_pk_fma_f32 v[24:25], v[10:11], v[66:67], v[24:25] op_sel_hi:[0,1,1]
	v_pk_fma_f32 v[32:33], v[10:11], v[74:75], v[32:33] op_sel_hi:[0,1,1]
	v_pk_fma_f32 v[56:57], v[10:11], v[82:83], v[56:57] op_sel_hi:[0,1,1]
	v_pk_fma_f32 v[64:65], v[10:11], v[90:91], v[64:65] op_sel_hi:[0,1,1]
	v_pk_fma_f32 v[26:27], v[8:9], v[66:67], v[26:27] op_sel_hi:[0,1,1]
	v_pk_fma_f32 v[34:35], v[8:9], v[74:75], v[34:35] op_sel_hi:[0,1,1]
	v_pk_fma_f32 v[58:59], v[8:9], v[82:83], v[58:59] op_sel_hi:[0,1,1]
	v_pk_fma_f32 v[18:19], v[8:9], v[90:91], v[18:19] op_sel_hi:[0,1,1]
	ds_read_b128 v[8:11], v209 offset:7040
	v_lshlrev_b32_e32 v66, 16, v84
	v_and_b32_e32 v67, 0xffff0000, v84
	v_lshlrev_b32_e32 v74, 16, v85
	v_and_b32_e32 v75, 0xffff0000, v85
	v_lshlrev_b32_e32 v82, 16, v86
	v_and_b32_e32 v83, 0xffff0000, v86
	v_lshlrev_b32_e32 v86, 16, v87
	v_and_b32_e32 v87, 0xffff0000, v87
	s_waitcnt lgkmcnt(0)
	v_pk_fma_f32 v[72:73], v[8:9], v[66:67], v[72:73] op_sel_hi:[0,1,1]
	v_pk_fma_f32 v[80:81], v[8:9], v[74:75], v[80:81] op_sel_hi:[0,1,1]
	v_pk_fma_f32 v[84:85], v[8:9], v[82:83], v[88:89] op_sel_hi:[0,1,1]
	v_pk_fma_f32 v[88:89], v[8:9], v[86:87], v[92:93] op_sel_hi:[0,1,1]
	v_pk_fma_f32 v[90:91], v[8:9], v[66:67], v[94:95] op_sel:[1,0,0]
	v_pk_fma_f32 v[92:93], v[8:9], v[74:75], v[96:97] op_sel:[1,0,0]
	v_pk_fma_f32 v[94:95], v[8:9], v[82:83], v[98:99] op_sel:[1,0,0]
	v_pk_fma_f32 v[16:17], v[8:9], v[86:87], v[16:17] op_sel:[1,0,0]
	v_mov_b32_e32 v8, v11
	v_pk_fma_f32 v[24:25], v[10:11], v[66:67], v[24:25] op_sel_hi:[0,1,1]
	v_pk_fma_f32 v[32:33], v[10:11], v[74:75], v[32:33] op_sel_hi:[0,1,1]
	v_pk_fma_f32 v[56:57], v[10:11], v[82:83], v[56:57] op_sel_hi:[0,1,1]
	v_pk_fma_f32 v[64:65], v[10:11], v[86:87], v[64:65] op_sel_hi:[0,1,1]
	v_pk_fma_f32 v[26:27], v[8:9], v[66:67], v[26:27] op_sel_hi:[0,1,1]
	v_pk_fma_f32 v[34:35], v[8:9], v[74:75], v[34:35] op_sel_hi:[0,1,1]
	v_pk_fma_f32 v[58:59], v[8:9], v[82:83], v[58:59] op_sel_hi:[0,1,1]
	v_pk_fma_f32 v[18:19], v[8:9], v[86:87], v[18:19] op_sel_hi:[0,1,1]
	ds_read_b128 v[8:11], v209 offset:7168
	v_lshlrev_b32_e32 v74, 16, v77
	v_and_b32_e32 v75, 0xffff0000, v77
	v_lshlrev_b32_e32 v66, 16, v76
	v_and_b32_e32 v67, 0xffff0000, v76
	s_waitcnt lgkmcnt(0)
	v_pk_fma_f32 v[76:77], v[8:9], v[74:75], v[80:81] op_sel_hi:[0,1,1]
	v_lshlrev_b32_e32 v80, 16, v78
	v_and_b32_e32 v81, 0xffff0000, v78
	v_lshlrev_b32_e32 v78, 16, v79
	v_and_b32_e32 v79, 0xffff0000, v79
	v_pk_fma_f32 v[72:73], v[8:9], v[66:67], v[72:73] op_sel_hi:[0,1,1]
	v_pk_fma_f32 v[82:83], v[8:9], v[80:81], v[84:85] op_sel_hi:[0,1,1]
	v_pk_fma_f32 v[84:85], v[8:9], v[78:79], v[88:89] op_sel_hi:[0,1,1]
	v_pk_fma_f32 v[86:87], v[8:9], v[66:67], v[90:91] op_sel:[1,0,0]
	v_pk_fma_f32 v[88:89], v[8:9], v[74:75], v[92:93] op_sel:[1,0,0]
	v_pk_fma_f32 v[90:91], v[8:9], v[80:81], v[94:95] op_sel:[1,0,0]
	v_pk_fma_f32 v[16:17], v[8:9], v[78:79], v[16:17] op_sel:[1,0,0]
	v_mov_b32_e32 v8, v11
	v_pk_fma_f32 v[24:25], v[10:11], v[66:67], v[24:25] op_sel_hi:[0,1,1]
	v_pk_fma_f32 v[32:33], v[10:11], v[74:75], v[32:33] op_sel_hi:[0,1,1]
	v_pk_fma_f32 v[56:57], v[10:11], v[80:81], v[56:57] op_sel_hi:[0,1,1]
	v_pk_fma_f32 v[64:65], v[10:11], v[78:79], v[64:65] op_sel_hi:[0,1,1]
	v_pk_fma_f32 v[26:27], v[8:9], v[66:67], v[26:27] op_sel_hi:[0,1,1]
	v_pk_fma_f32 v[34:35], v[8:9], v[74:75], v[34:35] op_sel_hi:[0,1,1]
	v_pk_fma_f32 v[58:59], v[8:9], v[80:81], v[58:59] op_sel_hi:[0,1,1]
	v_pk_fma_f32 v[18:19], v[8:9], v[78:79], v[18:19] op_sel_hi:[0,1,1]
	ds_read_b128 v[8:11], v209 offset:7296
	v_lshlrev_b32_e32 v66, 16, v68
	v_and_b32_e32 v67, 0xffff0000, v68
	v_lshlrev_b32_e32 v68, 16, v69
	v_and_b32_e32 v69, 0xffff0000, v69
	s_waitcnt lgkmcnt(0)
; DI float bf_lo(unsigned u) { return __uint_as_float(u << 16); }
; DI float bf_hi(unsigned u) { return __uint_as_float(u & 0xffff0000u); }
; DI void dsa_job(const Params& p, int b, int tq0, char* lds) {
;     ...
;   auto pv_fma = [&](int grp, const u32x4* src) {
; #pragma unroll
;     for (int s = 0; s < 16; ++s) {
;       const int slot = 4 * (grp * 16 + s) + ksub;
;       const f32x4 pp = *(const f32x4*)(Pl + slot * 8 + g * 4);
;       const u32x4 vv = src[s];
; #pragma unroll
;       for (int hh = 0; hh < 4; ++hh) {
;         const f32x2 ph = {pp[hh], pp[hh]};
; #pragma unroll
;         for (int e = 0; e < 4; ++e) {
;           const f32x2 vf2 = {bf_lo(vv[e]), bf_hi(vv[e])};
;           acc2[hh][e] += ph * vf2;
;         }
;       }
;     }
;   };
;   pv_load(0, vA);
;   pv_load(1, vB);
;   pv_fma(0, vA);
;   pv_load(2, vA);
;   pv_fma(1, vB);
;   pv_load(3, vB);
;   pv_fma(2, vA);
;   pv_fma(3, vB);
	v_pk_fma_f32 v[74:75], v[8:9], v[68:69], v[76:77] op_sel_hi:[0,1,1]
	v_lshlrev_b32_e32 v76, 16, v70
	v_and_b32_e32 v77, 0xffff0000, v70
	v_lshlrev_b32_e32 v70, 16, v71
	v_and_b32_e32 v71, 0xffff0000, v71
	v_pk_fma_f32 v[72:73], v[8:9], v[66:67], v[72:73] op_sel_hi:[0,1,1]
	v_pk_fma_f32 v[78:79], v[8:9], v[76:77], v[82:83] op_sel_hi:[0,1,1]
	v_pk_fma_f32 v[80:81], v[8:9], v[70:71], v[84:85] op_sel_hi:[0,1,1]
	v_pk_fma_f32 v[82:83], v[8:9], v[66:67], v[86:87] op_sel:[1,0,0]
	v_pk_fma_f32 v[84:85], v[8:9], v[68:69], v[88:89] op_sel:[1,0,0]
	v_pk_fma_f32 v[86:87], v[8:9], v[76:77], v[90:91] op_sel:[1,0,0]
	v_pk_fma_f32 v[16:17], v[8:9], v[70:71], v[16:17] op_sel:[1,0,0]
	v_mov_b32_e32 v8, v11
	v_pk_fma_f32 v[24:25], v[10:11], v[66:67], v[24:25] op_sel_hi:[0,1,1]
	v_pk_fma_f32 v[32:33], v[10:11], v[68:69], v[32:33] op_sel_hi:[0,1,1]
	v_pk_fma_f32 v[56:57], v[10:11], v[76:77], v[56:57] op_sel_hi:[0,1,1]
	v_pk_fma_f32 v[64:65], v[10:11], v[70:71], v[64:65] op_sel_hi:[0,1,1]
	v_pk_fma_f32 v[26:27], v[8:9], v[66:67], v[26:27] op_sel_hi:[0,1,1]
	v_pk_fma_f32 v[34:35], v[8:9], v[68:69], v[34:35] op_sel_hi:[0,1,1]
	v_pk_fma_f32 v[58:59], v[8:9], v[76:77], v[58:59] op_sel_hi:[0,1,1]
	v_pk_fma_f32 v[18:19], v[8:9], v[70:71], v[18:19] op_sel_hi:[0,1,1]
	ds_read_b128 v[8:11], v209 offset:7424
	v_lshlrev_b32_e32 v66, 16, v60
	v_and_b32_e32 v67, 0xffff0000, v60
	v_lshlrev_b32_e32 v60, 16, v61
	v_and_b32_e32 v61, 0xffff0000, v61
	s_waitcnt lgkmcnt(0)
	v_pk_fma_f32 v[68:69], v[8:9], v[66:67], v[72:73] op_sel_hi:[0,1,1]
	v_lshlrev_b32_e32 v72, 16, v62
	v_and_b32_e32 v73, 0xffff0000, v62
	v_lshlrev_b32_e32 v62, 16, v63
	v_and_b32_e32 v63, 0xffff0000, v63
	v_pk_fma_f32 v[70:71], v[8:9], v[60:61], v[74:75] op_sel_hi:[0,1,1]
	v_pk_fma_f32 v[74:75], v[8:9], v[72:73], v[78:79] op_sel_hi:[0,1,1]
	v_pk_fma_f32 v[76:77], v[8:9], v[62:63], v[80:81] op_sel_hi:[0,1,1]
	v_pk_fma_f32 v[78:79], v[8:9], v[66:67], v[82:83] op_sel:[1,0,0]
	v_pk_fma_f32 v[80:81], v[8:9], v[60:61], v[84:85] op_sel:[1,0,0]
	v_pk_fma_f32 v[82:83], v[8:9], v[72:73], v[86:87] op_sel:[1,0,0]
	v_pk_fma_f32 v[16:17], v[8:9], v[62:63], v[16:17] op_sel:[1,0,0]
	v_mov_b32_e32 v8, v11
	v_pk_fma_f32 v[24:25], v[10:11], v[66:67], v[24:25] op_sel_hi:[0,1,1]
	v_pk_fma_f32 v[32:33], v[10:11], v[60:61], v[32:33] op_sel_hi:[0,1,1]
	v_pk_fma_f32 v[56:57], v[10:11], v[72:73], v[56:57] op_sel_hi:[0,1,1]
	v_pk_fma_f32 v[64:65], v[10:11], v[62:63], v[64:65] op_sel_hi:[0,1,1]
	v_pk_fma_f32 v[26:27], v[8:9], v[66:67], v[26:27] op_sel_hi:[0,1,1]
	v_pk_fma_f32 v[34:35], v[8:9], v[60:61], v[34:35] op_sel_hi:[0,1,1]
	v_pk_fma_f32 v[58:59], v[8:9], v[72:73], v[58:59] op_sel_hi:[0,1,1]
	v_pk_fma_f32 v[18:19], v[8:9], v[62:63], v[18:19] op_sel_hi:[0,1,1]
	ds_read_b128 v[8:11], v209 offset:7552
	v_lshlrev_b32_e32 v60, 16, v52
	v_and_b32_e32 v61, 0xffff0000, v52
	v_lshlrev_b32_e32 v52, 16, v53
	v_and_b32_e32 v53, 0xffff0000, v53
	s_waitcnt lgkmcnt(0)
	v_pk_fma_f32 v[62:63], v[8:9], v[60:61], v[68:69] op_sel_hi:[0,1,1]
	v_lshlrev_b32_e32 v68, 16, v54
	v_and_b32_e32 v69, 0xffff0000, v54
	v_lshlrev_b32_e32 v54, 16, v55
	v_and_b32_e32 v55, 0xffff0000, v55
	v_pk_fma_f32 v[66:67], v[8:9], v[52:53], v[70:71] op_sel_hi:[0,1,1]
	v_pk_fma_f32 v[70:71], v[8:9], v[68:69], v[74:75] op_sel_hi:[0,1,1]
	v_pk_fma_f32 v[72:73], v[8:9], v[54:55], v[76:77] op_sel_hi:[0,1,1]
	v_pk_fma_f32 v[74:75], v[8:9], v[60:61], v[78:79] op_sel:[1,0,0]
	v_pk_fma_f32 v[76:77], v[8:9], v[52:53], v[80:81] op_sel:[1,0,0]
	v_pk_fma_f32 v[78:79], v[8:9], v[68:69], v[82:83] op_sel:[1,0,0]
	v_pk_fma_f32 v[16:17], v[8:9], v[54:55], v[16:17] op_sel:[1,0,0]
	v_mov_b32_e32 v8, v11
	v_pk_fma_f32 v[24:25], v[10:11], v[60:61], v[24:25] op_sel_hi:[0,1,1]
	v_pk_fma_f32 v[32:33], v[10:11], v[52:53], v[32:33] op_sel_hi:[0,1,1]
	v_pk_fma_f32 v[56:57], v[10:11], v[68:69], v[56:57] op_sel_hi:[0,1,1]
	v_pk_fma_f32 v[64:65], v[10:11], v[54:55], v[64:65] op_sel_hi:[0,1,1]
	v_pk_fma_f32 v[26:27], v[8:9], v[60:61], v[26:27] op_sel_hi:[0,1,1]
	v_pk_fma_f32 v[34:35], v[8:9], v[52:53], v[34:35] op_sel_hi:[0,1,1]
	v_pk_fma_f32 v[52:53], v[8:9], v[68:69], v[58:59] op_sel_hi:[0,1,1]
	v_pk_fma_f32 v[18:19], v[8:9], v[54:55], v[18:19] op_sel_hi:[0,1,1]
	ds_read_b128 v[8:11], v209 offset:7680
	v_lshlrev_b32_e32 v54, 16, v28
	v_and_b32_e32 v55, 0xffff0000, v28
	v_lshlrev_b32_e32 v28, 16, v29
	v_and_b32_e32 v29, 0xffff0000, v29
	s_waitcnt lgkmcnt(0)
	v_pk_fma_f32 v[58:59], v[8:9], v[54:55], v[62:63] op_sel_hi:[0,1,1]
	v_lshlrev_b32_e32 v62, 16, v30
	v_and_b32_e32 v63, 0xffff0000, v30
	v_lshlrev_b32_e32 v30, 16, v31
	v_and_b32_e32 v31, 0xffff0000, v31
	v_pk_fma_f32 v[60:61], v[8:9], v[28:29], v[66:67] op_sel_hi:[0,1,1]
	v_pk_fma_f32 v[66:67], v[8:9], v[62:63], v[70:71] op_sel_hi:[0,1,1]
	v_pk_fma_f32 v[68:69], v[8:9], v[30:31], v[72:73] op_sel_hi:[0,1,1]
	v_pk_fma_f32 v[70:71], v[8:9], v[54:55], v[74:75] op_sel:[1,0,0]
	v_pk_fma_f32 v[72:73], v[8:9], v[28:29], v[76:77] op_sel:[1,0,0]
	v_pk_fma_f32 v[74:75], v[8:9], v[62:63], v[78:79] op_sel:[1,0,0]
	v_pk_fma_f32 v[16:17], v[8:9], v[30:31], v[16:17] op_sel:[1,0,0]
	v_mov_b32_e32 v8, v11
	v_pk_fma_f32 v[24:25], v[10:11], v[54:55], v[24:25] op_sel_hi:[0,1,1]
	v_pk_fma_f32 v[32:33], v[10:11], v[28:29], v[32:33] op_sel_hi:[0,1,1]
	v_pk_fma_f32 v[56:57], v[10:11], v[62:63], v[56:57] op_sel_hi:[0,1,1]
	v_pk_fma_f32 v[64:65], v[10:11], v[30:31], v[64:65] op_sel_hi:[0,1,1]
	v_pk_fma_f32 v[26:27], v[8:9], v[54:55], v[26:27] op_sel_hi:[0,1,1]
	v_pk_fma_f32 v[28:29], v[8:9], v[28:29], v[34:35] op_sel_hi:[0,1,1]
	v_pk_fma_f32 v[34:35], v[8:9], v[62:63], v[52:53] op_sel_hi:[0,1,1]
	v_pk_fma_f32 v[18:19], v[8:9], v[30:31], v[18:19] op_sel_hi:[0,1,1]
	ds_read_b128 v[8:11], v209 offset:7808
	v_lshlrev_b32_e32 v30, 16, v20
	v_and_b32_e32 v31, 0xffff0000, v20
	v_lshlrev_b32_e32 v20, 16, v21
	v_and_b32_e32 v21, 0xffff0000, v21
	s_waitcnt lgkmcnt(0)
; DI float bf_lo(unsigned u) { return __uint_as_float(u << 16); }
; DI float bf_hi(unsigned u) { return __uint_as_float(u & 0xffff0000u); }
; DI void dsa_job(const Params& p, int b, int tq0, char* lds) {
;     ...
;   auto pv_fma = [&](int grp, const u32x4* src) {
; #pragma unroll
;     for (int s = 0; s < 16; ++s) {
;       const int slot = 4 * (grp * 16 + s) + ksub;
;       const f32x4 pp = *(const f32x4*)(Pl + slot * 8 + g * 4);
;       const u32x4 vv = src[s];
; #pragma unroll
;       for (int hh = 0; hh < 4; ++hh) {
;         const f32x2 ph = {pp[hh], pp[hh]};
; #pragma unroll
;         for (int e = 0; e < 4; ++e) {
;           const f32x2 vf2 = {bf_lo(vv[e]), bf_hi(vv[e])};
;           acc2[hh][e] += ph * vf2;
;         }
;       }
;     }
;   };
;   pv_load(0, vA);
;   pv_load(1, vB);
;   pv_fma(0, vA);
;   pv_load(2, vA);
;   pv_fma(1, vB);
;   pv_load(3, vB);
;   pv_fma(2, vA);
;   pv_fma(3, vB);
;   float acc[4][8];
; #pragma unroll
;   for (int hh = 0; hh < 4; ++hh)
; #pragma unroll
;     for (int e = 0; e < 8; ++e) { float v = acc2[hh][e >> 1][e & 1]; v += __shfl_xor(v, 16); v += __shfl_xor(v, 32); acc[hh][e] = v; }
	v_pk_fma_f32 v[52:53], v[8:9], v[30:31], v[58:59] op_sel_hi:[0,1,1]
	v_lshlrev_b32_e32 v58, 16, v22
	v_and_b32_e32 v59, 0xffff0000, v22
	v_lshlrev_b32_e32 v22, 16, v23
	v_and_b32_e32 v23, 0xffff0000, v23
	v_pk_fma_f32 v[54:55], v[8:9], v[20:21], v[60:61] op_sel_hi:[0,1,1]
	v_pk_fma_f32 v[60:61], v[8:9], v[58:59], v[66:67] op_sel_hi:[0,1,1]
	v_pk_fma_f32 v[62:63], v[8:9], v[22:23], v[68:69] op_sel_hi:[0,1,1]
	v_pk_fma_f32 v[66:67], v[8:9], v[30:31], v[70:71] op_sel:[1,0,0]
	v_pk_fma_f32 v[68:69], v[8:9], v[20:21], v[72:73] op_sel:[1,0,0]
	v_pk_fma_f32 v[70:71], v[8:9], v[58:59], v[74:75] op_sel:[1,0,0]
	v_pk_fma_f32 v[16:17], v[8:9], v[22:23], v[16:17] op_sel:[1,0,0]
	v_mov_b32_e32 v8, v11
	v_pk_fma_f32 v[24:25], v[10:11], v[30:31], v[24:25] op_sel_hi:[0,1,1]
	v_pk_fma_f32 v[32:33], v[10:11], v[20:21], v[32:33] op_sel_hi:[0,1,1]
	v_pk_fma_f32 v[56:57], v[10:11], v[58:59], v[56:57] op_sel_hi:[0,1,1]
	v_pk_fma_f32 v[64:65], v[10:11], v[22:23], v[64:65] op_sel_hi:[0,1,1]
	v_pk_fma_f32 v[26:27], v[8:9], v[30:31], v[26:27] op_sel_hi:[0,1,1]
	v_pk_fma_f32 v[20:21], v[8:9], v[20:21], v[28:29] op_sel_hi:[0,1,1]
	v_pk_fma_f32 v[28:29], v[8:9], v[58:59], v[34:35] op_sel_hi:[0,1,1]
	v_pk_fma_f32 v[18:19], v[8:9], v[22:23], v[18:19] op_sel_hi:[0,1,1]
	ds_read_b128 v[8:11], v209 offset:7936
	v_lshlrev_b32_e32 v22, 16, v12
	v_and_b32_e32 v23, 0xffff0000, v12
	v_lshlrev_b32_e32 v12, 16, v13
	v_and_b32_e32 v13, 0xffff0000, v13
	s_waitcnt lgkmcnt(0)
	v_pk_fma_f32 v[30:31], v[8:9], v[22:23], v[52:53] op_sel_hi:[0,1,1]
	v_lshlrev_b32_e32 v52, 16, v14
	v_and_b32_e32 v53, 0xffff0000, v14
	v_lshlrev_b32_e32 v14, 16, v15
	v_and_b32_e32 v15, 0xffff0000, v15
	v_pk_fma_f32 v[34:35], v[8:9], v[12:13], v[54:55] op_sel_hi:[0,1,1]
	v_pk_fma_f32 v[54:55], v[8:9], v[52:53], v[60:61] op_sel_hi:[0,1,1]
	v_pk_fma_f32 v[58:59], v[8:9], v[14:15], v[62:63] op_sel_hi:[0,1,1]
	v_pk_fma_f32 v[60:61], v[8:9], v[22:23], v[66:67] op_sel:[1,0,0]
	v_pk_fma_f32 v[62:63], v[8:9], v[12:13], v[68:69] op_sel:[1,0,0]
	v_pk_fma_f32 v[66:67], v[8:9], v[52:53], v[70:71] op_sel:[1,0,0]
	v_pk_fma_f32 v[16:17], v[8:9], v[14:15], v[16:17] op_sel:[1,0,0]
	v_mov_b32_e32 v8, v11
	v_pk_fma_f32 v[24:25], v[10:11], v[22:23], v[24:25] op_sel_hi:[0,1,1]
	v_pk_fma_f32 v[32:33], v[10:11], v[12:13], v[32:33] op_sel_hi:[0,1,1]
	v_pk_fma_f32 v[56:57], v[10:11], v[52:53], v[56:57] op_sel_hi:[0,1,1]
	v_pk_fma_f32 v[64:65], v[10:11], v[14:15], v[64:65] op_sel_hi:[0,1,1]
	v_pk_fma_f32 v[22:23], v[8:9], v[22:23], v[26:27] op_sel_hi:[0,1,1]
	v_pk_fma_f32 v[26:27], v[8:9], v[12:13], v[20:21] op_sel_hi:[0,1,1]
	v_pk_fma_f32 v[28:29], v[8:9], v[52:53], v[28:29] op_sel_hi:[0,1,1]
	v_pk_fma_f32 v[52:53], v[8:9], v[14:15], v[18:19] op_sel_hi:[0,1,1]
	ds_read_b128 v[8:11], v209 offset:8064
	v_lshlrev_b32_e32 v12, 16, v4
	v_and_b32_e32 v13, 0xffff0000, v4
	v_lshlrev_b32_e32 v4, 16, v5
	v_and_b32_e32 v5, 0xffff0000, v5
	v_lshlrev_b32_e32 v68, 16, v6
	v_and_b32_e32 v69, 0xffff0000, v6
	v_lshlrev_b32_e32 v6, 16, v7
	v_and_b32_e32 v7, 0xffff0000, v7
	s_waitcnt lgkmcnt(0)
	v_pk_fma_f32 v[20:21], v[10:11], v[12:13], v[24:25] op_sel_hi:[0,1,1]
	v_mov_b32_e32 v24, v11
	v_pk_fma_f32 v[34:35], v[8:9], v[4:5], v[34:35] op_sel_hi:[0,1,1]
	v_pk_fma_f32 v[58:59], v[8:9], v[6:7], v[58:59] op_sel_hi:[0,1,1]
	v_pk_fma_f32 v[62:63], v[8:9], v[4:5], v[62:63] op_sel:[1,0,0]
	v_pk_fma_f32 v[88:89], v[8:9], v[6:7], v[16:17] op_sel:[1,0,0]
	v_pk_fma_f32 v[18:19], v[10:11], v[4:5], v[32:33] op_sel_hi:[0,1,1]
	v_pk_fma_f32 v[16:17], v[10:11], v[68:69], v[56:57] op_sel_hi:[0,1,1]
	v_pk_fma_f32 v[14:15], v[10:11], v[6:7], v[64:65] op_sel_hi:[0,1,1]
	v_pk_fma_f32 v[10:11], v[24:25], v[4:5], v[26:27] op_sel_hi:[0,1,1]
	v_pk_fma_f32 v[4:5], v[24:25], v[6:7], v[52:53] op_sel_hi:[0,1,1]
	v_and_b32_e32 v7, 64, v198
	v_xor_b32_e32 v6, 16, v198
	v_add_u32_e32 v7, 64, v7
	v_cmp_lt_i32_e32 vcc, v6, v7
	v_pk_fma_f32 v[30:31], v[8:9], v[12:13], v[30:31] op_sel_hi:[0,1,1]
	v_pk_fma_f32 v[60:61], v[8:9], v[12:13], v[60:61] op_sel:[1,0,0]
	v_cndmask_b32_e32 v6, v198, v6, vcc
	v_lshlrev_b32_e32 v90, 2, v6
	v_pk_fma_f32 v[12:13], v[24:25], v[12:13], v[22:23] op_sel_hi:[0,1,1]
	ds_bpermute_b32 v22, v90, v58
	ds_bpermute_b32 v23, v90, v59
	v_pk_fma_f32 v[54:55], v[8:9], v[68:69], v[54:55] op_sel_hi:[0,1,1]
	v_pk_fma_f32 v[86:87], v[8:9], v[68:69], v[66:67] op_sel:[1,0,0]
	v_pk_fma_f32 v[8:9], v[24:25], v[68:69], v[28:29] op_sel_hi:[0,1,1]
	v_xor_b32_e32 v6, 32, v198
	s_waitcnt lgkmcnt(0)
	v_pk_add_f32 v[72:73], v[58:59], v[22:23]
	ds_bpermute_b32 v22, v90, v60
	ds_bpermute_b32 v23, v90, v61
	v_cmp_lt_i32_e32 vcc, v6, v7
	ds_bpermute_b32 v7, v90, v31
	s_waitcnt lgkmcnt(1)
	v_pk_add_f32 v[68:69], v[60:61], v[22:23]
	ds_bpermute_b32 v22, v90, v62
	ds_bpermute_b32 v23, v90, v63
	v_cndmask_b32_e32 v6, v198, v6, vcc
	v_lshlrev_b32_e32 v91, 2, v6
	ds_bpermute_b32 v6, v90, v30
	ds_bpermute_b32 v74, v91, v72
	s_waitcnt lgkmcnt(2)
	v_pk_add_f32 v[64:65], v[62:63], v[22:23]
	ds_bpermute_b32 v22, v90, v86
	ds_bpermute_b32 v23, v90, v87
	s_waitcnt lgkmcnt(3)
	v_pk_add_f32 v[82:83], v[30:31], v[6:7]
	ds_bpermute_b32 v6, v90, v34
	ds_bpermute_b32 v7, v90, v35
	ds_bpermute_b32 v84, v91, v82
	s_waitcnt lgkmcnt(3)
	v_pk_add_f32 v[60:61], v[86:87], v[22:23]
	ds_bpermute_b32 v22, v90, v88
	ds_bpermute_b32 v23, v90, v89
	s_waitcnt lgkmcnt(3)
	v_pk_add_f32 v[78:79], v[34:35], v[6:7]
	ds_bpermute_b32 v6, v90, v54
	ds_bpermute_b32 v7, v90, v55
	ds_bpermute_b32 v85, v91, v83
	s_waitcnt lgkmcnt(3)
	v_pk_add_f32 v[56:57], v[88:89], v[22:23]
	ds_bpermute_b32 v22, v90, v20
	ds_bpermute_b32 v23, v90, v21
	s_waitcnt lgkmcnt(3)
; DI unsigned pk2(float a, float b) { f32x2 v = {a, b}; return __builtin_bit_cast(unsigned, __builtin_convertvector(v, bf2_t)); }
; DI float bf_lo(unsigned u) { return __uint_as_float(u << 16); }
; DI float bf_hi(unsigned u) { return __uint_as_float(u & 0xffff0000u); }
; DI float silu(float g) { return g / (1.f + __expf(-g)); }
; DI void dsa_job(const Params& p, int b, int tq0, char* lds) {
;     ...
;   float acc[4][8];
; #pragma unroll
;   for (int hh = 0; hh < 4; ++hh)
; #pragma unroll
;     for (int e = 0; e < 8; ++e) { float v = acc2[hh][e >> 1][e & 1]; v += __shfl_xor(v, 16); v += __shfl_xor(v, 32); acc[hh][e] = v; }
;   if (ksub == 0) {
; #pragma unroll
;     for (int hh = 0; hh < 4; ++hh) {
;       const int hd = g * 4 + hh;
;       const u32x4 gv = gvp[hh];
;       u32x4 ov;
; #pragma unroll
;       for (int e = 0; e < 4; ++e) ov[e] = pk2(acc[hh][2 * e] * SC_DSA * silu(bf_lo(gv[e])), acc[hh][2 * e + 1] * SC_DSA * silu(bf_hi(gv[e])));
;       *(u32x4*)(p.Mix + tok * 2048 + 1024 + hd * 64 + dc * 8) = ov;
	v_pk_add_f32 v[6:7], v[54:55], v[6:7]
	ds_bpermute_b32 v80, v91, v78
	ds_bpermute_b32 v81, v91, v79
	ds_bpermute_b32 v76, v91, v6
	s_waitcnt lgkmcnt(3)
	v_pk_add_f32 v[52:53], v[20:21], v[22:23]
	ds_bpermute_b32 v20, v90, v18
	ds_bpermute_b32 v21, v90, v19
	ds_bpermute_b32 v77, v91, v7
	ds_bpermute_b32 v75, v91, v73
	ds_bpermute_b32 v70, v91, v68
	ds_bpermute_b32 v71, v91, v69
	s_waitcnt lgkmcnt(4)
	v_pk_add_f32 v[32:33], v[18:19], v[20:21]
	ds_bpermute_b32 v18, v90, v16
	ds_bpermute_b32 v19, v90, v17
	ds_bpermute_b32 v66, v91, v64
	ds_bpermute_b32 v67, v91, v65
	ds_bpermute_b32 v62, v91, v60
	ds_bpermute_b32 v63, v91, v61
	s_waitcnt lgkmcnt(4)
	v_pk_add_f32 v[28:29], v[16:17], v[18:19]
	ds_bpermute_b32 v16, v90, v14
	ds_bpermute_b32 v17, v90, v15
	ds_bpermute_b32 v58, v91, v56
	ds_bpermute_b32 v59, v91, v57
	ds_bpermute_b32 v54, v91, v52
	ds_bpermute_b32 v55, v91, v53
	s_waitcnt lgkmcnt(4)
	v_pk_add_f32 v[24:25], v[14:15], v[16:17]
	ds_bpermute_b32 v14, v90, v12
	ds_bpermute_b32 v15, v90, v13
	ds_bpermute_b32 v34, v91, v32
	ds_bpermute_b32 v35, v91, v33
	ds_bpermute_b32 v30, v91, v28
	ds_bpermute_b32 v31, v91, v29
	s_waitcnt lgkmcnt(4)
	v_pk_add_f32 v[20:21], v[12:13], v[14:15]
	ds_bpermute_b32 v12, v90, v10
	ds_bpermute_b32 v13, v90, v11
	ds_bpermute_b32 v26, v91, v24
	ds_bpermute_b32 v27, v91, v25
	ds_bpermute_b32 v22, v91, v20
	ds_bpermute_b32 v23, v91, v21
	s_waitcnt lgkmcnt(4)
	v_pk_add_f32 v[16:17], v[10:11], v[12:13]
	ds_bpermute_b32 v10, v90, v8
	ds_bpermute_b32 v11, v90, v9
	ds_bpermute_b32 v18, v91, v16
	ds_bpermute_b32 v19, v91, v17
	v_cmp_gt_u32_e32 vcc, 16, v153
	s_waitcnt lgkmcnt(2)
	v_pk_add_f32 v[12:13], v[8:9], v[10:11]
	ds_bpermute_b32 v8, v90, v4
	ds_bpermute_b32 v9, v90, v5
	ds_bpermute_b32 v14, v91, v12
	ds_bpermute_b32 v15, v91, v13
	s_waitcnt lgkmcnt(2)
	v_pk_add_f32 v[8:9], v[4:5], v[8:9]
	ds_bpermute_b32 v10, v91, v8
	ds_bpermute_b32 v11, v91, v9
	s_and_saveexec_b64 s[0:1], vcc
	s_xor_b64 s[0:1], exec, s[0:1]
	s_cbranch_execz .LBB0_2358
	v_pk_add_f32 v[4:5], v[82:83], v[84:85]
	v_lshlrev_b32_e32 v84, 16, v48
	v_and_b32_e32 v48, 0xffff0000, v48
	v_mul_f32_e32 v82, 0xbfb8aa3b, v84
	v_mul_f32_e32 v83, 0xbfb8aa3b, v48
	v_exp_f32_e32 v82, v82
	v_exp_f32_e32 v83, v83
	v_pk_add_f32 v[78:79], v[78:79], v[80:81]
	v_and_b32_e32 v80, 0xffff0000, v49
	v_pk_add_f32 v[6:7], v[6:7], v[76:77]
	v_pk_add_f32 v[82:83], v[82:83], 1.0 op_sel_hi:[1,0]
	v_lshlrev_b32_e32 v76, 16, v50
	v_div_scale_f32 v85, s[2:3], v83, v83, v48
	v_rcp_f32_e32 v86, v85
	v_and_b32_e32 v50, 0xffff0000, v50
	v_lshlrev_b64 v[0:1], 12, v[0:1]
	v_fma_f32 v87, -v85, v86, 1.0
	v_fmac_f32_e32 v86, v87, v86
	v_div_scale_f32 v87, vcc, v48, v83, v48
	v_mul_f32_e32 v88, v87, v86
	v_fma_f32 v89, -v85, v88, v87
	v_fmac_f32_e32 v88, v89, v86
	v_fma_f32 v85, -v85, v88, v87
	v_div_fmas_f32 v85, v85, v86, v88
	v_div_fixup_f32 v83, v85, v83, v48
	v_div_scale_f32 v48, s[2:3], v82, v82, v84
	v_rcp_f32_e32 v85, v48
	v_readlane_b32 s80, v241, 28
	v_readlane_b32 s81, v241, 29
	v_pk_add_f32 v[24:25], v[24:25], v[26:27]
	v_fma_f32 v86, -v48, v85, 1.0
	v_fmac_f32_e32 v85, v86, v85
	v_div_scale_f32 v86, vcc, v84, v82, v84
	v_mul_f32_e32 v87, v86, v85
	v_fma_f32 v88, -v48, v87, v86
	v_fmac_f32_e32 v87, v88, v85
	v_fma_f32 v48, -v48, v87, v86
	v_div_fmas_f32 v48, v48, v85, v87
	v_div_fixup_f32 v82, v48, v82, v84
	v_pk_mul_f32 v[4:5], v[82:83], v[4:5]
	v_lshl_add_u64 v[0:1], s[80:81], 0, v[0:1]
	v_cvt_pk_bf16_f32 v4, v4, v5
	v_lshlrev_b32_e32 v5, 16, v49
	v_mul_f32_e32 v48, 0xbfb8aa3b, v5
	v_mul_f32_e32 v49, 0xbfb8aa3b, v80
	v_exp_f32_e32 v48, v48
	v_exp_f32_e32 v49, v49
	s_waitcnt lgkmcnt(0)
	v_pk_add_f32 v[8:9], v[8:9], v[10:11]
	v_pk_add_f32 v[48:49], v[48:49], 1.0 op_sel_hi:[1,0]
	v_div_scale_f32 v81, s[2:3], v49, v49, v80
	v_rcp_f32_e32 v82, v81
	s_nop 0
	s_nop 0
	v_fma_f32 v83, -v81, v82, 1.0
	v_fmac_f32_e32 v82, v83, v82
	v_div_scale_f32 v83, vcc, v80, v49, v80
	v_mul_f32_e32 v84, v83, v82
	v_fma_f32 v85, -v81, v84, v83
	v_fmac_f32_e32 v84, v85, v82
	v_fma_f32 v81, -v81, v84, v83
	v_div_fmas_f32 v81, v81, v82, v84
	v_div_fixup_f32 v49, v81, v49, v80
	v_div_scale_f32 v80, s[2:3], v48, v48, v5
	v_rcp_f32_e32 v81, v80
	s_nop 0
	s_nop 0
	v_fma_f32 v82, -v80, v81, 1.0
	v_fmac_f32_e32 v81, v82, v81
	v_div_scale_f32 v82, vcc, v5, v48, v5
	v_mul_f32_e32 v83, v82, v81
	v_fma_f32 v84, -v80, v83, v82
	v_fmac_f32_e32 v83, v84, v81
	v_fma_f32 v80, -v80, v83, v82
	v_div_fmas_f32 v80, v80, v81, v83
	v_div_fixup_f32 v48, v80, v48, v5
	v_pk_mul_f32 v[48:49], v[48:49], v[78:79]
	v_cvt_pk_bf16_f32 v5, v48, v49
	v_mul_f32_e32 v48, 0xbfb8aa3b, v76
	v_mul_f32_e32 v49, 0xbfb8aa3b, v50
	v_exp_f32_e32 v48, v48
	v_exp_f32_e32 v49, v49
	s_nop 0
	s_nop 0
	v_pk_add_f32 v[48:49], v[48:49], 1.0 op_sel_hi:[1,0]
	s_nop 0
	v_div_scale_f32 v77, s[2:3], v49, v49, v50
	v_rcp_f32_e32 v78, v77
	s_nop 0
	v_fma_f32 v79, -v77, v78, 1.0
	v_fmac_f32_e32 v78, v79, v78
	v_div_scale_f32 v79, vcc, v50, v49, v50
	v_mul_f32_e32 v80, v79, v78
	v_fma_f32 v81, -v77, v80, v79
	v_fmac_f32_e32 v80, v81, v78
	v_fma_f32 v77, -v77, v80, v79
	v_div_fmas_f32 v77, v77, v78, v80
	v_div_fixup_f32 v49, v77, v49, v50
	v_div_scale_f32 v50, s[2:3], v48, v48, v76
	v_rcp_f32_e32 v77, v50
	s_nop 0
	v_fma_f32 v78, -v50, v77, 1.0
	v_fmac_f32_e32 v77, v78, v77
	v_div_scale_f32 v78, vcc, v76, v48, v76
	v_mul_f32_e32 v79, v78, v77
	v_fma_f32 v80, -v50, v79, v78
	v_fmac_f32_e32 v79, v80, v77
	v_fma_f32 v50, -v50, v79, v78
	v_div_fmas_f32 v50, v50, v77, v79
	v_div_fixup_f32 v48, v50, v48, v76
	v_pk_mul_f32 v[6:7], v[48:49], v[6:7]
	v_pk_add_f32 v[48:49], v[72:73], v[74:75]
	v_cvt_pk_bf16_f32 v6, v6, v7
	v_lshlrev_b32_e32 v7, 16, v51
; DI unsigned pk2(float a, float b) { f32x2 v = {a, b}; return __builtin_bit_cast(unsigned, __builtin_convertvector(v, bf2_t)); }
; DI float bf_lo(unsigned u) { return __uint_as_float(u << 16); }
; DI float bf_hi(unsigned u) { return __uint_as_float(u & 0xffff0000u); }
; DI float silu(float g) { return g / (1.f + __expf(-g)); }
; DI void dsa_job(const Params& p, int b, int tq0, char* lds) {
;     ...
;   if (ksub == 0) {
; #pragma unroll
;     for (int hh = 0; hh < 4; ++hh) {
;       const int hd = g * 4 + hh;
;       const u32x4 gv = gvp[hh];
;       u32x4 ov;
; #pragma unroll
;       for (int e = 0; e < 4; ++e) ov[e] = pk2(acc[hh][2 * e] * SC_DSA * silu(bf_lo(gv[e])), acc[hh][2 * e + 1] * SC_DSA * silu(bf_hi(gv[e])));
;       *(u32x4*)(p.Mix + tok * 2048 + 1024 + hd * 64 + dc * 8) = ov;
	v_and_b32_e32 v72, 0xffff0000, v51
	v_mul_f32_e32 v50, 0xbfb8aa3b, v7
	v_mul_f32_e32 v51, 0xbfb8aa3b, v72
	v_exp_f32_e32 v50, v50
	v_exp_f32_e32 v51, v51
	s_nop 0
	v_pk_add_f32 v[50:51], v[50:51], 1.0 op_sel_hi:[1,0]
	s_nop 0
	v_div_scale_f32 v73, s[2:3], v51, v51, v72
	v_rcp_f32_e32 v74, v73
	s_nop 0
	v_fma_f32 v75, -v73, v74, 1.0
	v_fmac_f32_e32 v74, v75, v74
	v_div_scale_f32 v75, vcc, v72, v51, v72
	v_mul_f32_e32 v76, v75, v74
	v_fma_f32 v77, -v73, v76, v75
	v_fmac_f32_e32 v76, v77, v74
	v_fma_f32 v73, -v73, v76, v75
	v_div_fmas_f32 v73, v73, v74, v76
	v_div_fixup_f32 v51, v73, v51, v72
	v_div_scale_f32 v72, s[2:3], v50, v50, v7
	v_rcp_f32_e32 v73, v72
	s_nop 0
	v_fma_f32 v74, -v72, v73, 1.0
	v_fmac_f32_e32 v73, v74, v73
	v_div_scale_f32 v74, vcc, v7, v50, v7
	v_mul_f32_e32 v75, v74, v73
	v_fma_f32 v76, -v72, v75, v74
	v_fmac_f32_e32 v75, v76, v73
	v_fma_f32 v72, -v72, v75, v74
	v_div_fmas_f32 v72, v72, v73, v75
	v_div_fixup_f32 v50, v72, v50, v7
	v_pk_mul_f32 v[48:49], v[50:51], v[48:49]
	s_nop 0
	v_cvt_pk_bf16_f32 v7, v48, v49
	v_lshlrev_b32_e32 v48, 9, v208
	v_mov_b32_e32 v49, v3
	v_lshl_add_u64 v[0:1], v[0:1], 0, v[48:49]
	v_lshl_add_u64 v[0:1], v[0:1], 0, v[2:3]
	v_lshlrev_b32_e32 v2, 16, v44
	v_and_b32_e32 v44, 0xffff0000, v44
	global_store_dwordx4 v[0:1], v[4:7], off offset:2048
	s_nop 1
	v_mul_f32_e32 v6, 0xbfb8aa3b, v2
	v_mul_f32_e32 v7, 0xbfb8aa3b, v44
	v_exp_f32_e32 v6, v6
	v_exp_f32_e32 v7, v7
	v_pk_add_f32 v[4:5], v[68:69], v[70:71]
	v_pk_add_f32 v[6:7], v[6:7], 1.0 op_sel_hi:[1,0]
	s_nop 0
	v_div_scale_f32 v48, s[2:3], v7, v7, v44
	v_rcp_f32_e32 v49, v48
	s_nop 0
	v_fma_f32 v50, -v48, v49, 1.0
	v_fmac_f32_e32 v49, v50, v49
	v_div_scale_f32 v50, vcc, v44, v7, v44
	v_mul_f32_e32 v51, v50, v49
	v_fma_f32 v68, -v48, v51, v50
	v_fmac_f32_e32 v51, v68, v49
	v_fma_f32 v48, -v48, v51, v50
	v_div_fmas_f32 v48, v48, v49, v51
	v_div_fixup_f32 v7, v48, v7, v44
	v_div_scale_f32 v44, s[2:3], v6, v6, v2
	v_rcp_f32_e32 v48, v44
	s_nop 0
	v_fma_f32 v49, -v44, v48, 1.0
	v_fmac_f32_e32 v48, v49, v48
	v_div_scale_f32 v49, vcc, v2, v6, v2
	v_mul_f32_e32 v50, v49, v48
	v_fma_f32 v51, -v44, v50, v49
	v_fmac_f32_e32 v50, v51, v48
	v_fma_f32 v44, -v44, v50, v49
	v_div_fmas_f32 v44, v44, v48, v50
	v_div_fixup_f32 v6, v44, v6, v2
	v_pk_mul_f32 v[4:5], v[6:7], v[4:5]
	v_lshlrev_b32_e32 v2, 16, v45
	v_cvt_pk_bf16_f32 v4, v4, v5
	v_and_b32_e32 v5, 0xffff0000, v45
	v_mul_f32_e32 v44, 0xbfb8aa3b, v2
	v_mul_f32_e32 v45, 0xbfb8aa3b, v5
	v_exp_f32_e32 v44, v44
	v_exp_f32_e32 v45, v45
	v_pk_add_f32 v[6:7], v[64:65], v[66:67]
	v_pk_add_f32 v[44:45], v[44:45], 1.0 op_sel_hi:[1,0]
	s_nop 0
	v_div_scale_f32 v48, s[2:3], v45, v45, v5
	v_rcp_f32_e32 v49, v48
	s_nop 0
	v_fma_f32 v50, -v48, v49, 1.0
	v_fmac_f32_e32 v49, v50, v49
	v_div_scale_f32 v50, vcc, v5, v45, v5
	v_mul_f32_e32 v51, v50, v49
	v_fma_f32 v64, -v48, v51, v50
	v_fmac_f32_e32 v51, v64, v49
	v_fma_f32 v48, -v48, v51, v50
	v_div_fmas_f32 v48, v48, v49, v51
	v_div_fixup_f32 v45, v48, v45, v5
	v_div_scale_f32 v5, s[2:3], v44, v44, v2
	v_rcp_f32_e32 v48, v5
	s_nop 0
	v_fma_f32 v49, -v5, v48, 1.0
	v_fmac_f32_e32 v48, v49, v48
	v_div_scale_f32 v49, vcc, v2, v44, v2
	v_mul_f32_e32 v50, v49, v48
	v_fma_f32 v51, -v5, v50, v49
	v_fmac_f32_e32 v50, v51, v48
	v_fma_f32 v5, -v5, v50, v49
	v_div_fmas_f32 v5, v5, v48, v50
	v_div_fixup_f32 v44, v5, v44, v2
	v_lshlrev_b32_e32 v2, 16, v46
	v_and_b32_e32 v46, 0xffff0000, v46
	v_pk_mul_f32 v[6:7], v[44:45], v[6:7]
	v_mul_f32_e32 v44, 0xbfb8aa3b, v2
	v_mul_f32_e32 v45, 0xbfb8aa3b, v46
	v_exp_f32_e32 v44, v44
	v_exp_f32_e32 v45, v45
	v_cvt_pk_bf16_f32 v5, v6, v7
	v_pk_add_f32 v[6:7], v[60:61], v[62:63]
	v_pk_add_f32 v[44:45], v[44:45], 1.0 op_sel_hi:[1,0]
	s_nop 0
	v_div_scale_f32 v48, s[2:3], v45, v45, v46
	v_rcp_f32_e32 v49, v48
	s_nop 0
	v_fma_f32 v50, -v48, v49, 1.0
	v_fmac_f32_e32 v49, v50, v49
	v_div_scale_f32 v50, vcc, v46, v45, v46
	v_mul_f32_e32 v51, v50, v49
	v_fma_f32 v60, -v48, v51, v50
	v_fmac_f32_e32 v51, v60, v49
	v_fma_f32 v48, -v48, v51, v50
	v_div_fmas_f32 v48, v48, v49, v51
	v_div_fixup_f32 v45, v48, v45, v46
	v_div_scale_f32 v46, s[2:3], v44, v44, v2
	v_rcp_f32_e32 v48, v46
	s_nop 0
	v_fma_f32 v49, -v46, v48, 1.0
	v_fmac_f32_e32 v48, v49, v48
	v_div_scale_f32 v49, vcc, v2, v44, v2
	v_mul_f32_e32 v50, v49, v48
	v_fma_f32 v51, -v46, v50, v49
	v_fmac_f32_e32 v50, v51, v48
	v_fma_f32 v46, -v46, v50, v49
	v_div_fmas_f32 v46, v46, v48, v50
	v_div_fixup_f32 v44, v46, v44, v2
	v_pk_mul_f32 v[6:7], v[44:45], v[6:7]
	v_lshlrev_b32_e32 v2, 16, v47
	v_cvt_pk_bf16_f32 v6, v6, v7
	v_and_b32_e32 v7, 0xffff0000, v47
	v_mul_f32_e32 v46, 0xbfb8aa3b, v2
	v_mul_f32_e32 v47, 0xbfb8aa3b, v7
	v_exp_f32_e32 v46, v46
	v_exp_f32_e32 v47, v47
	v_pk_add_f32 v[44:45], v[56:57], v[58:59]
	v_pk_add_f32 v[46:47], v[46:47], 1.0 op_sel_hi:[1,0]
	s_nop 0
	v_div_scale_f32 v48, s[2:3], v47, v47, v7
	v_rcp_f32_e32 v49, v48
	s_nop 0
	v_fma_f32 v50, -v48, v49, 1.0
	v_fmac_f32_e32 v49, v50, v49
	v_div_scale_f32 v50, vcc, v7, v47, v7
	v_mul_f32_e32 v51, v50, v49
	v_fma_f32 v56, -v48, v51, v50
	v_fmac_f32_e32 v51, v56, v49
	v_fma_f32 v48, -v48, v51, v50
	v_div_fmas_f32 v48, v48, v49, v51
	v_div_fixup_f32 v47, v48, v47, v7
	v_div_scale_f32 v7, s[2:3], v46, v46, v2
	v_rcp_f32_e32 v48, v7
	s_nop 0
	v_fma_f32 v49, -v7, v48, 1.0
	v_fmac_f32_e32 v48, v49, v48
	v_div_scale_f32 v49, vcc, v2, v46, v2
	v_mul_f32_e32 v50, v49, v48
	v_fma_f32 v51, -v7, v50, v49
	v_fmac_f32_e32 v50, v51, v48
	v_fma_f32 v7, -v7, v50, v49
	v_div_fmas_f32 v7, v7, v48, v50
	v_div_fixup_f32 v46, v7, v46, v2
	v_pk_mul_f32 v[44:45], v[46:47], v[44:45]
	v_lshlrev_b32_e32 v2, 16, v40
	v_cvt_pk_bf16_f32 v7, v44, v45
; DI unsigned pk2(float a, float b) { f32x2 v = {a, b}; return __builtin_bit_cast(unsigned, __builtin_convertvector(v, bf2_t)); }
; DI float bf_lo(unsigned u) { return __uint_as_float(u << 16); }
; DI float bf_hi(unsigned u) { return __uint_as_float(u & 0xffff0000u); }
; DI float silu(float g) { return g / (1.f + __expf(-g)); }
; DI void dsa_job(const Params& p, int b, int tq0, char* lds) {
;     ...
;   if (ksub == 0) {
; #pragma unroll
;     for (int hh = 0; hh < 4; ++hh) {
;       const int hd = g * 4 + hh;
;       const u32x4 gv = gvp[hh];
;       u32x4 ov;
; #pragma unroll
;       for (int e = 0; e < 4; ++e) ov[e] = pk2(acc[hh][2 * e] * SC_DSA * silu(bf_lo(gv[e])), acc[hh][2 * e + 1] * SC_DSA * silu(bf_hi(gv[e])));
;       *(u32x4*)(p.Mix + tok * 2048 + 1024 + hd * 64 + dc * 8) = ov;
	v_and_b32_e32 v40, 0xffff0000, v40
	global_store_dwordx4 v[0:1], v[4:7], off offset:2176
	s_nop 1
	v_mul_f32_e32 v6, 0xbfb8aa3b, v2
	v_mul_f32_e32 v7, 0xbfb8aa3b, v40
	v_exp_f32_e32 v6, v6
	v_exp_f32_e32 v7, v7
	v_pk_add_f32 v[4:5], v[52:53], v[54:55]
	v_pk_add_f32 v[6:7], v[6:7], 1.0 op_sel_hi:[1,0]
	s_nop 0
	v_div_scale_f32 v44, s[2:3], v7, v7, v40
	v_rcp_f32_e32 v45, v44
	s_nop 0
	v_fma_f32 v46, -v44, v45, 1.0
	v_fmac_f32_e32 v45, v46, v45
	v_div_scale_f32 v46, vcc, v40, v7, v40
	v_mul_f32_e32 v47, v46, v45
	v_fma_f32 v48, -v44, v47, v46
	v_fmac_f32_e32 v47, v48, v45
	v_fma_f32 v44, -v44, v47, v46
	v_div_fmas_f32 v44, v44, v45, v47
	v_div_fixup_f32 v7, v44, v7, v40
	v_div_scale_f32 v40, s[2:3], v6, v6, v2
	v_rcp_f32_e32 v44, v40
	s_nop 0
	v_fma_f32 v45, -v40, v44, 1.0
	v_fmac_f32_e32 v44, v45, v44
	v_div_scale_f32 v45, vcc, v2, v6, v2
	v_mul_f32_e32 v46, v45, v44
	v_fma_f32 v47, -v40, v46, v45
	v_fmac_f32_e32 v46, v47, v44
	v_fma_f32 v40, -v40, v46, v45
	v_div_fmas_f32 v40, v40, v44, v46
	v_div_fixup_f32 v6, v40, v6, v2
	v_pk_mul_f32 v[4:5], v[6:7], v[4:5]
	v_lshlrev_b32_e32 v2, 16, v41
	v_cvt_pk_bf16_f32 v4, v4, v5
	v_and_b32_e32 v5, 0xffff0000, v41
	v_pk_add_f32 v[6:7], v[32:33], v[34:35]
	v_mul_f32_e32 v32, 0xbfb8aa3b, v2
	v_mul_f32_e32 v33, 0xbfb8aa3b, v5
	v_exp_f32_e32 v32, v32
	v_exp_f32_e32 v33, v33
	s_nop 0
	v_pk_add_f32 v[32:33], v[32:33], 1.0 op_sel_hi:[1,0]
	s_nop 0
	v_div_scale_f32 v34, s[2:3], v33, v33, v5
	v_rcp_f32_e32 v35, v34
	s_nop 0
	v_fma_f32 v40, -v34, v35, 1.0
	v_fmac_f32_e32 v35, v40, v35
	v_div_scale_f32 v40, vcc, v5, v33, v5
	v_mul_f32_e32 v41, v40, v35
	v_fma_f32 v44, -v34, v41, v40
	v_fmac_f32_e32 v41, v44, v35
	v_fma_f32 v34, -v34, v41, v40
	v_div_fmas_f32 v34, v34, v35, v41
	v_div_fixup_f32 v33, v34, v33, v5
	v_div_scale_f32 v5, s[2:3], v32, v32, v2
	v_rcp_f32_e32 v34, v5
	s_nop 0
	v_fma_f32 v35, -v5, v34, 1.0
	v_fmac_f32_e32 v34, v35, v34
	v_div_scale_f32 v35, vcc, v2, v32, v2
	v_mul_f32_e32 v40, v35, v34
	v_fma_f32 v41, -v5, v40, v35
	v_fmac_f32_e32 v40, v41, v34
	v_fma_f32 v5, -v5, v40, v35
	v_div_fmas_f32 v5, v5, v34, v40
	v_div_fixup_f32 v32, v5, v32, v2
	v_pk_mul_f32 v[6:7], v[32:33], v[6:7]
	v_lshlrev_b32_e32 v2, 16, v42
	v_cvt_pk_bf16_f32 v5, v6, v7
	v_pk_add_f32 v[6:7], v[28:29], v[30:31]
	v_and_b32_e32 v30, 0xffff0000, v42
	v_mul_f32_e32 v28, 0xbfb8aa3b, v2
	v_mul_f32_e32 v29, 0xbfb8aa3b, v30
	v_exp_f32_e32 v28, v28
	v_exp_f32_e32 v29, v29
	s_nop 0
	v_pk_add_f32 v[28:29], v[28:29], 1.0 op_sel_hi:[1,0]
	s_nop 0
	v_div_scale_f32 v31, s[2:3], v29, v29, v30
	v_rcp_f32_e32 v32, v31
	s_nop 0
	v_fma_f32 v33, -v31, v32, 1.0
	v_fmac_f32_e32 v32, v33, v32
	v_div_scale_f32 v33, vcc, v30, v29, v30
	v_mul_f32_e32 v34, v33, v32
	v_fma_f32 v35, -v31, v34, v33
	v_fmac_f32_e32 v34, v35, v32
	v_fma_f32 v31, -v31, v34, v33
	v_div_fmas_f32 v31, v31, v32, v34
	v_div_fixup_f32 v29, v31, v29, v30
	v_div_scale_f32 v30, s[2:3], v28, v28, v2
	v_rcp_f32_e32 v31, v30
	s_nop 0
	v_fma_f32 v32, -v30, v31, 1.0
	v_fmac_f32_e32 v31, v32, v31
	v_div_scale_f32 v32, vcc, v2, v28, v2
	v_mul_f32_e32 v33, v32, v31
	v_fma_f32 v34, -v30, v33, v32
	v_fmac_f32_e32 v33, v34, v31
	v_fma_f32 v30, -v30, v33, v32
	v_div_fmas_f32 v30, v30, v31, v33
	v_div_fixup_f32 v28, v30, v28, v2
	v_pk_mul_f32 v[6:7], v[28:29], v[6:7]
	v_lshlrev_b32_e32 v2, 16, v43
	v_cvt_pk_bf16_f32 v6, v6, v7
	v_and_b32_e32 v7, 0xffff0000, v43
	v_mul_f32_e32 v26, 0xbfb8aa3b, v2
	v_mul_f32_e32 v27, 0xbfb8aa3b, v7
	v_exp_f32_e32 v26, v26
	v_exp_f32_e32 v27, v27
	s_nop 0
	v_pk_add_f32 v[26:27], v[26:27], 1.0 op_sel_hi:[1,0]
	s_nop 0
	v_div_scale_f32 v28, s[2:3], v27, v27, v7
	v_rcp_f32_e32 v29, v28
	s_nop 0
	v_fma_f32 v30, -v28, v29, 1.0
	v_fmac_f32_e32 v29, v30, v29
	v_div_scale_f32 v30, vcc, v7, v27, v7
	v_mul_f32_e32 v31, v30, v29
	v_fma_f32 v32, -v28, v31, v30
	v_fmac_f32_e32 v31, v32, v29
	v_fma_f32 v28, -v28, v31, v30
	v_div_fmas_f32 v28, v28, v29, v31
	v_div_fixup_f32 v27, v28, v27, v7
	v_div_scale_f32 v7, s[2:3], v26, v26, v2
	v_rcp_f32_e32 v28, v7
	s_nop 0
	v_fma_f32 v29, -v7, v28, 1.0
	v_fmac_f32_e32 v28, v29, v28
	v_div_scale_f32 v29, vcc, v2, v26, v2
	v_mul_f32_e32 v30, v29, v28
	v_fma_f32 v31, -v7, v30, v29
	v_fmac_f32_e32 v30, v31, v28
	v_fma_f32 v7, -v7, v30, v29
	v_div_fmas_f32 v7, v7, v28, v30
	v_div_fixup_f32 v26, v7, v26, v2
	v_pk_mul_f32 v[24:25], v[26:27], v[24:25]
	v_lshlrev_b32_e32 v2, 16, v36
	v_cvt_pk_bf16_f32 v7, v24, v25
; DI unsigned pk2(float a, float b) { f32x2 v = {a, b}; return __builtin_bit_cast(unsigned, __builtin_convertvector(v, bf2_t)); }
; DI float bf_lo(unsigned u) { return __uint_as_float(u << 16); }
; DI float bf_hi(unsigned u) { return __uint_as_float(u & 0xffff0000u); }
; DI float silu(float g) { return g / (1.f + __expf(-g)); }
; DI void dsa_job(const Params& p, int b, int tq0, char* lds) {
;     ...
;   if (ksub == 0) {
; #pragma unroll
;     for (int hh = 0; hh < 4; ++hh) {
;       const int hd = g * 4 + hh;
;       const u32x4 gv = gvp[hh];
;       u32x4 ov;
; #pragma unroll
;       for (int e = 0; e < 4; ++e) ov[e] = pk2(acc[hh][2 * e] * SC_DSA * silu(bf_lo(gv[e])), acc[hh][2 * e + 1] * SC_DSA * silu(bf_hi(gv[e])));
;       *(u32x4*)(p.Mix + tok * 2048 + 1024 + hd * 64 + dc * 8) = ov;
	global_store_dwordx4 v[0:1], v[4:7], off offset:2304
	s_nop 1
	v_pk_add_f32 v[4:5], v[20:21], v[22:23]
	v_and_b32_e32 v20, 0xffff0000, v36
	v_mul_f32_e32 v6, 0xbfb8aa3b, v2
	v_mul_f32_e32 v7, 0xbfb8aa3b, v20
	v_exp_f32_e32 v6, v6
	v_exp_f32_e32 v7, v7
	s_nop 0
	v_pk_add_f32 v[6:7], v[6:7], 1.0 op_sel_hi:[1,0]
	s_nop 0
	v_div_scale_f32 v21, s[2:3], v7, v7, v20
	v_rcp_f32_e32 v22, v21
	s_nop 0
	v_fma_f32 v23, -v21, v22, 1.0
	v_fmac_f32_e32 v22, v23, v22
	v_div_scale_f32 v23, vcc, v20, v7, v20
	v_mul_f32_e32 v24, v23, v22
	v_fma_f32 v25, -v21, v24, v23
	v_fmac_f32_e32 v24, v25, v22
	v_fma_f32 v21, -v21, v24, v23
	v_div_fmas_f32 v21, v21, v22, v24
	v_div_fixup_f32 v7, v21, v7, v20
	v_div_scale_f32 v20, s[2:3], v6, v6, v2
	v_rcp_f32_e32 v21, v20
	s_nop 0
	v_fma_f32 v22, -v20, v21, 1.0
	v_fmac_f32_e32 v21, v22, v21
	v_div_scale_f32 v22, vcc, v2, v6, v2
	v_mul_f32_e32 v23, v22, v21
	v_fma_f32 v24, -v20, v23, v22
	v_fmac_f32_e32 v23, v24, v21
	v_fma_f32 v20, -v20, v23, v22
	v_div_fmas_f32 v20, v20, v21, v23
	v_div_fixup_f32 v6, v20, v6, v2
	v_pk_mul_f32 v[4:5], v[6:7], v[4:5]
	v_lshlrev_b32_e32 v2, 16, v37
	v_cvt_pk_bf16_f32 v4, v4, v5
	v_and_b32_e32 v5, 0xffff0000, v37
	v_pk_add_f32 v[6:7], v[16:17], v[18:19]
	v_mul_f32_e32 v16, 0xbfb8aa3b, v2
	v_mul_f32_e32 v17, 0xbfb8aa3b, v5
	v_exp_f32_e32 v16, v16
	v_exp_f32_e32 v17, v17
	s_nop 0
	v_pk_add_f32 v[16:17], v[16:17], 1.0 op_sel_hi:[1,0]
	s_nop 0
	v_div_scale_f32 v18, s[2:3], v17, v17, v5
	v_rcp_f32_e32 v19, v18
	s_nop 0
	v_fma_f32 v20, -v18, v19, 1.0
	v_fmac_f32_e32 v19, v20, v19
	v_div_scale_f32 v20, vcc, v5, v17, v5
	v_mul_f32_e32 v21, v20, v19
	v_fma_f32 v22, -v18, v21, v20
	v_fmac_f32_e32 v21, v22, v19
	v_fma_f32 v18, -v18, v21, v20
	v_div_fmas_f32 v18, v18, v19, v21
	v_div_fixup_f32 v17, v18, v17, v5
	v_div_scale_f32 v5, s[2:3], v16, v16, v2
	v_rcp_f32_e32 v18, v5
	s_nop 0
	v_fma_f32 v19, -v5, v18, 1.0
	v_fmac_f32_e32 v18, v19, v18
	v_div_scale_f32 v19, vcc, v2, v16, v2
	v_mul_f32_e32 v20, v19, v18
	v_fma_f32 v21, -v5, v20, v19
	v_fmac_f32_e32 v20, v21, v18
	v_fma_f32 v5, -v5, v20, v19
	v_div_fmas_f32 v5, v5, v18, v20
	v_div_fixup_f32 v16, v5, v16, v2
	v_pk_mul_f32 v[6:7], v[16:17], v[6:7]
	v_lshlrev_b32_e32 v2, 16, v38
	v_cvt_pk_bf16_f32 v5, v6, v7
	v_pk_add_f32 v[6:7], v[12:13], v[14:15]
	v_and_b32_e32 v14, 0xffff0000, v38
	v_mul_f32_e32 v12, 0xbfb8aa3b, v2
	v_mul_f32_e32 v13, 0xbfb8aa3b, v14
	v_exp_f32_e32 v12, v12
	v_exp_f32_e32 v13, v13
	s_nop 0
	v_pk_add_f32 v[12:13], v[12:13], 1.0 op_sel_hi:[1,0]
	s_nop 0
	v_div_scale_f32 v15, s[2:3], v13, v13, v14
	v_rcp_f32_e32 v16, v15
	s_nop 0
	v_fma_f32 v17, -v15, v16, 1.0
	v_fmac_f32_e32 v16, v17, v16
	v_div_scale_f32 v17, vcc, v14, v13, v14
	v_mul_f32_e32 v18, v17, v16
	v_fma_f32 v19, -v15, v18, v17
	v_fmac_f32_e32 v18, v19, v16
	v_fma_f32 v15, -v15, v18, v17
	v_div_fmas_f32 v15, v15, v16, v18
	v_div_fixup_f32 v13, v15, v13, v14
	v_div_scale_f32 v14, s[2:3], v12, v12, v2
	v_rcp_f32_e32 v15, v14
	s_nop 0
	v_fma_f32 v16, -v14, v15, 1.0
	v_fmac_f32_e32 v15, v16, v15
	v_div_scale_f32 v16, vcc, v2, v12, v2
	v_mul_f32_e32 v17, v16, v15
	v_fma_f32 v18, -v14, v17, v16
	v_fmac_f32_e32 v17, v18, v15
	v_fma_f32 v14, -v14, v17, v16
	v_div_fmas_f32 v14, v14, v15, v17
	v_div_fixup_f32 v12, v14, v12, v2
	v_pk_mul_f32 v[6:7], v[12:13], v[6:7]
	v_lshlrev_b32_e32 v2, 16, v39
	v_cvt_pk_bf16_f32 v6, v6, v7
	v_and_b32_e32 v7, 0xffff0000, v39
	v_mul_f32_e32 v10, 0xbfb8aa3b, v2
	v_mul_f32_e32 v11, 0xbfb8aa3b, v7
	v_exp_f32_e32 v10, v10
	v_exp_f32_e32 v11, v11
	s_nop 0
	v_pk_add_f32 v[10:11], v[10:11], 1.0 op_sel_hi:[1,0]
	s_nop 0
	v_div_scale_f32 v12, s[2:3], v11, v11, v7
	v_rcp_f32_e32 v13, v12
	s_nop 0
	v_fma_f32 v14, -v12, v13, 1.0
	v_fmac_f32_e32 v13, v14, v13
	v_div_scale_f32 v14, vcc, v7, v11, v7
	v_mul_f32_e32 v15, v14, v13
	v_fma_f32 v16, -v12, v15, v14
	v_fmac_f32_e32 v15, v16, v13
	v_fma_f32 v12, -v12, v15, v14
	v_div_fmas_f32 v12, v12, v13, v15
	v_div_fixup_f32 v11, v12, v11, v7
	v_div_scale_f32 v7, s[2:3], v10, v10, v2
	v_rcp_f32_e32 v12, v7
	s_nop 0
	v_fma_f32 v13, -v7, v12, 1.0
	v_fmac_f32_e32 v12, v13, v12
	v_div_scale_f32 v13, vcc, v2, v10, v2
	v_mul_f32_e32 v14, v13, v12
	v_fma_f32 v15, -v7, v14, v13
	v_fmac_f32_e32 v14, v15, v12
	v_fma_f32 v7, -v7, v14, v13
	v_div_fmas_f32 v7, v7, v12, v14
	v_div_fixup_f32 v10, v7, v10, v2
	v_pk_mul_f32 v[8:9], v[10:11], v[8:9]
	s_nop 0
	v_cvt_pk_bf16_f32 v7, v8, v9
	global_store_dwordx4 v[0:1], v[4:7], off offset:2432
